# residual-GEMM epilogues: row-sum cross-lane adds via v_permlane16/32_swap instead of ds_bpermute (96 sites, on v16)
# speedup vs baseline: 1.0054x; 1.0030x over previous
;     ...
;         G_PAIR(0, 1);
; #pragma unroll 1
;         for (int t = 2; t < nt; t += 2) G_PAIR(t, 0);
.LBB0_357:
	ds_read_b128 v[134:137], v190
	ds_read_b128 v[138:141], v190 offset:1024
	ds_read_b128 v[142:145], v190 offset:2048
	ds_read_b128 v[146:149], v190 offset:3072
	s_mov_b32 m0, s54
	v_lshl_add_u64 v[150:151], v[128:129], 0, s[34:35]
	ds_read_b128 v[166:169], v191
	ds_read_b128 v[170:173], v191 offset:1024
	ds_read_b128 v[174:177], v191 offset:2048
	ds_read_b128 v[178:181], v191 offset:3072
	ds_read_b128 v[194:197], v191 offset:4096
	ds_read_b128 v[198:201], v191 offset:5120
	ds_read_b128 v[202:205], v191 offset:6144
	ds_read_b128 v[206:209], v191 offset:7168
	global_load_lds_dwordx4 v[150:151], off
	s_mov_b32 m0, s55
	v_lshl_add_u64 v[150:151], v[130:131], 0, s[34:35]
	global_load_lds_dwordx4 v[150:151], off
	s_waitcnt lgkmcnt(8)
	s_barrier
	s_waitcnt lgkmcnt(0)
	v_mfma_f32_16x16x32_bf16 v[116:119], v[134:137], v[166:169], v[116:119]
	s_add_i32 s36, s34, 0xfff50080
	v_mfma_f32_16x16x32_bf16 v[112:115], v[142:145], v[166:169], v[112:115]
	s_cmp_eq_u32 s67, 40
	v_mfma_f32_16x16x32_bf16 v[108:111], v[134:137], v[174:177], v[108:111]
	s_cselect_b32 s69, s27, s29
	v_mfma_f32_16x16x32_bf16 v[104:107], v[142:145], v[174:177], v[104:107]
	s_cselect_b32 s68, s26, s28
	v_mfma_f32_16x16x32_bf16 v[92:95], v[134:137], v[194:197], v[92:95]
	s_cselect_b32 s37, s9, s31
	v_mfma_f32_16x16x32_bf16 v[88:91], v[142:145], v[194:197], v[88:91]
	s_cselect_b32 s70, s8, s30
	v_mfma_f32_16x16x32_bf16 v[76:79], v[134:137], v[202:205], v[76:79]
	v_mfma_f32_16x16x32_bf16 v[72:75], v[142:145], v[202:205], v[72:75]
	v_mfma_f32_16x16x32_bf16 v[116:119], v[138:141], v[170:173], v[116:119]
	v_mfma_f32_16x16x32_bf16 v[112:115], v[146:149], v[170:173], v[112:115]
	v_mfma_f32_16x16x32_bf16 v[108:111], v[138:141], v[178:181], v[108:111]
	v_mfma_f32_16x16x32_bf16 v[104:107], v[146:149], v[178:181], v[104:107]
	v_mfma_f32_16x16x32_bf16 v[92:95], v[138:141], v[198:201], v[92:95]
	v_mfma_f32_16x16x32_bf16 v[88:91], v[146:149], v[198:201], v[88:91]
	v_mfma_f32_16x16x32_bf16 v[76:79], v[138:141], v[206:209], v[76:79]
	v_mfma_f32_16x16x32_bf16 v[72:75], v[146:149], v[206:209], v[72:75]
	s_barrier
	s_cselect_b32 s71, 0, s36
	s_add_u32 s36, s70, s71
	s_addc_u32 s37, s37, 0
	s_mov_b32 m0, s56
	v_lshl_add_u64 v[150:151], s[36:37], 0, v[156:157]
	ds_read_b128 v[210:213], v192
	ds_read_b128 v[214:217], v192 offset:1024
	ds_read_b128 v[222:225], v192 offset:2048
	ds_read_b128 v[226:229], v192 offset:3072
	global_load_lds_dwordx4 v[150:151], off
	s_mov_b32 m0, s57
	v_lshl_add_u64 v[182:183], s[36:37], 0, v[160:161]
	global_load_lds_dwordx4 v[182:183], off
	s_barrier
	s_waitcnt lgkmcnt(0)
	v_mfma_f32_16x16x32_bf16 v[124:127], v[210:213], v[166:169], v[124:127]
	v_mfma_f32_16x16x32_bf16 v[120:123], v[222:225], v[166:169], v[120:123]
	v_mfma_f32_16x16x32_bf16 v[100:103], v[210:213], v[174:177], v[100:103]
	v_mfma_f32_16x16x32_bf16 v[96:99], v[222:225], v[174:177], v[96:99]
	v_mfma_f32_16x16x32_bf16 v[84:87], v[210:213], v[194:197], v[84:87]
	v_mfma_f32_16x16x32_bf16 v[80:83], v[222:225], v[194:197], v[80:83]
	v_mfma_f32_16x16x32_bf16 v[68:71], v[210:213], v[202:205], v[68:71]
	v_mfma_f32_16x16x32_bf16 v[64:67], v[222:225], v[202:205], v[64:67]
	v_mfma_f32_16x16x32_bf16 v[124:127], v[214:217], v[170:173], v[124:127]
	v_mfma_f32_16x16x32_bf16 v[120:123], v[226:229], v[170:173], v[120:123]
	v_mfma_f32_16x16x32_bf16 v[100:103], v[214:217], v[178:181], v[100:103]
	v_mfma_f32_16x16x32_bf16 v[96:99], v[226:229], v[178:181], v[96:99]
	v_mfma_f32_16x16x32_bf16 v[84:87], v[214:217], v[198:201], v[84:87]
	v_mfma_f32_16x16x32_bf16 v[80:83], v[226:229], v[198:201], v[80:83]
	v_mfma_f32_16x16x32_bf16 v[68:71], v[214:217], v[206:209], v[68:71]
	v_mfma_f32_16x16x32_bf16 v[64:67], v[226:229], v[206:209], v[64:67]
	s_add_u32 s68, s68, s71
	s_addc_u32 s69, s69, 0
	s_mov_b32 m0, s46
	v_lshl_add_u64 v[218:219], s[68:69], 0, v[154:155]
	s_barrier
	ds_read_b128 v[166:169], v191 offset:16384
	ds_read_b128 v[170:173], v191 offset:17408
	ds_read_b128 v[174:177], v191 offset:18432
	ds_read_b128 v[178:181], v191 offset:19456
	ds_read_b128 v[194:197], v191 offset:20480
	ds_read_b128 v[198:201], v191 offset:21504
	ds_read_b128 v[202:205], v191 offset:22528
	ds_read_b128 v[206:209], v191 offset:23552
	global_load_lds_dwordx4 v[218:219], off
	s_mov_b32 m0, s47
	v_lshl_add_u64 v[230:231], s[68:69], 0, v[158:159]
	global_load_lds_dwordx4 v[230:231], off
	s_barrier
	s_waitcnt lgkmcnt(0)
	v_mfma_f32_16x16x32_bf16 v[52:55], v[134:137], v[166:169], v[52:55]
	v_mfma_f32_16x16x32_bf16 v[48:51], v[142:145], v[166:169], v[48:51]
	v_mfma_f32_16x16x32_bf16 v[44:47], v[134:137], v[174:177], v[44:47]
	v_mfma_f32_16x16x32_bf16 v[36:39], v[142:145], v[174:177], v[36:39]
	v_mfma_f32_16x16x32_bf16 v[28:31], v[134:137], v[194:197], v[28:31]
	v_mfma_f32_16x16x32_bf16 v[20:23], v[142:145], v[194:197], v[20:23]
	v_mfma_f32_16x16x32_bf16 v[12:15], v[134:137], v[202:205], v[12:15]
	v_mfma_f32_16x16x32_bf16 v[4:7], v[142:145], v[202:205], v[4:7]
	v_mfma_f32_16x16x32_bf16 v[52:55], v[138:141], v[170:173], v[52:55]
	v_mfma_f32_16x16x32_bf16 v[48:51], v[146:149], v[170:173], v[48:51]
	v_mfma_f32_16x16x32_bf16 v[44:47], v[138:141], v[178:181], v[44:47]
	v_mfma_f32_16x16x32_bf16 v[36:39], v[146:149], v[178:181], v[36:39]
	v_mfma_f32_16x16x32_bf16 v[28:31], v[138:141], v[198:201], v[28:31]
	v_mfma_f32_16x16x32_bf16 v[20:23], v[146:149], v[198:201], v[20:23]
	v_mfma_f32_16x16x32_bf16 v[12:15], v[138:141], v[206:209], v[12:15]
	v_mfma_f32_16x16x32_bf16 v[4:7], v[146:149], v[206:209], v[4:7]
	s_barrier
	s_add_u32 s70, s36, 0xb0000
	s_addc_u32 s71, s37, 0
	s_mov_b32 m0, s0
	v_lshl_add_u64 v[134:135], s[70:71], 0, v[156:157]
	global_load_lds_dwordx4 v[134:135], off
	s_mov_b32 m0, s62
	v_lshl_add_u64 v[134:135], s[70:71], 0, v[160:161]
	global_load_lds_dwordx4 v[134:135], off
	s_waitcnt vmcnt(6)
	s_barrier
	v_mfma_f32_16x16x32_bf16 v[60:63], v[210:213], v[166:169], v[60:63]
	v_mfma_f32_16x16x32_bf16 v[56:59], v[222:225], v[166:169], v[56:59]
	v_mfma_f32_16x16x32_bf16 v[40:43], v[210:213], v[174:177], v[40:43]
	v_mfma_f32_16x16x32_bf16 v[32:35], v[222:225], v[174:177], v[32:35]
	v_mfma_f32_16x16x32_bf16 v[24:27], v[210:213], v[194:197], v[24:27]
	v_mfma_f32_16x16x32_bf16 v[16:19], v[222:225], v[194:197], v[16:19]
	v_mfma_f32_16x16x32_bf16 v[8:11], v[210:213], v[202:205], v[8:11]
	v_mfma_f32_16x16x32_bf16 v[0:3], v[222:225], v[202:205], v[0:3]
	v_mfma_f32_16x16x32_bf16 v[60:63], v[214:217], v[170:173], v[60:63]
	v_mfma_f32_16x16x32_bf16 v[56:59], v[226:229], v[170:173], v[56:59]
	v_mfma_f32_16x16x32_bf16 v[40:43], v[214:217], v[178:181], v[40:43]
	v_mfma_f32_16x16x32_bf16 v[32:35], v[226:229], v[178:181], v[32:35]
	v_mfma_f32_16x16x32_bf16 v[24:27], v[214:217], v[198:201], v[24:27]
	v_mfma_f32_16x16x32_bf16 v[16:19], v[226:229], v[198:201], v[16:19]
	v_mfma_f32_16x16x32_bf16 v[8:11], v[214:217], v[206:209], v[8:11]
	v_mfma_f32_16x16x32_bf16 v[0:3], v[226:229], v[206:209], v[0:3]
	s_barrier
	ds_read_b128 v[134:137], v132
	ds_read_b128 v[138:141], v132 offset:1024
	ds_read_b128 v[142:145], v132 offset:2048
	ds_read_b128 v[146:149], v132 offset:3072
	s_add_u32 s68, s68, 0xb0000
	s_addc_u32 s69, s69, 0
	s_mov_b32 m0, s48
	v_lshl_add_u64 v[210:211], s[68:69], 0, v[154:155]
	ds_read_b128 v[166:169], v191 offset:32768
	ds_read_b128 v[170:173], v191 offset:33792
	ds_read_b128 v[174:177], v191 offset:34816
	ds_read_b128 v[178:181], v191 offset:35840
	ds_read_b128 v[194:197], v191 offset:36864
	ds_read_b128 v[198:201], v191 offset:37888
	ds_read_b128 v[202:205], v191 offset:38912
	ds_read_b128 v[206:209], v191 offset:39936
	global_load_lds_dwordx4 v[210:211], off
	s_mov_b32 m0, s49
	v_lshl_add_u64 v[210:211], s[68:69], 0, v[158:159]
	global_load_lds_dwordx4 v[210:211], off
	s_waitcnt lgkmcnt(8)
	s_barrier
	s_waitcnt lgkmcnt(0)
	v_mfma_f32_16x16x32_bf16 v[116:119], v[134:137], v[166:169], v[116:119]
	v_mfma_f32_16x16x32_bf16 v[112:115], v[142:145], v[166:169], v[112:115]
	v_mfma_f32_16x16x32_bf16 v[108:111], v[134:137], v[174:177], v[108:111]
	v_mfma_f32_16x16x32_bf16 v[104:107], v[142:145], v[174:177], v[104:107]
	v_mfma_f32_16x16x32_bf16 v[92:95], v[134:137], v[194:197], v[92:95]
	v_mfma_f32_16x16x32_bf16 v[88:91], v[142:145], v[194:197], v[88:91]
	v_mfma_f32_16x16x32_bf16 v[76:79], v[134:137], v[202:205], v[76:79]
	v_mfma_f32_16x16x32_bf16 v[72:75], v[142:145], v[202:205], v[72:75]
	v_mfma_f32_16x16x32_bf16 v[116:119], v[138:141], v[170:173], v[116:119]
	v_mfma_f32_16x16x32_bf16 v[112:115], v[146:149], v[170:173], v[112:115]
	v_mfma_f32_16x16x32_bf16 v[108:111], v[138:141], v[178:181], v[108:111]
	v_mfma_f32_16x16x32_bf16 v[104:107], v[146:149], v[178:181], v[104:107]
	v_mfma_f32_16x16x32_bf16 v[92:95], v[138:141], v[198:201], v[92:95]
	v_mfma_f32_16x16x32_bf16 v[88:91], v[146:149], v[198:201], v[88:91]
	v_mfma_f32_16x16x32_bf16 v[76:79], v[138:141], v[206:209], v[76:79]
	v_mfma_f32_16x16x32_bf16 v[72:75], v[146:149], v[206:209], v[72:75]
	s_barrier
	s_mov_b32 m0, s63
	v_lshl_add_u64 v[150:151], v[150:151], 0, s[10:11]
	ds_read_b128 v[210:213], v133
	ds_read_b128 v[214:217], v133 offset:1024
	ds_read_b128 v[222:225], v133 offset:2048
	ds_read_b128 v[226:229], v133 offset:3072
	global_load_lds_dwordx4 v[150:151], off
	s_mov_b32 m0, s64
	v_lshl_add_u64 v[150:151], v[182:183], 0, s[10:11]
	global_load_lds_dwordx4 v[150:151], off
	s_barrier
	s_waitcnt lgkmcnt(0)
	v_mfma_f32_16x16x32_bf16 v[124:127], v[210:213], v[166:169], v[124:127]
	v_mfma_f32_16x16x32_bf16 v[120:123], v[222:225], v[166:169], v[120:123]
	v_mfma_f32_16x16x32_bf16 v[100:103], v[210:213], v[174:177], v[100:103]
	v_mfma_f32_16x16x32_bf16 v[96:99], v[222:225], v[174:177], v[96:99]
	v_mfma_f32_16x16x32_bf16 v[84:87], v[210:213], v[194:197], v[84:87]
	v_mfma_f32_16x16x32_bf16 v[80:83], v[222:225], v[194:197], v[80:83]
	v_mfma_f32_16x16x32_bf16 v[68:71], v[210:213], v[202:205], v[68:71]
	v_mfma_f32_16x16x32_bf16 v[64:67], v[222:225], v[202:205], v[64:67]
	v_mfma_f32_16x16x32_bf16 v[124:127], v[214:217], v[170:173], v[124:127]
	v_mfma_f32_16x16x32_bf16 v[120:123], v[226:229], v[170:173], v[120:123]
	v_mfma_f32_16x16x32_bf16 v[100:103], v[214:217], v[178:181], v[100:103]
	v_mfma_f32_16x16x32_bf16 v[96:99], v[226:229], v[178:181], v[96:99]
	v_mfma_f32_16x16x32_bf16 v[84:87], v[214:217], v[198:201], v[84:87]
	v_mfma_f32_16x16x32_bf16 v[80:83], v[226:229], v[198:201], v[80:83]
	v_mfma_f32_16x16x32_bf16 v[68:71], v[214:217], v[206:209], v[68:71]
	v_mfma_f32_16x16x32_bf16 v[64:67], v[226:229], v[206:209], v[64:67]
	s_mov_b32 m0, s51
	v_lshl_add_u64 v[150:151], v[218:219], 0, s[10:11]
	s_barrier
	ds_read_b128 v[166:169], v191 offset:49152
	ds_read_b128 v[170:173], v191 offset:50176
	ds_read_b128 v[174:177], v191 offset:51200
	ds_read_b128 v[178:181], v191 offset:52224
	ds_read_b128 v[194:197], v191 offset:53248
	ds_read_b128 v[198:201], v191 offset:54272
	ds_read_b128 v[202:205], v191 offset:55296
	ds_read_b128 v[206:209], v191 offset:56320
	global_load_lds_dwordx4 v[150:151], off
	s_mov_b32 m0, s52
	v_lshl_add_u64 v[150:151], v[230:231], 0, s[10:11]
	global_load_lds_dwordx4 v[150:151], off
	s_barrier
;     ...
;         G_PAIR(0, 1);
; #pragma unroll 1
;         for (int t = 2; t < nt; t += 2) G_PAIR(t, 0);
	s_waitcnt lgkmcnt(0)
	v_mfma_f32_16x16x32_bf16 v[52:55], v[134:137], v[166:169], v[52:55]
	v_mfma_f32_16x16x32_bf16 v[48:51], v[142:145], v[166:169], v[48:51]
	v_mfma_f32_16x16x32_bf16 v[44:47], v[134:137], v[174:177], v[44:47]
	v_mfma_f32_16x16x32_bf16 v[36:39], v[142:145], v[174:177], v[36:39]
	v_mfma_f32_16x16x32_bf16 v[28:31], v[134:137], v[194:197], v[28:31]
	v_mfma_f32_16x16x32_bf16 v[20:23], v[142:145], v[194:197], v[20:23]
	v_mfma_f32_16x16x32_bf16 v[12:15], v[134:137], v[202:205], v[12:15]
	v_mfma_f32_16x16x32_bf16 v[4:7], v[142:145], v[202:205], v[4:7]
	v_mfma_f32_16x16x32_bf16 v[52:55], v[138:141], v[170:173], v[52:55]
	v_mfma_f32_16x16x32_bf16 v[48:51], v[146:149], v[170:173], v[48:51]
	v_mfma_f32_16x16x32_bf16 v[44:47], v[138:141], v[178:181], v[44:47]
	v_mfma_f32_16x16x32_bf16 v[36:39], v[146:149], v[178:181], v[36:39]
	v_mfma_f32_16x16x32_bf16 v[28:31], v[138:141], v[198:201], v[28:31]
	v_mfma_f32_16x16x32_bf16 v[20:23], v[146:149], v[198:201], v[20:23]
	v_mfma_f32_16x16x32_bf16 v[12:15], v[138:141], v[206:209], v[12:15]
	v_mfma_f32_16x16x32_bf16 v[4:7], v[146:149], v[206:209], v[4:7]
	s_barrier
	s_add_u32 s36, s36, 0xb0080
	s_addc_u32 s37, s37, 0
	s_mov_b32 m0, s65
	v_lshl_add_u64 v[134:135], s[36:37], 0, v[156:157]
	global_load_lds_dwordx4 v[134:135], off
	s_mov_b32 m0, s66
	v_lshl_add_u64 v[134:135], s[36:37], 0, v[160:161]
	global_load_lds_dwordx4 v[134:135], off
	s_waitcnt vmcnt(6)
	s_barrier
	v_mfma_f32_16x16x32_bf16 v[60:63], v[210:213], v[166:169], v[60:63]
	v_mfma_f32_16x16x32_bf16 v[56:59], v[222:225], v[166:169], v[56:59]
	v_mfma_f32_16x16x32_bf16 v[40:43], v[210:213], v[174:177], v[40:43]
	v_mfma_f32_16x16x32_bf16 v[32:35], v[222:225], v[174:177], v[32:35]
	v_mfma_f32_16x16x32_bf16 v[24:27], v[210:213], v[194:197], v[24:27]
	v_mfma_f32_16x16x32_bf16 v[16:19], v[222:225], v[194:197], v[16:19]
	v_mfma_f32_16x16x32_bf16 v[8:11], v[210:213], v[202:205], v[8:11]
	v_mfma_f32_16x16x32_bf16 v[0:3], v[222:225], v[202:205], v[0:3]
	v_mfma_f32_16x16x32_bf16 v[60:63], v[214:217], v[170:173], v[60:63]
	v_mfma_f32_16x16x32_bf16 v[56:59], v[226:229], v[170:173], v[56:59]
	v_mfma_f32_16x16x32_bf16 v[40:43], v[214:217], v[178:181], v[40:43]
	v_mfma_f32_16x16x32_bf16 v[32:35], v[226:229], v[178:181], v[32:35]
	v_mfma_f32_16x16x32_bf16 v[24:27], v[214:217], v[198:201], v[24:27]
	v_mfma_f32_16x16x32_bf16 v[16:19], v[226:229], v[198:201], v[16:19]
	v_mfma_f32_16x16x32_bf16 v[8:11], v[214:217], v[206:209], v[8:11]
	v_mfma_f32_16x16x32_bf16 v[0:3], v[226:229], v[206:209], v[0:3]
	s_add_i32 s67, s67, 2
	s_add_u32 s34, s34, 0x100
	s_addc_u32 s35, s35, 0
	s_cmp_gt_u32 s67, 39
	s_cbranch_scc0 .Lrot_357
	s_barrier
	ds_read_b128 v[134:137], v190
	ds_read_b128 v[138:141], v190 offset:1024
	ds_read_b128 v[142:145], v190 offset:2048
	ds_read_b128 v[146:149], v190 offset:3072
	s_mov_b32 m0, s54
	v_lshl_add_u64 v[150:151], v[128:129], 0, s[34:35]
	ds_read_b128 v[166:169], v191
	ds_read_b128 v[170:173], v191 offset:1024
	ds_read_b128 v[174:177], v191 offset:2048
	ds_read_b128 v[178:181], v191 offset:3072
	ds_read_b128 v[194:197], v191 offset:4096
	ds_read_b128 v[198:201], v191 offset:5120
	ds_read_b128 v[202:205], v191 offset:6144
	ds_read_b128 v[206:209], v191 offset:7168
	global_load_lds_dwordx4 v[150:151], off
	s_mov_b32 m0, s55
	v_lshl_add_u64 v[150:151], v[130:131], 0, s[34:35]
	global_load_lds_dwordx4 v[150:151], off
	s_waitcnt lgkmcnt(8)
	s_barrier
	s_waitcnt lgkmcnt(0)
	v_mfma_f32_16x16x32_bf16 v[116:119], v[134:137], v[166:169], v[116:119]
	s_add_i32 s36, s34, 0xfff50080
	v_mfma_f32_16x16x32_bf16 v[112:115], v[142:145], v[166:169], v[112:115]
	s_cmp_eq_u32 s67, 40
	v_mfma_f32_16x16x32_bf16 v[108:111], v[134:137], v[174:177], v[108:111]
	s_cselect_b32 s69, s27, s29
	v_mfma_f32_16x16x32_bf16 v[104:107], v[142:145], v[174:177], v[104:107]
	s_cselect_b32 s68, s26, s28
	v_mfma_f32_16x16x32_bf16 v[92:95], v[134:137], v[194:197], v[92:95]
	s_cselect_b32 s37, s9, s31
	v_mfma_f32_16x16x32_bf16 v[88:91], v[142:145], v[194:197], v[88:91]
	s_cselect_b32 s70, s8, s30
	v_mfma_f32_16x16x32_bf16 v[76:79], v[134:137], v[202:205], v[76:79]
	v_mfma_f32_16x16x32_bf16 v[72:75], v[142:145], v[202:205], v[72:75]
	v_mfma_f32_16x16x32_bf16 v[116:119], v[138:141], v[170:173], v[116:119]
	v_mfma_f32_16x16x32_bf16 v[112:115], v[146:149], v[170:173], v[112:115]
	v_mfma_f32_16x16x32_bf16 v[108:111], v[138:141], v[178:181], v[108:111]
	v_mfma_f32_16x16x32_bf16 v[104:107], v[146:149], v[178:181], v[104:107]
	v_mfma_f32_16x16x32_bf16 v[92:95], v[138:141], v[198:201], v[92:95]
	v_mfma_f32_16x16x32_bf16 v[88:91], v[146:149], v[198:201], v[88:91]
	v_mfma_f32_16x16x32_bf16 v[76:79], v[138:141], v[206:209], v[76:79]
	v_mfma_f32_16x16x32_bf16 v[72:75], v[146:149], v[206:209], v[72:75]
	s_barrier
	s_cselect_b32 s71, 0, s36
	s_add_u32 s36, s70, s71
	s_addc_u32 s37, s37, 0
	s_mov_b32 m0, s56
	v_lshl_add_u64 v[150:151], s[36:37], 0, v[156:157]
	ds_read_b128 v[210:213], v192
	ds_read_b128 v[214:217], v192 offset:1024
	ds_read_b128 v[222:225], v192 offset:2048
	ds_read_b128 v[226:229], v192 offset:3072
	global_load_lds_dwordx4 v[150:151], off
	s_mov_b32 m0, s57
	v_lshl_add_u64 v[182:183], s[36:37], 0, v[160:161]
	global_load_lds_dwordx4 v[182:183], off
	s_barrier
;     __device__ __forceinline__ void epi(const f32x4 (&acc)[2][2][4][2], const Unit& u, int wr, int wc, int fr, int fq) const {
;     ...
;                 for (int bj = 0; bj < 2; ++bj) xo[m][bj] = *(const u32x4*)(xb + (size_t)(row0 + ai * 128 + m * 16) * D + col0 + bj * 128);
	s_waitcnt lgkmcnt(0)
	v_mfma_f32_16x16x32_bf16 v[124:127], v[210:213], v[166:169], v[124:127]
	v_mfma_f32_16x16x32_bf16 v[120:123], v[222:225], v[166:169], v[120:123]
	v_mfma_f32_16x16x32_bf16 v[100:103], v[210:213], v[174:177], v[100:103]
	v_mfma_f32_16x16x32_bf16 v[96:99], v[222:225], v[174:177], v[96:99]
	v_mfma_f32_16x16x32_bf16 v[84:87], v[210:213], v[194:197], v[84:87]
	v_mfma_f32_16x16x32_bf16 v[80:83], v[222:225], v[194:197], v[80:83]
	v_mfma_f32_16x16x32_bf16 v[68:71], v[210:213], v[202:205], v[68:71]
	v_mfma_f32_16x16x32_bf16 v[64:67], v[222:225], v[202:205], v[64:67]
	v_mfma_f32_16x16x32_bf16 v[124:127], v[214:217], v[170:173], v[124:127]
	v_mfma_f32_16x16x32_bf16 v[120:123], v[226:229], v[170:173], v[120:123]
	v_mfma_f32_16x16x32_bf16 v[100:103], v[214:217], v[178:181], v[100:103]
	v_mfma_f32_16x16x32_bf16 v[96:99], v[226:229], v[178:181], v[96:99]
	v_mfma_f32_16x16x32_bf16 v[84:87], v[214:217], v[198:201], v[84:87]
	v_mfma_f32_16x16x32_bf16 v[80:83], v[226:229], v[198:201], v[80:83]
	v_mfma_f32_16x16x32_bf16 v[68:71], v[214:217], v[206:209], v[68:71]
	v_mfma_f32_16x16x32_bf16 v[64:67], v[226:229], v[206:209], v[64:67]
	s_add_u32 s68, s68, s71
	s_addc_u32 s69, s69, 0
	s_mov_b32 m0, s46
	v_lshl_add_u64 v[218:219], s[68:69], 0, v[154:155]
	s_barrier
	ds_read_b128 v[166:169], v191 offset:16384
	ds_read_b128 v[170:173], v191 offset:17408
	ds_read_b128 v[174:177], v191 offset:18432
	ds_read_b128 v[178:181], v191 offset:19456
	ds_read_b128 v[194:197], v191 offset:20480
	ds_read_b128 v[198:201], v191 offset:21504
	ds_read_b128 v[202:205], v191 offset:22528
	ds_read_b128 v[206:209], v191 offset:23552
	global_load_lds_dwordx4 v[218:219], off
	s_mov_b32 m0, s47
	v_lshl_add_u64 v[230:231], s[68:69], 0, v[158:159]
	global_load_lds_dwordx4 v[230:231], off
	s_barrier
	s_waitcnt lgkmcnt(0)
	v_mfma_f32_16x16x32_bf16 v[52:55], v[134:137], v[166:169], v[52:55]
	v_mfma_f32_16x16x32_bf16 v[48:51], v[142:145], v[166:169], v[48:51]
	v_mfma_f32_16x16x32_bf16 v[44:47], v[134:137], v[174:177], v[44:47]
	v_mfma_f32_16x16x32_bf16 v[36:39], v[142:145], v[174:177], v[36:39]
	v_mfma_f32_16x16x32_bf16 v[28:31], v[134:137], v[194:197], v[28:31]
	v_mfma_f32_16x16x32_bf16 v[20:23], v[142:145], v[194:197], v[20:23]
	v_mfma_f32_16x16x32_bf16 v[12:15], v[134:137], v[202:205], v[12:15]
	v_mfma_f32_16x16x32_bf16 v[4:7], v[142:145], v[202:205], v[4:7]
	v_mfma_f32_16x16x32_bf16 v[52:55], v[138:141], v[170:173], v[52:55]
	v_mfma_f32_16x16x32_bf16 v[48:51], v[146:149], v[170:173], v[48:51]
	v_mfma_f32_16x16x32_bf16 v[44:47], v[138:141], v[178:181], v[44:47]
	v_mfma_f32_16x16x32_bf16 v[36:39], v[146:149], v[178:181], v[36:39]
	v_mfma_f32_16x16x32_bf16 v[28:31], v[138:141], v[198:201], v[28:31]
	v_mfma_f32_16x16x32_bf16 v[20:23], v[146:149], v[198:201], v[20:23]
	v_mfma_f32_16x16x32_bf16 v[12:15], v[138:141], v[206:209], v[12:15]
	v_mfma_f32_16x16x32_bf16 v[4:7], v[146:149], v[206:209], v[4:7]
	s_barrier
	s_add_u32 s70, s36, 0xb0000
	s_addc_u32 s71, s37, 0
	s_mov_b32 m0, s0
	v_lshl_add_u64 v[134:135], s[70:71], 0, v[156:157]
	global_load_lds_dwordx4 v[134:135], off
	s_mov_b32 m0, s62
	v_lshl_add_u64 v[134:135], s[70:71], 0, v[160:161]
	global_load_lds_dwordx4 v[134:135], off
	s_waitcnt vmcnt(6)
	s_barrier
	v_mfma_f32_16x16x32_bf16 v[60:63], v[210:213], v[166:169], v[60:63]
	v_lshl_or_b32 v248, s40, 8, v189
	v_mfma_f32_16x16x32_bf16 v[56:59], v[222:225], v[166:169], v[56:59]
	v_lshl_add_u32 v250, s61, 8, v153
	v_mfma_f32_16x16x32_bf16 v[40:43], v[210:213], v[174:177], v[40:43]
	v_ashrrev_i32_e32 v249, 31, v248
	v_mfma_f32_16x16x32_bf16 v[32:35], v[222:225], v[174:177], v[32:35]
	v_lshlrev_b64 v[248:249], 1, v[248:249]
	v_mfma_f32_16x16x32_bf16 v[24:27], v[210:213], v[194:197], v[24:27]
	v_ashrrev_i32_e32 v251, 31, v250
	v_mfma_f32_16x16x32_bf16 v[16:19], v[222:225], v[194:197], v[16:19]
	v_lshl_add_u64 v[248:249], s[20:21], 0, v[248:249]
	v_mfma_f32_16x16x32_bf16 v[8:11], v[210:213], v[202:205], v[8:11]
	v_lshlrev_b64 v[250:251], 11, v[250:251]
	v_mfma_f32_16x16x32_bf16 v[0:3], v[222:225], v[202:205], v[0:3]
	v_lshl_add_u64 v[252:253], v[248:249], 0, v[250:251]
	v_mfma_f32_16x16x32_bf16 v[60:63], v[214:217], v[170:173], v[60:63]
	global_load_dwordx4 v[232:235], v[252:253], off
	v_mfma_f32_16x16x32_bf16 v[56:59], v[226:229], v[170:173], v[56:59]
	global_load_dwordx4 v[236:239], v[252:253], off offset:256
	v_mfma_f32_16x16x32_bf16 v[40:43], v[214:217], v[178:181], v[40:43]
	v_mov_b32_e32 v250, 0x8000
	v_mfma_f32_16x16x32_bf16 v[32:35], v[226:229], v[178:181], v[32:35]
	v_mov_b32_e32 v251, 0
	v_mfma_f32_16x16x32_bf16 v[24:27], v[214:217], v[198:201], v[24:27]
	v_lshl_add_u64 v[250:251], v[252:253], 0, v[250:251]
	v_mfma_f32_16x16x32_bf16 v[16:19], v[226:229], v[198:201], v[16:19]
	global_load_dwordx4 v[240:243], v[250:251], off
	v_mfma_f32_16x16x32_bf16 v[8:11], v[214:217], v[206:209], v[8:11]
	global_load_dwordx4 v[244:247], v[250:251], off offset:256
	v_mfma_f32_16x16x32_bf16 v[0:3], v[226:229], v[206:209], v[0:3]
	s_barrier
	ds_read_b128 v[134:137], v132
	ds_read_b128 v[138:141], v132 offset:1024
	ds_read_b128 v[142:145], v132 offset:2048
	ds_read_b128 v[146:149], v132 offset:3072
	s_add_u32 s68, s68, 0xb0000
	s_addc_u32 s69, s69, 0
	s_mov_b32 m0, s48
	v_lshl_add_u64 v[210:211], s[68:69], 0, v[154:155]
	ds_read_b128 v[166:169], v191 offset:32768
	ds_read_b128 v[170:173], v191 offset:33792
	ds_read_b128 v[174:177], v191 offset:34816
	ds_read_b128 v[178:181], v191 offset:35840
	ds_read_b128 v[194:197], v191 offset:36864
	ds_read_b128 v[198:201], v191 offset:37888
	ds_read_b128 v[202:205], v191 offset:38912
	ds_read_b128 v[206:209], v191 offset:39936
	global_load_lds_dwordx4 v[210:211], off
	s_mov_b32 m0, s49
	v_lshl_add_u64 v[210:211], s[68:69], 0, v[158:159]
	global_load_lds_dwordx4 v[210:211], off
	s_waitcnt lgkmcnt(8)
	s_barrier
	s_waitcnt lgkmcnt(0)
	v_mfma_f32_16x16x32_bf16 v[116:119], v[134:137], v[166:169], v[116:119]
	v_mfma_f32_16x16x32_bf16 v[112:115], v[142:145], v[166:169], v[112:115]
	v_mfma_f32_16x16x32_bf16 v[108:111], v[134:137], v[174:177], v[108:111]
	v_mfma_f32_16x16x32_bf16 v[104:107], v[142:145], v[174:177], v[104:107]
	v_mfma_f32_16x16x32_bf16 v[92:95], v[134:137], v[194:197], v[92:95]
	v_mfma_f32_16x16x32_bf16 v[88:91], v[142:145], v[194:197], v[88:91]
	v_mfma_f32_16x16x32_bf16 v[76:79], v[134:137], v[202:205], v[76:79]
	v_mfma_f32_16x16x32_bf16 v[72:75], v[142:145], v[202:205], v[72:75]
	v_mfma_f32_16x16x32_bf16 v[116:119], v[138:141], v[170:173], v[116:119]
	v_mfma_f32_16x16x32_bf16 v[112:115], v[146:149], v[170:173], v[112:115]
	v_mfma_f32_16x16x32_bf16 v[108:111], v[138:141], v[178:181], v[108:111]
	v_mfma_f32_16x16x32_bf16 v[104:107], v[146:149], v[178:181], v[104:107]
	v_mfma_f32_16x16x32_bf16 v[92:95], v[138:141], v[198:201], v[92:95]
	v_mfma_f32_16x16x32_bf16 v[88:91], v[146:149], v[198:201], v[88:91]
	v_mfma_f32_16x16x32_bf16 v[76:79], v[138:141], v[206:209], v[76:79]
	v_mfma_f32_16x16x32_bf16 v[72:75], v[146:149], v[206:209], v[72:75]
	s_barrier
	s_mov_b32 m0, s63
	v_lshl_add_u64 v[150:151], v[150:151], 0, s[10:11]
	ds_read_b128 v[210:213], v133
	ds_read_b128 v[214:217], v133 offset:1024
	ds_read_b128 v[222:225], v133 offset:2048
	ds_read_b128 v[226:229], v133 offset:3072
	global_load_lds_dwordx4 v[150:151], off
	s_mov_b32 m0, s64
	v_lshl_add_u64 v[150:151], v[182:183], 0, s[10:11]
	global_load_lds_dwordx4 v[150:151], off
	s_barrier
	s_waitcnt lgkmcnt(0)
	v_mfma_f32_16x16x32_bf16 v[124:127], v[210:213], v[166:169], v[124:127]
	v_mfma_f32_16x16x32_bf16 v[120:123], v[222:225], v[166:169], v[120:123]
	v_mfma_f32_16x16x32_bf16 v[100:103], v[210:213], v[174:177], v[100:103]
	v_mfma_f32_16x16x32_bf16 v[96:99], v[222:225], v[174:177], v[96:99]
	v_mfma_f32_16x16x32_bf16 v[84:87], v[210:213], v[194:197], v[84:87]
	v_mfma_f32_16x16x32_bf16 v[80:83], v[222:225], v[194:197], v[80:83]
	v_mfma_f32_16x16x32_bf16 v[68:71], v[210:213], v[202:205], v[68:71]
	v_mfma_f32_16x16x32_bf16 v[64:67], v[222:225], v[202:205], v[64:67]
	v_mfma_f32_16x16x32_bf16 v[124:127], v[214:217], v[170:173], v[124:127]
	v_mfma_f32_16x16x32_bf16 v[120:123], v[226:229], v[170:173], v[120:123]
	v_mfma_f32_16x16x32_bf16 v[100:103], v[214:217], v[178:181], v[100:103]
	v_mfma_f32_16x16x32_bf16 v[96:99], v[226:229], v[178:181], v[96:99]
	v_mfma_f32_16x16x32_bf16 v[84:87], v[214:217], v[198:201], v[84:87]
	v_mfma_f32_16x16x32_bf16 v[80:83], v[226:229], v[198:201], v[80:83]
	v_mfma_f32_16x16x32_bf16 v[68:71], v[214:217], v[206:209], v[68:71]
	v_mfma_f32_16x16x32_bf16 v[64:67], v[226:229], v[206:209], v[64:67]
	s_mov_b32 m0, s51
	v_lshl_add_u64 v[150:151], v[218:219], 0, s[10:11]
	s_barrier
	ds_read_b128 v[166:169], v191 offset:49152
	ds_read_b128 v[170:173], v191 offset:50176
	ds_read_b128 v[174:177], v191 offset:51200
	ds_read_b128 v[178:181], v191 offset:52224
	ds_read_b128 v[194:197], v191 offset:53248
	ds_read_b128 v[198:201], v191 offset:54272
	ds_read_b128 v[202:205], v191 offset:55296
	ds_read_b128 v[206:209], v191 offset:56320
	global_load_lds_dwordx4 v[150:151], off
	s_mov_b32 m0, s52
	v_lshl_add_u64 v[150:151], v[230:231], 0, s[10:11]
	global_load_lds_dwordx4 v[150:151], off
	s_barrier
	s_waitcnt lgkmcnt(0)
	v_mfma_f32_16x16x32_bf16 v[52:55], v[134:137], v[166:169], v[52:55]
	v_mfma_f32_16x16x32_bf16 v[48:51], v[142:145], v[166:169], v[48:51]
	v_mfma_f32_16x16x32_bf16 v[44:47], v[134:137], v[174:177], v[44:47]
	v_mfma_f32_16x16x32_bf16 v[36:39], v[142:145], v[174:177], v[36:39]
	v_mfma_f32_16x16x32_bf16 v[28:31], v[134:137], v[194:197], v[28:31]
	v_mfma_f32_16x16x32_bf16 v[20:23], v[142:145], v[194:197], v[20:23]
	v_mfma_f32_16x16x32_bf16 v[12:15], v[134:137], v[202:205], v[12:15]
	v_mfma_f32_16x16x32_bf16 v[4:7], v[142:145], v[202:205], v[4:7]
	v_mfma_f32_16x16x32_bf16 v[52:55], v[138:141], v[170:173], v[52:55]
	v_mfma_f32_16x16x32_bf16 v[48:51], v[146:149], v[170:173], v[48:51]
	v_mfma_f32_16x16x32_bf16 v[44:47], v[138:141], v[178:181], v[44:47]
	v_mfma_f32_16x16x32_bf16 v[36:39], v[146:149], v[178:181], v[36:39]
	v_mfma_f32_16x16x32_bf16 v[28:31], v[138:141], v[198:201], v[28:31]
	v_mfma_f32_16x16x32_bf16 v[20:23], v[146:149], v[198:201], v[20:23]
	v_mfma_f32_16x16x32_bf16 v[12:15], v[138:141], v[206:209], v[12:15]
	v_mfma_f32_16x16x32_bf16 v[4:7], v[146:149], v[206:209], v[4:7]
	s_barrier
	s_add_u32 s36, s36, 0xb0080
	s_addc_u32 s37, s37, 0
	s_mov_b32 m0, s65
	v_lshl_add_u64 v[134:135], s[36:37], 0, v[156:157]
	global_load_lds_dwordx4 v[134:135], off
	s_mov_b32 m0, s66
	v_lshl_add_u64 v[134:135], s[36:37], 0, v[160:161]
	global_load_lds_dwordx4 v[134:135], off
	s_waitcnt vmcnt(6)
	s_barrier
	v_mfma_f32_16x16x32_bf16 v[60:63], v[210:213], v[166:169], v[60:63]
	v_mfma_f32_16x16x32_bf16 v[56:59], v[222:225], v[166:169], v[56:59]
	v_mfma_f32_16x16x32_bf16 v[40:43], v[210:213], v[174:177], v[40:43]
	v_mfma_f32_16x16x32_bf16 v[32:35], v[222:225], v[174:177], v[32:35]
	v_mfma_f32_16x16x32_bf16 v[24:27], v[210:213], v[194:197], v[24:27]
	v_mfma_f32_16x16x32_bf16 v[16:19], v[222:225], v[194:197], v[16:19]
	v_mfma_f32_16x16x32_bf16 v[8:11], v[210:213], v[202:205], v[8:11]
	v_mfma_f32_16x16x32_bf16 v[0:3], v[222:225], v[202:205], v[0:3]
	v_mfma_f32_16x16x32_bf16 v[60:63], v[214:217], v[170:173], v[60:63]
	v_mfma_f32_16x16x32_bf16 v[56:59], v[226:229], v[170:173], v[56:59]
	v_mfma_f32_16x16x32_bf16 v[40:43], v[214:217], v[178:181], v[40:43]
	v_mfma_f32_16x16x32_bf16 v[32:35], v[226:229], v[178:181], v[32:35]
	v_mfma_f32_16x16x32_bf16 v[24:27], v[214:217], v[198:201], v[24:27]
	v_mfma_f32_16x16x32_bf16 v[16:19], v[226:229], v[198:201], v[16:19]
	v_mfma_f32_16x16x32_bf16 v[8:11], v[214:217], v[206:209], v[8:11]
	v_mfma_f32_16x16x32_bf16 v[0:3], v[226:229], v[206:209], v[0:3]
	s_add_i32 s67, s67, 2
	s_add_u32 s34, s34, 0x100
	s_addc_u32 s35, s35, 0
	s_cmp_gt_u32 s67, 41
	s_barrier
; __device__ __forceinline__ unsigned pk2(float lo, float hi) { unsigned r; asm volatile("v_cvt_pk_bf16_f32 %0, %1, %2" : "=v"(r) : "v"(lo), "v"(hi)); return r; }
; __device__ __forceinline__ unsigned pk2(float lo, float hi) { return f2bf(lo) | (f2bf(hi) << 16); }
;     __device__ __forceinline__ void epi(const f32x4 (&acc)[2][2][4][2], const Unit& u, int wr, int wc, int fr, int fq) const {
;     ...
;         for (int ai = 0; ai < 2; ++ai) {
;             u32x4 xo[4][2];
; #pragma unroll
;             for (int m = 0; m < 4; ++m)
; #pragma unroll
;                 for (int bj = 0; bj < 2; ++bj) xo[m][bj] = *(const u32x4*)(xb + (size_t)(row0 + ai * 128 + m * 16) * D + col0 + bj * 128);
; #pragma unroll
;             for (int m = 0; m < 4; ++m) {
;                 const int row = row0 + ai * 128 + m * 16; const size_t off = (size_t)row * D + col0; float ss = 0.f;
; #pragma unroll
;                 for (int bj = 0; bj < 2; ++bj) {
;                     const u32x4 o = xo[m][bj]; const f32x4 a0v = acc[ai][bj][m][0], a1v = acc[ai][bj][m][1];
;                     const float v0 = bf_lo(o.x) + coef * a0v[0], v1 = bf_hi(o.x) + coef * a0v[1], v2 = bf_lo(o.y) + coef * a0v[2], v3 = bf_hi(o.y) + coef * a0v[3];
;                     const float v4 = bf_lo(o.z) + coef * a1v[0], v5 = bf_hi(o.z) + coef * a1v[1], v6 = bf_lo(o.w) + coef * a1v[2], v7 = bf_hi(o.w) + coef * a1v[3];
;                     u32x4 w; w.x = pk2(v0, v1); w.y = pk2(v2, v3); w.z = pk2(v4, v5); w.w = pk2(v6, v7);
;                     *(u32x4*)(xb + off + bj * 128) = w;
;                     ss += ((v0 * v0 + v1 * v1) + (v2 * v2 + v3 * v3)) + ((v4 * v4 + v5 * v5) + (v6 * v6 + v7 * v7));
;                 }
;                 ss += __shfl_xor(ss, 16); ss += __shfl_xor(ss, 32);
;                 if (fq == 0) rowss[(size_t)row * 32 + u.pn * 4 + wc] = ss;
;             }
	v_lshl_or_b32 v166, s40, 8, v189
	v_lshl_add_u32 v170, s61, 8, v153
	v_ashrrev_i32_e32 v167, 31, v166
	v_lshlrev_b64 v[202:203], 1, v[166:167]
	v_ashrrev_i32_e32 v171, 31, v170
	v_lshl_add_u64 v[168:169], s[20:21], 0, v[202:203]
	v_lshlrev_b64 v[204:205], 11, v[170:171]
	v_lshl_add_u64 v[128:129], v[168:169], 0, v[204:205]
	v_mov_b32_e32 v218, 0x40000
	v_mov_b32_e32 v219, 0
	v_lshl_add_u64 v[216:217], v[128:129], 0, v[218:219]
	v_mov_b32_e32 v218, 0x8000
	s_waitcnt vmcnt(8)
	v_mov_b64_e32 v[194:195], v[232:233]
	v_mov_b64_e32 v[196:197], v[234:235]
	v_mov_b64_e32 v[198:199], v[236:237]
	v_mov_b64_e32 v[200:201], v[238:239]
	v_or_b32_e32 v180, 16, v170
	v_or_b32_e32 v176, 32, v170
	v_or_b32_e32 v172, 48, v170
	v_ashrrev_i32_e32 v181, 31, v180
	v_ashrrev_i32_e32 v177, 31, v176
	v_ashrrev_i32_e32 v173, 31, v172
	v_lshlrev_b64 v[182:183], 11, v[180:181]
	v_lshlrev_b64 v[178:179], 11, v[176:177]
	v_lshlrev_b64 v[174:175], 11, v[172:173]
	v_lshl_add_u64 v[128:129], v[168:169], 0, v[182:183]
	v_lshl_add_u64 v[130:131], v[168:169], 0, v[178:179]
	v_lshl_add_u64 v[206:207], v[168:169], 0, v[174:175]
	v_mov_b64_e32 v[148:149], v[240:241]
	v_mov_b64_e32 v[150:151], v[242:243]
	v_mov_b64_e32 v[144:145], v[244:245]
	v_mov_b64_e32 v[146:147], v[246:247]
	global_load_dwordx4 v[140:143], v[130:131], off
	global_load_dwordx4 v[136:139], v[130:131], off offset:256
	global_load_dwordx4 v[132:135], v[206:207], off
	s_nop 0
	global_load_dwordx4 v[128:131], v[206:207], off offset:256
	global_load_dwordx4 v[222:225], v[216:217], off
	global_load_dwordx4 v[226:229], v[216:217], off offset:256
	v_lshl_add_u64 v[216:217], v[216:217], 0, v[218:219]
	global_load_dwordx4 v[230:233], v[216:217], off
	global_load_dwordx4 v[234:237], v[216:217], off offset:256
	v_lshl_add_u64 v[216:217], v[216:217], 0, v[218:219]
	global_load_dwordx4 v[238:241], v[216:217], off
	global_load_dwordx4 v[242:245], v[216:217], off offset:256
	v_lshl_add_u64 v[216:217], v[216:217], 0, v[218:219]
	global_load_dwordx4 v[246:249], v[216:217], off
	global_load_dwordx4 v[250:253], v[216:217], off offset:256
	v_and_b32_e32 v206, 64, v193
	v_xor_b32_e32 v208, 16, v193
	v_add_u32_e32 v206, 64, v206
	v_cmp_lt_i32_e32 vcc, v208, v206
	v_lshlrev_b32_e32 v209, 16, v195
	v_cndmask_b32_e32 v207, v193, v208, vcc
	v_lshlrev_b32_e32 v208, 16, v194
	v_and_b32_e32 v194, 0xffff0000, v194
	v_and_b32_e32 v195, 0xffff0000, v195
	v_lshlrev_b32_e32 v210, 16, v196
	v_and_b32_e32 v196, 0xffff0000, v196
	v_lshlrev_b32_e32 v211, 16, v197
	v_and_b32_e32 v197, 0xffff0000, v197
	v_lshlrev_b32_e32 v212, 16, v198
	v_and_b32_e32 v198, 0xffff0000, v198
	v_lshlrev_b32_e32 v213, 16, v199
	v_and_b32_e32 v199, 0xffff0000, v199
	v_lshlrev_b32_e32 v214, 16, v200
	v_and_b32_e32 v200, 0xffff0000, v200
	v_lshlrev_b32_e32 v215, 16, v201
	v_and_b32_e32 v201, 0xffff0000, v201
	v_fmac_f32_e32 v194, 0.5, v117
	v_fmac_f32_e32 v195, 0.5, v119
	v_fmac_f32_e32 v196, 0.5, v113
	v_fmac_f32_e32 v197, 0.5, v115
	v_fmac_f32_e32 v198, 0.5, v125
	v_fmac_f32_e32 v199, 0.5, v127
	v_fmac_f32_e32 v200, 0.5, v121
	v_fmac_f32_e32 v201, 0.5, v123
	v_fmac_f32_e32 v208, 0.5, v116
	v_fmac_f32_e32 v209, 0.5, v118
	v_fmac_f32_e32 v210, 0.5, v112
	v_fmac_f32_e32 v211, 0.5, v114
	v_fmac_f32_e32 v212, 0.5, v124
	v_fmac_f32_e32 v213, 0.5, v126
	v_fmac_f32_e32 v214, 0.5, v120
	v_fmac_f32_e32 v215, 0.5, v122
	v_mul_f32_e32 v112, v194, v194
	v_mul_f32_e32 v113, v195, v195
	v_mul_f32_e32 v118, v196, v196
	v_mul_f32_e32 v119, v197, v197
	v_mul_f32_e32 v120, v198, v198
	v_mul_f32_e32 v121, v199, v199
	v_mul_f32_e32 v122, v200, v200
	v_mul_f32_e32 v123, v201, v201
	v_fmac_f32_e32 v112, v208, v208
	v_fmac_f32_e32 v113, v209, v209
	v_fmac_f32_e32 v118, v210, v210
	v_fmac_f32_e32 v119, v211, v211
	v_fmac_f32_e32 v120, v212, v212
	v_fmac_f32_e32 v121, v213, v213
	v_fmac_f32_e32 v122, v214, v214
	v_fmac_f32_e32 v123, v215, v215
	v_add_f32_e32 v112, v112, v113
	v_add_f32_e32 v113, v118, v119
	v_add_f32_e32 v118, v120, v121
	v_add_f32_e32 v119, v122, v123
	v_add_f32_e32 v112, v112, v113
	v_add_f32_e32 v113, v118, v119
	v_add_f32_e32 v113, v112, v113
	v_lshlrev_b32_e32 v112, 2, v207
	v_mov_b32_e32 v122, v113
	s_nop 1
	v_permlane16_swap_b32 v122, v113
	v_lshl_add_u64 v[118:119], s[20:21], 0, v[204:205]
	v_cvt_pk_bf16_f32 v114, v208, v194
	v_lshl_add_u64 v[120:121], v[118:119], 0, v[202:203]
	v_cvt_pk_bf16_f32 v115, v209, v195
	v_cvt_pk_bf16_f32 v116, v210, v196
	v_cvt_pk_bf16_f32 v117, v211, v197
	global_store_dwordx4 v[120:121], v[114:117], off
	s_waitcnt lgkmcnt(0)
	s_nop 0
	v_add_f32_e32 v114, v113, v122
	v_xor_b32_e32 v113, 32, v193
	v_cmp_lt_i32_e32 vcc, v113, v206
	v_cvt_pk_bf16_f32 v116, v212, v198
	v_cvt_pk_bf16_f32 v117, v213, v199
	v_cvt_pk_bf16_f32 v118, v214, v200
	v_cvt_pk_bf16_f32 v119, v215, v201
	global_store_dwordx4 v[120:121], v[116:119], off offset:256
	s_nop 0
	v_cndmask_b32_e32 v113, v193, v113, vcc
	v_lshlrev_b32_e32 v113, 2, v113
	v_mov_b32_e32 v115, v114
	s_nop 1
	v_permlane32_swap_b32 v115, v114
	s_and_saveexec_b64 s[28:29], s[6:7]
	s_cbranch_execz .LBB0_360
	s_waitcnt lgkmcnt(0)
	v_add_f32_e32 v116, v114, v115
	s_lshl_b32 s30, s40, 2
	v_lshlrev_b64 v[114:115], 7, v[170:171]
	s_ashr_i32 s31, s30, 31
	v_lshl_add_u64 v[114:115], s[2:3], 0, v[114:115]
	v_lshl_add_u64 v[114:115], s[30:31], 2, v[114:115]
	s_lshl_b32 s0, s50, 2
	v_lshl_add_u64 v[114:115], v[114:115], 0, s[0:1]
	global_store_dword v[114:115], v116, off
; __device__ __forceinline__ unsigned pk2(float lo, float hi) { unsigned r; asm volatile("v_cvt_pk_bf16_f32 %0, %1, %2" : "=v"(r) : "v"(lo), "v"(hi)); return r; }
; __device__ __forceinline__ unsigned pk2(float lo, float hi) { return f2bf(lo) | (f2bf(hi) << 16); }
;     __device__ __forceinline__ void epi(const f32x4 (&acc)[2][2][4][2], const Unit& u, int wr, int wc, int fr, int fq) const {
;     ...
;             for (int m = 0; m < 4; ++m) {
;                 const int row = row0 + ai * 128 + m * 16; const size_t off = (size_t)row * D + col0; float ss = 0.f;
; #pragma unroll
;                 for (int bj = 0; bj < 2; ++bj) {
;                     const u32x4 o = xo[m][bj]; const f32x4 a0v = acc[ai][bj][m][0], a1v = acc[ai][bj][m][1];
;                     const float v0 = bf_lo(o.x) + coef * a0v[0], v1 = bf_hi(o.x) + coef * a0v[1], v2 = bf_lo(o.y) + coef * a0v[2], v3 = bf_hi(o.y) + coef * a0v[3];
;                     const float v4 = bf_lo(o.z) + coef * a1v[0], v5 = bf_hi(o.z) + coef * a1v[1], v6 = bf_lo(o.w) + coef * a1v[2], v7 = bf_hi(o.w) + coef * a1v[3];
;                     u32x4 w; w.x = pk2(v0, v1); w.y = pk2(v2, v3); w.z = pk2(v4, v5); w.w = pk2(v6, v7);
;                     *(u32x4*)(xb + off + bj * 128) = w;
;                     ss += ((v0 * v0 + v1 * v1) + (v2 * v2 + v3 * v3)) + ((v4 * v4 + v5 * v5) + (v6 * v6 + v7 * v7));
;                 }
;                 ss += __shfl_xor(ss, 16); ss += __shfl_xor(ss, 32);
;                 if (fq == 0) rowss[(size_t)row * 32 + u.pn * 4 + wc] = ss;
;             }
.LBB0_360:
	s_or_b64 exec, exec, s[28:29]
	v_lshlrev_b32_e32 v114, 16, v148
	v_fmac_f32_e32 v114, 0.5, v108
	v_and_b32_e32 v108, 0xffff0000, v148
	v_fmac_f32_e32 v108, 0.5, v109
	v_lshlrev_b32_e32 v109, 16, v149
	v_fmac_f32_e32 v109, 0.5, v110
	v_and_b32_e32 v110, 0xffff0000, v149
	v_fmac_f32_e32 v110, 0.5, v111
	v_lshlrev_b32_e32 v111, 16, v150
	s_waitcnt lgkmcnt(0)
	v_and_b32_e32 v115, 0xffff0000, v150
	v_fmac_f32_e32 v111, 0.5, v104
	v_fmac_f32_e32 v115, 0.5, v105
	v_and_b32_e32 v117, 0xffff0000, v151
	v_cvt_pk_bf16_f32 v104, v114, v108
	v_cvt_pk_bf16_f32 v105, v109, v110
	v_mul_f32_e32 v108, v108, v108
	v_mul_f32_e32 v110, v110, v110
	v_lshlrev_b32_e32 v116, 16, v151
	v_fmac_f32_e32 v117, 0.5, v107
	v_fmac_f32_e32 v108, v114, v114
	v_fmac_f32_e32 v110, v109, v109
	v_fmac_f32_e32 v116, 0.5, v106
	v_add_f32_e32 v108, v108, v110
	v_mul_f32_e32 v109, v115, v115
	v_mul_f32_e32 v110, v117, v117
	v_fmac_f32_e32 v109, v111, v111
	v_fmac_f32_e32 v110, v116, v116
	v_add_f32_e32 v109, v109, v110
	v_add_f32_e32 v108, v108, v109
	v_lshlrev_b32_e32 v109, 16, v144
	v_fmac_f32_e32 v109, 0.5, v100
	v_and_b32_e32 v100, 0xffff0000, v144
	v_and_b32_e32 v110, 0xffff0000, v145
	v_cvt_pk_bf16_f32 v106, v111, v115
	v_fmac_f32_e32 v100, 0.5, v101
	v_lshlrev_b32_e32 v101, 16, v145
	v_fmac_f32_e32 v110, 0.5, v103
	v_lshlrev_b32_e32 v111, 16, v146
	v_and_b32_e32 v114, 0xffff0000, v146
	v_cvt_pk_bf16_f32 v107, v116, v117
	v_fmac_f32_e32 v101, 0.5, v102
	v_fmac_f32_e32 v111, 0.5, v96
	v_fmac_f32_e32 v114, 0.5, v97
	v_and_b32_e32 v116, 0xffff0000, v147
	v_mul_f32_e32 v96, v100, v100
	v_mul_f32_e32 v97, v110, v110
	v_lshlrev_b32_e32 v115, 16, v147
	v_fmac_f32_e32 v116, 0.5, v99
	v_fmac_f32_e32 v96, v109, v109
	v_fmac_f32_e32 v97, v101, v101
	v_fmac_f32_e32 v115, 0.5, v98
	v_add_f32_e32 v96, v96, v97
	v_mul_f32_e32 v97, v114, v114
	v_mul_f32_e32 v98, v116, v116
	v_fmac_f32_e32 v97, v111, v111
	v_fmac_f32_e32 v98, v115, v115
	v_add_f32_e32 v97, v97, v98
	v_add_f32_e32 v96, v96, v97
	v_add_f32_e32 v99, v108, v96
	v_mov_b32_e32 v108, v99
	s_nop 1
	v_permlane16_swap_b32 v108, v99
	v_lshl_add_u64 v[96:97], s[20:21], 0, v[182:183]
	v_lshl_add_u64 v[102:103], v[166:167], 1, v[96:97]
	global_store_dwordx4 v[102:103], v[104:107], off
	v_cvt_pk_bf16_f32 v98, v109, v100
	s_waitcnt lgkmcnt(0)
	v_add_f32_e32 v96, v99, v108
	v_mov_b32_e32 v97, v96
	s_nop 1
	v_permlane32_swap_b32 v97, v96
	v_cvt_pk_bf16_f32 v99, v101, v110
	v_cvt_pk_bf16_f32 v100, v111, v114
	v_cvt_pk_bf16_f32 v101, v115, v116
	global_store_dwordx4 v[102:103], v[98:101], off offset:256
	s_and_saveexec_b64 s[28:29], s[6:7]
	s_cbranch_execz .LBB0_362
	s_waitcnt lgkmcnt(0)
	v_add_f32_e32 v98, v96, v97
	s_lshl_b32 s30, s40, 2
	v_lshlrev_b64 v[96:97], 7, v[180:181]
	s_ashr_i32 s31, s30, 31
	v_lshl_add_u64 v[96:97], s[2:3], 0, v[96:97]
	v_lshl_add_u64 v[96:97], s[30:31], 2, v[96:97]
	s_lshl_b32 s0, s50, 2
	v_lshl_add_u64 v[96:97], v[96:97], 0, s[0:1]
	global_store_dword v[96:97], v98, off
.LBB0_362:
	s_or_b64 exec, exec, s[28:29]
	s_waitcnt vmcnt(12)
	v_lshlrev_b32_e32 v96, 16, v140
	v_fmac_f32_e32 v96, 0.5, v92
	v_and_b32_e32 v92, 0xffff0000, v140
	v_fmac_f32_e32 v92, 0.5, v93
	v_lshlrev_b32_e32 v93, 16, v141
	v_fmac_f32_e32 v93, 0.5, v94
	v_and_b32_e32 v94, 0xffff0000, v141
	v_fmac_f32_e32 v94, 0.5, v95
	v_lshlrev_b32_e32 v95, 16, v142
	s_waitcnt lgkmcnt(0)
	v_and_b32_e32 v97, 0xffff0000, v142
	v_fmac_f32_e32 v95, 0.5, v88
	v_fmac_f32_e32 v97, 0.5, v89
	v_and_b32_e32 v99, 0xffff0000, v143
	v_cvt_pk_bf16_f32 v88, v96, v92
	v_cvt_pk_bf16_f32 v89, v93, v94
	v_mul_f32_e32 v92, v92, v92
	v_mul_f32_e32 v94, v94, v94
	v_lshlrev_b32_e32 v98, 16, v143
	v_fmac_f32_e32 v99, 0.5, v91
	v_fmac_f32_e32 v92, v96, v96
	v_fmac_f32_e32 v94, v93, v93
	v_fmac_f32_e32 v98, 0.5, v90
	v_add_f32_e32 v92, v92, v94
	v_mul_f32_e32 v93, v97, v97
	v_mul_f32_e32 v94, v99, v99
	v_fmac_f32_e32 v93, v95, v95
	v_fmac_f32_e32 v94, v98, v98
	v_add_f32_e32 v93, v93, v94
	v_add_f32_e32 v92, v92, v93
	v_lshlrev_b32_e32 v93, 16, v136
	v_fmac_f32_e32 v93, 0.5, v84
	v_and_b32_e32 v84, 0xffff0000, v136
	v_and_b32_e32 v94, 0xffff0000, v137
	v_cvt_pk_bf16_f32 v90, v95, v97
	v_fmac_f32_e32 v84, 0.5, v85
	v_lshlrev_b32_e32 v85, 16, v137
	v_fmac_f32_e32 v94, 0.5, v87
	v_lshlrev_b32_e32 v95, 16, v138
	v_and_b32_e32 v96, 0xffff0000, v138
	v_cvt_pk_bf16_f32 v91, v98, v99
	v_fmac_f32_e32 v85, 0.5, v86
	v_fmac_f32_e32 v95, 0.5, v80
	v_fmac_f32_e32 v96, 0.5, v81
	v_and_b32_e32 v98, 0xffff0000, v139
	v_mul_f32_e32 v80, v84, v84
	v_mul_f32_e32 v81, v94, v94
	v_lshlrev_b32_e32 v97, 16, v139
	v_fmac_f32_e32 v98, 0.5, v83
	v_fmac_f32_e32 v80, v93, v93
	v_fmac_f32_e32 v81, v85, v85
	v_fmac_f32_e32 v97, 0.5, v82
	v_add_f32_e32 v80, v80, v81
	v_mul_f32_e32 v81, v96, v96
	v_mul_f32_e32 v82, v98, v98
	v_fmac_f32_e32 v81, v95, v95
	v_fmac_f32_e32 v82, v97, v97
	v_add_f32_e32 v81, v81, v82
	v_add_f32_e32 v80, v80, v81
	v_add_f32_e32 v83, v92, v80
	v_mov_b32_e32 v92, v83
	s_nop 1
	v_permlane16_swap_b32 v92, v83
	v_lshl_add_u64 v[80:81], s[20:21], 0, v[178:179]
	v_lshl_add_u64 v[86:87], v[166:167], 1, v[80:81]
	global_store_dwordx4 v[86:87], v[88:91], off
	v_cvt_pk_bf16_f32 v82, v93, v84
	s_waitcnt lgkmcnt(0)
	v_add_f32_e32 v80, v83, v92
	v_mov_b32_e32 v81, v80
	s_nop 1
	v_permlane32_swap_b32 v81, v80
	v_cvt_pk_bf16_f32 v83, v85, v94
	v_cvt_pk_bf16_f32 v84, v95, v96
	v_cvt_pk_bf16_f32 v85, v97, v98
	global_store_dwordx4 v[86:87], v[82:85], off offset:256
	s_and_saveexec_b64 s[28:29], s[6:7]
	s_cbranch_execz .LBB0_364
	s_waitcnt lgkmcnt(0)
	v_add_f32_e32 v82, v80, v81
	s_lshl_b32 s30, s40, 2
	v_lshlrev_b64 v[80:81], 7, v[176:177]
	s_ashr_i32 s31, s30, 31
	v_lshl_add_u64 v[80:81], s[2:3], 0, v[80:81]
	v_lshl_add_u64 v[80:81], s[30:31], 2, v[80:81]
	s_lshl_b32 s0, s50, 2
	v_lshl_add_u64 v[80:81], v[80:81], 0, s[0:1]
	global_store_dword v[80:81], v82, off
; __device__ __forceinline__ unsigned pk2(float lo, float hi) { unsigned r; asm volatile("v_cvt_pk_bf16_f32 %0, %1, %2" : "=v"(r) : "v"(lo), "v"(hi)); return r; }
; __device__ __forceinline__ unsigned pk2(float lo, float hi) { return f2bf(lo) | (f2bf(hi) << 16); }
;     __device__ __forceinline__ void epi(const f32x4 (&acc)[2][2][4][2], const Unit& u, int wr, int wc, int fr, int fq) const {
;     ...
;         for (int ai = 0; ai < 2; ++ai) {
;             u32x4 xo[4][2];
; #pragma unroll
;             for (int m = 0; m < 4; ++m)
; #pragma unroll
;                 for (int bj = 0; bj < 2; ++bj) xo[m][bj] = *(const u32x4*)(xb + (size_t)(row0 + ai * 128 + m * 16) * D + col0 + bj * 128);
; #pragma unroll
;             for (int m = 0; m < 4; ++m) {
;                 const int row = row0 + ai * 128 + m * 16; const size_t off = (size_t)row * D + col0; float ss = 0.f;
; #pragma unroll
;                 for (int bj = 0; bj < 2; ++bj) {
;                     const u32x4 o = xo[m][bj]; const f32x4 a0v = acc[ai][bj][m][0], a1v = acc[ai][bj][m][1];
;                     const float v0 = bf_lo(o.x) + coef * a0v[0], v1 = bf_hi(o.x) + coef * a0v[1], v2 = bf_lo(o.y) + coef * a0v[2], v3 = bf_hi(o.y) + coef * a0v[3];
;                     const float v4 = bf_lo(o.z) + coef * a1v[0], v5 = bf_hi(o.z) + coef * a1v[1], v6 = bf_lo(o.w) + coef * a1v[2], v7 = bf_hi(o.w) + coef * a1v[3];
;                     u32x4 w; w.x = pk2(v0, v1); w.y = pk2(v2, v3); w.z = pk2(v4, v5); w.w = pk2(v6, v7);
;                     *(u32x4*)(xb + off + bj * 128) = w;
;                     ss += ((v0 * v0 + v1 * v1) + (v2 * v2 + v3 * v3)) + ((v4 * v4 + v5 * v5) + (v6 * v6 + v7 * v7));
;                 }
;                 ss += __shfl_xor(ss, 16); ss += __shfl_xor(ss, 32);
;                 if (fq == 0) rowss[(size_t)row * 32 + u.pn * 4 + wc] = ss;
;             }
.LBB0_364:
	s_or_b64 exec, exec, s[28:29]
	v_lshlrev_b32_e32 v80, 16, v132
	v_fmac_f32_e32 v80, 0.5, v76
	v_and_b32_e32 v76, 0xffff0000, v132
	v_fmac_f32_e32 v76, 0.5, v77
	v_lshlrev_b32_e32 v77, 16, v133
	v_fmac_f32_e32 v77, 0.5, v78
	v_and_b32_e32 v78, 0xffff0000, v133
	v_fmac_f32_e32 v78, 0.5, v79
	v_lshlrev_b32_e32 v79, 16, v134
	s_waitcnt lgkmcnt(0)
	v_and_b32_e32 v81, 0xffff0000, v134
	v_fmac_f32_e32 v79, 0.5, v72
	v_fmac_f32_e32 v81, 0.5, v73
	v_and_b32_e32 v83, 0xffff0000, v135
	v_cvt_pk_bf16_f32 v72, v80, v76
	v_cvt_pk_bf16_f32 v73, v77, v78
	v_mul_f32_e32 v76, v76, v76
	v_mul_f32_e32 v78, v78, v78
	v_lshlrev_b32_e32 v82, 16, v135
	v_fmac_f32_e32 v83, 0.5, v75
	v_fmac_f32_e32 v76, v80, v80
	v_fmac_f32_e32 v78, v77, v77
	v_fmac_f32_e32 v82, 0.5, v74
	v_add_f32_e32 v76, v76, v78
	v_mul_f32_e32 v77, v81, v81
	v_mul_f32_e32 v78, v83, v83
	v_fmac_f32_e32 v77, v79, v79
	v_fmac_f32_e32 v78, v82, v82
	v_add_f32_e32 v77, v77, v78
	v_add_f32_e32 v76, v76, v77
	v_lshlrev_b32_e32 v77, 16, v128
	v_fmac_f32_e32 v77, 0.5, v68
	v_and_b32_e32 v68, 0xffff0000, v128
	v_and_b32_e32 v78, 0xffff0000, v129
	v_cvt_pk_bf16_f32 v74, v79, v81
	v_fmac_f32_e32 v68, 0.5, v69
	v_lshlrev_b32_e32 v69, 16, v129
	v_fmac_f32_e32 v78, 0.5, v71
	v_lshlrev_b32_e32 v79, 16, v130
	v_and_b32_e32 v80, 0xffff0000, v130
	v_cvt_pk_bf16_f32 v75, v82, v83
	v_fmac_f32_e32 v69, 0.5, v70
	v_fmac_f32_e32 v79, 0.5, v64
	v_fmac_f32_e32 v80, 0.5, v65
	v_and_b32_e32 v82, 0xffff0000, v131
	v_mul_f32_e32 v64, v68, v68
	v_mul_f32_e32 v65, v78, v78
	v_lshlrev_b32_e32 v81, 16, v131
	v_fmac_f32_e32 v82, 0.5, v67
	v_fmac_f32_e32 v64, v77, v77
	v_fmac_f32_e32 v65, v69, v69
	v_fmac_f32_e32 v81, 0.5, v66
	v_add_f32_e32 v64, v64, v65
	v_mul_f32_e32 v65, v80, v80
	v_mul_f32_e32 v66, v82, v82
	v_fmac_f32_e32 v65, v79, v79
	v_fmac_f32_e32 v66, v81, v81
	v_add_f32_e32 v65, v65, v66
	v_add_f32_e32 v64, v64, v65
	v_add_f32_e32 v67, v76, v64
	v_mov_b32_e32 v76, v67
	s_nop 1
	v_permlane16_swap_b32 v76, v67
	v_lshl_add_u64 v[64:65], s[20:21], 0, v[174:175]
	v_lshl_add_u64 v[70:71], v[166:167], 1, v[64:65]
	global_store_dwordx4 v[70:71], v[72:75], off
	v_cvt_pk_bf16_f32 v66, v77, v68
	s_waitcnt lgkmcnt(0)
	v_add_f32_e32 v64, v67, v76
	v_mov_b32_e32 v65, v64
	s_nop 1
	v_permlane32_swap_b32 v65, v64
	v_cvt_pk_bf16_f32 v67, v69, v78
	v_cvt_pk_bf16_f32 v68, v79, v80
	v_cvt_pk_bf16_f32 v69, v81, v82
	global_store_dwordx4 v[70:71], v[66:69], off offset:256
	s_and_saveexec_b64 s[28:29], s[6:7]
	s_cbranch_execz .LBB0_366
	s_waitcnt lgkmcnt(0)
	v_add_f32_e32 v66, v64, v65
	s_lshl_b32 s30, s40, 2
	v_lshlrev_b64 v[64:65], 7, v[172:173]
	s_ashr_i32 s31, s30, 31
	v_lshl_add_u64 v[64:65], s[2:3], 0, v[64:65]
	v_lshl_add_u64 v[64:65], s[30:31], 2, v[64:65]
	s_lshl_b32 s0, s50, 2
	v_lshl_add_u64 v[64:65], v[64:65], 0, s[0:1]
	global_store_dword v[64:65], v66, off
.LBB0_366:
	s_or_b64 exec, exec, s[28:29]
	v_add_u32_e32 v100, 0x80, v170
	v_ashrrev_i32_e32 v101, 31, v100
	v_lshlrev_b64 v[110:111], 11, v[100:101]
	s_waitcnt lgkmcnt(0)
	v_lshl_add_u64 v[64:65], v[168:169], 0, v[110:111]
	s_waitcnt vmcnt(8)
	v_mov_b64_e32 v[102:103], v[222:223]
	v_mov_b64_e32 v[104:105], v[224:225]
	v_mov_b64_e32 v[106:107], v[226:227]
	v_mov_b64_e32 v[108:109], v[228:229]
	v_add_u32_e32 v96, 0x90, v170
	v_add_u32_e32 v92, 0xa0, v170
	v_add_u32_e32 v88, 0xb0, v170
	v_ashrrev_i32_e32 v97, 31, v96
	v_ashrrev_i32_e32 v93, 31, v92
	v_ashrrev_i32_e32 v89, 31, v88
	v_lshlrev_b64 v[98:99], 11, v[96:97]
	v_lshlrev_b64 v[94:95], 11, v[92:93]
	v_lshlrev_b64 v[90:91], 11, v[88:89]
	v_lshl_add_u64 v[64:65], v[168:169], 0, v[98:99]
	v_lshl_add_u64 v[66:67], v[168:169], 0, v[94:95]
	v_lshl_add_u64 v[114:115], v[168:169], 0, v[90:91]
	v_mov_b64_e32 v[84:85], v[230:231]
	v_mov_b64_e32 v[86:87], v[232:233]
	v_mov_b64_e32 v[80:81], v[234:235]
	v_mov_b64_e32 v[82:83], v[236:237]
	v_mov_b64_e32 v[76:77], v[238:239]
	v_mov_b64_e32 v[78:79], v[240:241]
	v_mov_b64_e32 v[72:73], v[242:243]
	v_mov_b64_e32 v[74:75], v[244:245]
	v_mov_b64_e32 v[68:69], v[246:247]
	v_mov_b64_e32 v[70:71], v[248:249]
	s_nop 0
	v_mov_b64_e32 v[64:65], v[250:251]
	v_mov_b64_e32 v[66:67], v[252:253]
	v_lshlrev_b32_e32 v114, 16, v102
	v_and_b32_e32 v102, 0xffff0000, v102
	v_lshlrev_b32_e32 v115, 16, v103
	v_and_b32_e32 v103, 0xffff0000, v103
	v_lshlrev_b32_e32 v116, 16, v104
	v_and_b32_e32 v104, 0xffff0000, v104
	v_lshlrev_b32_e32 v117, 16, v105
	v_and_b32_e32 v105, 0xffff0000, v105
	v_lshlrev_b32_e32 v118, 16, v106
	v_and_b32_e32 v106, 0xffff0000, v106
	v_lshlrev_b32_e32 v119, 16, v107
	v_and_b32_e32 v107, 0xffff0000, v107
	v_lshlrev_b32_e32 v120, 16, v108
	v_and_b32_e32 v108, 0xffff0000, v108
	v_lshlrev_b32_e32 v121, 16, v109
	v_and_b32_e32 v109, 0xffff0000, v109
	v_fmac_f32_e32 v102, 0.5, v53
	v_fmac_f32_e32 v103, 0.5, v55
	v_fmac_f32_e32 v104, 0.5, v49
	v_fmac_f32_e32 v105, 0.5, v51
	v_fmac_f32_e32 v106, 0.5, v61
	v_fmac_f32_e32 v107, 0.5, v63
	v_fmac_f32_e32 v108, 0.5, v57
	v_fmac_f32_e32 v109, 0.5, v59
	v_fmac_f32_e32 v114, 0.5, v52
	v_fmac_f32_e32 v115, 0.5, v54
	v_fmac_f32_e32 v116, 0.5, v48
	v_fmac_f32_e32 v117, 0.5, v50
	v_fmac_f32_e32 v118, 0.5, v60
	v_fmac_f32_e32 v119, 0.5, v62
	v_fmac_f32_e32 v120, 0.5, v56
	v_fmac_f32_e32 v121, 0.5, v58
	v_mul_f32_e32 v52, v102, v102
	v_mul_f32_e32 v53, v103, v103
	v_mul_f32_e32 v54, v104, v104
	v_mul_f32_e32 v55, v105, v105
	v_mul_f32_e32 v56, v106, v106
	v_mul_f32_e32 v57, v107, v107
	v_mul_f32_e32 v58, v108, v108
	v_mul_f32_e32 v59, v109, v109
	v_fmac_f32_e32 v52, v114, v114
	v_fmac_f32_e32 v53, v115, v115
	v_fmac_f32_e32 v54, v116, v116
	v_fmac_f32_e32 v55, v117, v117
	v_fmac_f32_e32 v56, v118, v118
	v_fmac_f32_e32 v57, v119, v119
	v_fmac_f32_e32 v58, v120, v120
	v_fmac_f32_e32 v59, v121, v121
	v_add_f32_e32 v52, v52, v53
	v_add_f32_e32 v53, v54, v55
	v_add_f32_e32 v54, v56, v57
	v_add_f32_e32 v55, v58, v59
	v_add_f32_e32 v52, v52, v53
	v_add_f32_e32 v53, v54, v55
	v_add_f32_e32 v56, v52, v53
	v_mov_b32_e32 v57, v56
	s_nop 1
	v_permlane16_swap_b32 v57, v56
	v_lshl_add_u64 v[52:53], s[20:21], 0, v[110:111]
	v_cvt_pk_bf16_f32 v48, v114, v102
	v_lshl_add_u64 v[54:55], v[166:167], 1, v[52:53]
	v_cvt_pk_bf16_f32 v49, v115, v103
	v_cvt_pk_bf16_f32 v50, v116, v104
	v_cvt_pk_bf16_f32 v51, v117, v105
	global_store_dwordx4 v[54:55], v[48:51], off
	s_waitcnt lgkmcnt(0)
	s_nop 0
	v_add_f32_e32 v48, v56, v57
	v_mov_b32_e32 v49, v48
	s_nop 1
	v_permlane32_swap_b32 v49, v48
	v_cvt_pk_bf16_f32 v50, v118, v106
	v_cvt_pk_bf16_f32 v51, v119, v107
	v_cvt_pk_bf16_f32 v52, v120, v108
	v_cvt_pk_bf16_f32 v53, v121, v109
	global_store_dwordx4 v[54:55], v[50:53], off offset:256
	s_and_saveexec_b64 s[28:29], s[6:7]
	s_cbranch_execz .LBB0_368
	s_waitcnt lgkmcnt(0)
	v_add_f32_e32 v50, v48, v49
	s_lshl_b32 s30, s40, 2
	v_lshlrev_b64 v[48:49], 7, v[100:101]
	s_ashr_i32 s31, s30, 31
	v_lshl_add_u64 v[48:49], s[2:3], 0, v[48:49]
	v_lshl_add_u64 v[48:49], s[30:31], 2, v[48:49]
	s_lshl_b32 s0, s50, 2
	v_lshl_add_u64 v[48:49], v[48:49], 0, s[0:1]
	global_store_dword v[48:49], v50, off
; __device__ __forceinline__ unsigned pk2(float lo, float hi) { unsigned r; asm volatile("v_cvt_pk_bf16_f32 %0, %1, %2" : "=v"(r) : "v"(lo), "v"(hi)); return r; }
; __device__ __forceinline__ unsigned pk2(float lo, float hi) { return f2bf(lo) | (f2bf(hi) << 16); }
;     __device__ __forceinline__ void epi(const f32x4 (&acc)[2][2][4][2], const Unit& u, int wr, int wc, int fr, int fq) const {
;     ...
;             for (int m = 0; m < 4; ++m) {
;                 const int row = row0 + ai * 128 + m * 16; const size_t off = (size_t)row * D + col0; float ss = 0.f;
; #pragma unroll
;                 for (int bj = 0; bj < 2; ++bj) {
;                     const u32x4 o = xo[m][bj]; const f32x4 a0v = acc[ai][bj][m][0], a1v = acc[ai][bj][m][1];
;                     const float v0 = bf_lo(o.x) + coef * a0v[0], v1 = bf_hi(o.x) + coef * a0v[1], v2 = bf_lo(o.y) + coef * a0v[2], v3 = bf_hi(o.y) + coef * a0v[3];
;                     const float v4 = bf_lo(o.z) + coef * a1v[0], v5 = bf_hi(o.z) + coef * a1v[1], v6 = bf_lo(o.w) + coef * a1v[2], v7 = bf_hi(o.w) + coef * a1v[3];
;                     u32x4 w; w.x = pk2(v0, v1); w.y = pk2(v2, v3); w.z = pk2(v4, v5); w.w = pk2(v6, v7);
;                     *(u32x4*)(xb + off + bj * 128) = w;
;                     ss += ((v0 * v0 + v1 * v1) + (v2 * v2 + v3 * v3)) + ((v4 * v4 + v5 * v5) + (v6 * v6 + v7 * v7));
;                 }
;                 ss += __shfl_xor(ss, 16); ss += __shfl_xor(ss, 32);
;                 if (fq == 0) rowss[(size_t)row * 32 + u.pn * 4 + wc] = ss;
;             }
.LBB0_368:
	s_or_b64 exec, exec, s[28:29]
	v_lshlrev_b32_e32 v48, 16, v84
	v_fmac_f32_e32 v48, 0.5, v44
	v_and_b32_e32 v44, 0xffff0000, v84
	v_fmac_f32_e32 v44, 0.5, v45
	v_lshlrev_b32_e32 v45, 16, v85
	v_fmac_f32_e32 v45, 0.5, v46
	v_and_b32_e32 v46, 0xffff0000, v85
	v_fmac_f32_e32 v46, 0.5, v47
	v_lshlrev_b32_e32 v47, 16, v86
	s_waitcnt lgkmcnt(0)
	v_and_b32_e32 v49, 0xffff0000, v86
	v_fmac_f32_e32 v47, 0.5, v36
	v_fmac_f32_e32 v49, 0.5, v37
	v_and_b32_e32 v51, 0xffff0000, v87
	v_cvt_pk_bf16_f32 v36, v48, v44
	v_cvt_pk_bf16_f32 v37, v45, v46
	v_mul_f32_e32 v44, v44, v44
	v_mul_f32_e32 v46, v46, v46
	v_lshlrev_b32_e32 v50, 16, v87
	v_fmac_f32_e32 v51, 0.5, v39
	v_fmac_f32_e32 v44, v48, v48
	v_fmac_f32_e32 v46, v45, v45
	v_fmac_f32_e32 v50, 0.5, v38
	v_add_f32_e32 v44, v44, v46
	v_mul_f32_e32 v45, v49, v49
	v_mul_f32_e32 v46, v51, v51
	v_cvt_pk_bf16_f32 v38, v47, v49
	v_fmac_f32_e32 v45, v47, v47
	v_fmac_f32_e32 v46, v50, v50
	v_lshlrev_b32_e32 v47, 16, v81
	v_add_f32_e32 v45, v45, v46
	v_and_b32_e32 v46, 0xffff0000, v80
	v_fmac_f32_e32 v47, 0.5, v42
	v_and_b32_e32 v42, 0xffff0000, v81
	v_add_f32_e32 v44, v44, v45
	v_lshlrev_b32_e32 v45, 16, v80
	v_fmac_f32_e32 v46, 0.5, v41
	v_fmac_f32_e32 v42, 0.5, v43
	v_lshlrev_b32_e32 v43, 16, v82
	v_and_b32_e32 v48, 0xffff0000, v82
	v_cvt_pk_bf16_f32 v39, v50, v51
	v_fmac_f32_e32 v45, 0.5, v40
	v_fmac_f32_e32 v43, 0.5, v32
	v_fmac_f32_e32 v48, 0.5, v33
	v_and_b32_e32 v50, 0xffff0000, v83
	v_mul_f32_e32 v32, v46, v46
	v_mul_f32_e32 v33, v42, v42
	v_lshlrev_b32_e32 v49, 16, v83
	v_fmac_f32_e32 v50, 0.5, v35
	v_fmac_f32_e32 v32, v45, v45
	v_fmac_f32_e32 v33, v47, v47
	v_fmac_f32_e32 v49, 0.5, v34
	v_add_f32_e32 v32, v32, v33
	v_mul_f32_e32 v33, v48, v48
	v_mul_f32_e32 v34, v50, v50
	v_fmac_f32_e32 v33, v43, v43
	v_fmac_f32_e32 v34, v49, v49
	v_add_f32_e32 v33, v33, v34
	v_add_f32_e32 v32, v32, v33
	v_add_f32_e32 v35, v44, v32
	v_mov_b32_e32 v44, v35
	s_nop 1
	v_permlane16_swap_b32 v44, v35
	v_lshl_add_u64 v[32:33], s[20:21], 0, v[98:99]
	v_lshl_add_u64 v[40:41], v[166:167], 1, v[32:33]
	global_store_dwordx4 v[40:41], v[36:39], off
	v_cvt_pk_bf16_f32 v34, v45, v46
	s_waitcnt lgkmcnt(0)
	v_add_f32_e32 v32, v35, v44
	v_mov_b32_e32 v33, v32
	s_nop 1
	v_permlane32_swap_b32 v33, v32
	v_cvt_pk_bf16_f32 v35, v47, v42
	v_cvt_pk_bf16_f32 v36, v43, v48
	v_cvt_pk_bf16_f32 v37, v49, v50
	global_store_dwordx4 v[40:41], v[34:37], off offset:256
	s_and_saveexec_b64 s[28:29], s[6:7]
	s_cbranch_execz .LBB0_370
	s_waitcnt lgkmcnt(0)
	v_add_f32_e32 v34, v32, v33
	s_lshl_b32 s30, s40, 2
	v_lshlrev_b64 v[32:33], 7, v[96:97]
	s_ashr_i32 s31, s30, 31
	v_lshl_add_u64 v[32:33], s[2:3], 0, v[32:33]
	v_lshl_add_u64 v[32:33], s[30:31], 2, v[32:33]
	s_lshl_b32 s0, s50, 2
	v_lshl_add_u64 v[32:33], v[32:33], 0, s[0:1]
	global_store_dword v[32:33], v34, off
; __device__ __forceinline__ unsigned pk2(float lo, float hi) { unsigned r; asm volatile("v_cvt_pk_bf16_f32 %0, %1, %2" : "=v"(r) : "v"(lo), "v"(hi)); return r; }
; __device__ __forceinline__ unsigned pk2(float lo, float hi) { return f2bf(lo) | (f2bf(hi) << 16); }
;     __device__ __forceinline__ void epi(const f32x4 (&acc)[2][2][4][2], const Unit& u, int wr, int wc, int fr, int fq) const {
;     ...
;             for (int m = 0; m < 4; ++m) {
;                 const int row = row0 + ai * 128 + m * 16; const size_t off = (size_t)row * D + col0; float ss = 0.f;
; #pragma unroll
;                 for (int bj = 0; bj < 2; ++bj) {
;                     const u32x4 o = xo[m][bj]; const f32x4 a0v = acc[ai][bj][m][0], a1v = acc[ai][bj][m][1];
;                     const float v0 = bf_lo(o.x) + coef * a0v[0], v1 = bf_hi(o.x) + coef * a0v[1], v2 = bf_lo(o.y) + coef * a0v[2], v3 = bf_hi(o.y) + coef * a0v[3];
;                     const float v4 = bf_lo(o.z) + coef * a1v[0], v5 = bf_hi(o.z) + coef * a1v[1], v6 = bf_lo(o.w) + coef * a1v[2], v7 = bf_hi(o.w) + coef * a1v[3];
;                     u32x4 w; w.x = pk2(v0, v1); w.y = pk2(v2, v3); w.z = pk2(v4, v5); w.w = pk2(v6, v7);
;                     *(u32x4*)(xb + off + bj * 128) = w;
;                     ss += ((v0 * v0 + v1 * v1) + (v2 * v2 + v3 * v3)) + ((v4 * v4 + v5 * v5) + (v6 * v6 + v7 * v7));
;                 }
;                 ss += __shfl_xor(ss, 16); ss += __shfl_xor(ss, 32);
;                 if (fq == 0) rowss[(size_t)row * 32 + u.pn * 4 + wc] = ss;
;             }
.LBB0_370:
	s_or_b64 exec, exec, s[28:29]
	v_lshlrev_b32_e32 v32, 16, v76
	v_fmac_f32_e32 v32, 0.5, v28
	v_and_b32_e32 v28, 0xffff0000, v76
	v_fmac_f32_e32 v28, 0.5, v29
	v_lshlrev_b32_e32 v29, 16, v77
	v_fmac_f32_e32 v29, 0.5, v30
	v_and_b32_e32 v30, 0xffff0000, v77
	v_fmac_f32_e32 v30, 0.5, v31
	v_lshlrev_b32_e32 v31, 16, v78
	s_waitcnt lgkmcnt(0)
	v_and_b32_e32 v33, 0xffff0000, v78
	v_fmac_f32_e32 v31, 0.5, v20
	v_fmac_f32_e32 v33, 0.5, v21
	v_and_b32_e32 v35, 0xffff0000, v79
	v_cvt_pk_bf16_f32 v20, v32, v28
	v_cvt_pk_bf16_f32 v21, v29, v30
	v_mul_f32_e32 v28, v28, v28
	v_mul_f32_e32 v30, v30, v30
	v_lshlrev_b32_e32 v34, 16, v79
	v_fmac_f32_e32 v35, 0.5, v23
	v_fmac_f32_e32 v28, v32, v32
	v_fmac_f32_e32 v30, v29, v29
	v_fmac_f32_e32 v34, 0.5, v22
	v_add_f32_e32 v28, v28, v30
	v_mul_f32_e32 v29, v33, v33
	v_mul_f32_e32 v30, v35, v35
	v_cvt_pk_bf16_f32 v22, v31, v33
	v_fmac_f32_e32 v29, v31, v31
	v_fmac_f32_e32 v30, v34, v34
	v_lshlrev_b32_e32 v31, 16, v73
	v_add_f32_e32 v29, v29, v30
	v_and_b32_e32 v30, 0xffff0000, v72
	v_fmac_f32_e32 v31, 0.5, v26
	v_and_b32_e32 v26, 0xffff0000, v73
	v_add_f32_e32 v28, v28, v29
	v_lshlrev_b32_e32 v29, 16, v72
	v_fmac_f32_e32 v30, 0.5, v25
	v_fmac_f32_e32 v26, 0.5, v27
	v_lshlrev_b32_e32 v27, 16, v74
	v_and_b32_e32 v32, 0xffff0000, v74
	v_cvt_pk_bf16_f32 v23, v34, v35
	v_fmac_f32_e32 v29, 0.5, v24
	v_fmac_f32_e32 v27, 0.5, v16
	v_fmac_f32_e32 v32, 0.5, v17
	v_and_b32_e32 v34, 0xffff0000, v75
	v_mul_f32_e32 v16, v30, v30
	v_mul_f32_e32 v17, v26, v26
	v_lshlrev_b32_e32 v33, 16, v75
	v_fmac_f32_e32 v34, 0.5, v19
	v_fmac_f32_e32 v16, v29, v29
	v_fmac_f32_e32 v17, v31, v31
	v_fmac_f32_e32 v33, 0.5, v18
	v_add_f32_e32 v16, v16, v17
	v_mul_f32_e32 v17, v32, v32
	v_mul_f32_e32 v18, v34, v34
	v_fmac_f32_e32 v17, v27, v27
	v_fmac_f32_e32 v18, v33, v33
	v_add_f32_e32 v17, v17, v18
	v_add_f32_e32 v16, v16, v17
	v_add_f32_e32 v19, v28, v16
	v_mov_b32_e32 v28, v19
	s_nop 1
	v_permlane16_swap_b32 v28, v19
	v_lshl_add_u64 v[16:17], s[20:21], 0, v[94:95]
	v_lshl_add_u64 v[24:25], v[166:167], 1, v[16:17]
	global_store_dwordx4 v[24:25], v[20:23], off
	v_cvt_pk_bf16_f32 v18, v29, v30
	s_waitcnt lgkmcnt(0)
	v_add_f32_e32 v16, v19, v28
	v_mov_b32_e32 v17, v16
	s_nop 1
	v_permlane32_swap_b32 v17, v16
	v_cvt_pk_bf16_f32 v19, v31, v26
	v_cvt_pk_bf16_f32 v20, v27, v32
	v_cvt_pk_bf16_f32 v21, v33, v34
	global_store_dwordx4 v[24:25], v[18:21], off offset:256
	s_and_saveexec_b64 s[28:29], s[6:7]
	s_cbranch_execz .LBB0_372
	s_waitcnt lgkmcnt(0)
	v_add_f32_e32 v18, v16, v17
	s_lshl_b32 s30, s40, 2
	v_lshlrev_b64 v[16:17], 7, v[92:93]
	s_ashr_i32 s31, s30, 31
	v_lshl_add_u64 v[16:17], s[2:3], 0, v[16:17]
	v_lshl_add_u64 v[16:17], s[30:31], 2, v[16:17]
	s_lshl_b32 s0, s50, 2
	v_lshl_add_u64 v[16:17], v[16:17], 0, s[0:1]
	global_store_dword v[16:17], v18, off
.LBB0_372:
	s_or_b64 exec, exec, s[28:29]
	v_lshlrev_b32_e32 v16, 16, v68
	v_fmac_f32_e32 v16, 0.5, v12
	v_and_b32_e32 v12, 0xffff0000, v68
	v_fmac_f32_e32 v12, 0.5, v13
	v_lshlrev_b32_e32 v13, 16, v69
	v_fmac_f32_e32 v13, 0.5, v14
	v_and_b32_e32 v14, 0xffff0000, v69
	v_fmac_f32_e32 v14, 0.5, v15
	v_lshlrev_b32_e32 v15, 16, v70
	s_waitcnt lgkmcnt(0)
	v_and_b32_e32 v17, 0xffff0000, v70
	v_fmac_f32_e32 v15, 0.5, v4
	v_fmac_f32_e32 v17, 0.5, v5
	v_and_b32_e32 v19, 0xffff0000, v71
	v_cvt_pk_bf16_f32 v4, v16, v12
	v_cvt_pk_bf16_f32 v5, v13, v14
	v_mul_f32_e32 v12, v12, v12
	v_mul_f32_e32 v14, v14, v14
	v_lshlrev_b32_e32 v18, 16, v71
	v_fmac_f32_e32 v19, 0.5, v7
	v_fmac_f32_e32 v12, v16, v16
	v_fmac_f32_e32 v14, v13, v13
	v_fmac_f32_e32 v18, 0.5, v6
	v_add_f32_e32 v12, v12, v14
	v_mul_f32_e32 v13, v17, v17
	v_mul_f32_e32 v14, v19, v19
	v_cvt_pk_bf16_f32 v6, v15, v17
	v_fmac_f32_e32 v13, v15, v15
	v_fmac_f32_e32 v14, v18, v18
	v_lshlrev_b32_e32 v15, 16, v65
	v_add_f32_e32 v13, v13, v14
	v_and_b32_e32 v14, 0xffff0000, v64
	v_fmac_f32_e32 v15, 0.5, v10
	v_and_b32_e32 v10, 0xffff0000, v65
	v_add_f32_e32 v12, v12, v13
	v_lshlrev_b32_e32 v13, 16, v64
	v_fmac_f32_e32 v14, 0.5, v9
	v_fmac_f32_e32 v10, 0.5, v11
	v_lshlrev_b32_e32 v11, 16, v66
	v_and_b32_e32 v16, 0xffff0000, v66
	v_cvt_pk_bf16_f32 v7, v18, v19
	v_fmac_f32_e32 v13, 0.5, v8
	v_fmac_f32_e32 v11, 0.5, v0
	v_fmac_f32_e32 v16, 0.5, v1
	v_and_b32_e32 v18, 0xffff0000, v67
	v_mul_f32_e32 v0, v14, v14
	v_mul_f32_e32 v1, v10, v10
	v_lshlrev_b32_e32 v17, 16, v67
	v_fmac_f32_e32 v18, 0.5, v3
	v_fmac_f32_e32 v0, v13, v13
	v_fmac_f32_e32 v1, v15, v15
	v_fmac_f32_e32 v17, 0.5, v2
	v_add_f32_e32 v0, v0, v1
	v_mul_f32_e32 v1, v16, v16
	v_mul_f32_e32 v2, v18, v18
	v_fmac_f32_e32 v1, v11, v11
	v_fmac_f32_e32 v2, v17, v17
	v_add_f32_e32 v1, v1, v2
	v_add_f32_e32 v0, v0, v1
	v_add_f32_e32 v3, v12, v0
	v_mov_b32_e32 v12, v3
	s_nop 1
	v_permlane16_swap_b32 v12, v3
	v_lshl_add_u64 v[0:1], s[20:21], 0, v[90:91]
	v_lshl_add_u64 v[8:9], v[166:167], 1, v[0:1]
	global_store_dwordx4 v[8:9], v[4:7], off
	v_cvt_pk_bf16_f32 v2, v13, v14
	s_waitcnt lgkmcnt(0)
	v_add_f32_e32 v0, v3, v12
	v_mov_b32_e32 v1, v0
	s_nop 1
	v_permlane32_swap_b32 v1, v0
	v_cvt_pk_bf16_f32 v3, v15, v10
	v_cvt_pk_bf16_f32 v4, v11, v16
	v_cvt_pk_bf16_f32 v5, v17, v18
	global_store_dwordx4 v[8:9], v[2:5], off offset:256
	s_and_saveexec_b64 s[28:29], s[6:7]
	s_cbranch_execz .LBB0_349
	s_waitcnt lgkmcnt(0)
	v_add_f32_e32 v2, v0, v1
	s_lshl_b32 s30, s40, 2
	v_lshlrev_b64 v[0:1], 7, v[88:89]
	s_ashr_i32 s31, s30, 31
	v_lshl_add_u64 v[0:1], s[2:3], 0, v[0:1]
	v_lshl_add_u64 v[0:1], s[30:31], 2, v[0:1]
	s_lshl_b32 s0, s50, 2
	v_lshl_add_u64 v[0:1], v[0:1], 0, s[0:1]
	global_store_dword v[0:1], v2, off
	s_branch .LBB0_349

.LBB0_920:
	ds_read_b128 v[132:135], v172
	ds_read_b128 v[136:139], v172 offset:1024
	ds_read_b128 v[152:155], v172 offset:2048
	ds_read_b128 v[156:159], v172 offset:3072
	s_mov_b32 m0, s48
	v_lshl_add_u64 v[168:169], v[120:121], 0, s[30:31]
	ds_read_b128 v[160:163], v173
	ds_read_b128 v[164:167], v173 offset:1024
	ds_read_b128 v[178:181], v173 offset:2048
	ds_read_b128 v[182:185], v173 offset:3072
	ds_read_b128 v[186:189], v173 offset:4096
	ds_read_b128 v[190:193], v173 offset:5120
	ds_read_b128 v[194:197], v173 offset:6144
	ds_read_b128 v[198:201], v173 offset:7168
	global_load_lds_dwordx4 v[168:169], off
	s_mov_b32 m0, s49
	v_lshl_add_u64 v[168:169], v[122:123], 0, s[30:31]
	global_load_lds_dwordx4 v[168:169], off
	s_waitcnt lgkmcnt(8)
	s_barrier
	s_waitcnt lgkmcnt(0)
	v_mfma_f32_16x16x32_bf16 v[116:119], v[132:135], v[160:163], v[116:119]
	s_add_i32 s19, s30, 0xfffc0080
	v_mfma_f32_16x16x32_bf16 v[112:115], v[152:155], v[160:163], v[112:115]
	s_cmp_eq_u32 s17, 12
	v_mfma_f32_16x16x32_bf16 v[100:103], v[132:135], v[178:181], v[100:103]
	s_cselect_b64 s[34:35], -1, 0
	v_mfma_f32_16x16x32_bf16 v[96:99], v[152:155], v[178:181], v[96:99]
	s_and_b64 s[60:61], s[34:35], exec
	v_mfma_f32_16x16x32_bf16 v[84:87], v[132:135], v[186:189], v[84:87]
	s_cselect_b32 s19, 0, s19
	v_mfma_f32_16x16x32_bf16 v[80:83], v[152:155], v[186:189], v[80:83]
	s_and_b64 s[34:35], s[28:29], s[34:35]
	v_mfma_f32_16x16x32_bf16 v[68:71], v[132:135], v[194:197], v[68:71]
	s_and_b64 s[34:35], s[34:35], exec
	v_mfma_f32_16x16x32_bf16 v[64:67], v[152:155], v[194:197], v[64:67]
	s_cselect_b32 s61, s21, s25
	v_mfma_f32_16x16x32_bf16 v[116:119], v[136:139], v[164:167], v[116:119]
	s_cselect_b32 s60, s20, s24
	v_mfma_f32_16x16x32_bf16 v[112:115], v[156:159], v[164:167], v[112:115]
	s_cselect_b32 s35, s23, s27
	v_mfma_f32_16x16x32_bf16 v[100:103], v[136:139], v[182:185], v[100:103]
	s_cselect_b32 s34, s22, s26
	v_mfma_f32_16x16x32_bf16 v[96:99], v[156:159], v[182:185], v[96:99]
	v_mfma_f32_16x16x32_bf16 v[84:87], v[136:139], v[190:193], v[84:87]
	v_mfma_f32_16x16x32_bf16 v[80:83], v[156:159], v[190:193], v[80:83]
	v_mfma_f32_16x16x32_bf16 v[68:71], v[136:139], v[198:201], v[68:71]
	v_mfma_f32_16x16x32_bf16 v[64:67], v[156:159], v[198:201], v[64:67]
	s_barrier
	s_add_u32 s34, s34, s19
	s_addc_u32 s35, s35, 0
	s_mov_b32 m0, s50
	v_lshl_add_u64 v[168:169], s[34:35], 0, v[144:145]
	ds_read_b128 v[202:205], v174
	ds_read_b128 v[206:209], v174 offset:1024
	ds_read_b128 v[210:213], v174 offset:2048
	ds_read_b128 v[214:217], v174 offset:3072
	global_load_lds_dwordx4 v[168:169], off
	s_mov_b32 m0, s51
	v_lshl_add_u64 v[218:219], s[34:35], 0, v[140:141]
	global_load_lds_dwordx4 v[218:219], off
	s_barrier
	s_waitcnt lgkmcnt(0)
	v_mfma_f32_16x16x32_bf16 v[128:131], v[202:205], v[160:163], v[128:131]
	v_mfma_f32_16x16x32_bf16 v[124:127], v[210:213], v[160:163], v[124:127]
	v_mfma_f32_16x16x32_bf16 v[108:111], v[202:205], v[178:181], v[108:111]
	v_mfma_f32_16x16x32_bf16 v[104:107], v[210:213], v[178:181], v[104:107]
	v_mfma_f32_16x16x32_bf16 v[92:95], v[202:205], v[186:189], v[92:95]
	v_mfma_f32_16x16x32_bf16 v[88:91], v[210:213], v[186:189], v[88:91]
	v_mfma_f32_16x16x32_bf16 v[76:79], v[202:205], v[194:197], v[76:79]
	v_mfma_f32_16x16x32_bf16 v[72:75], v[210:213], v[194:197], v[72:75]
	v_mfma_f32_16x16x32_bf16 v[128:131], v[206:209], v[164:167], v[128:131]
	v_mfma_f32_16x16x32_bf16 v[124:127], v[214:217], v[164:167], v[124:127]
	v_mfma_f32_16x16x32_bf16 v[108:111], v[206:209], v[182:185], v[108:111]
	v_mfma_f32_16x16x32_bf16 v[104:107], v[214:217], v[182:185], v[104:107]
	v_mfma_f32_16x16x32_bf16 v[92:95], v[206:209], v[190:193], v[92:95]
	v_mfma_f32_16x16x32_bf16 v[88:91], v[214:217], v[190:193], v[88:91]
	v_mfma_f32_16x16x32_bf16 v[76:79], v[206:209], v[198:201], v[76:79]
	v_mfma_f32_16x16x32_bf16 v[72:75], v[214:217], v[198:201], v[72:75]
	s_add_u32 s60, s60, s19
	s_addc_u32 s61, s61, 0
	s_mov_b32 m0, s41
	v_lshl_add_u64 v[222:223], s[60:61], 0, v[146:147]
	s_barrier
	ds_read_b128 v[160:163], v173 offset:16384
	ds_read_b128 v[164:167], v173 offset:17408
	ds_read_b128 v[178:181], v173 offset:18432
	ds_read_b128 v[182:185], v173 offset:19456
	ds_read_b128 v[186:189], v173 offset:20480
	ds_read_b128 v[190:193], v173 offset:21504
	ds_read_b128 v[194:197], v173 offset:22528
	ds_read_b128 v[198:201], v173 offset:23552
	global_load_lds_dwordx4 v[222:223], off
	s_mov_b32 m0, s42
	v_lshl_add_u64 v[224:225], s[60:61], 0, v[142:143]
	global_load_lds_dwordx4 v[224:225], off
	s_barrier
	s_waitcnt lgkmcnt(0)
	v_mfma_f32_16x16x32_bf16 v[52:55], v[132:135], v[160:163], v[52:55]
	v_mfma_f32_16x16x32_bf16 v[48:51], v[152:155], v[160:163], v[48:51]
	v_mfma_f32_16x16x32_bf16 v[36:39], v[132:135], v[178:181], v[36:39]
	v_mfma_f32_16x16x32_bf16 v[32:35], v[152:155], v[178:181], v[32:35]
	v_mfma_f32_16x16x32_bf16 v[20:23], v[132:135], v[186:189], v[20:23]
	v_mfma_f32_16x16x32_bf16 v[16:19], v[152:155], v[186:189], v[16:19]
	v_mfma_f32_16x16x32_bf16 v[4:7], v[132:135], v[194:197], v[4:7]
	v_mfma_f32_16x16x32_bf16 v[0:3], v[152:155], v[194:197], v[0:3]
	v_mfma_f32_16x16x32_bf16 v[52:55], v[136:139], v[164:167], v[52:55]
	v_mfma_f32_16x16x32_bf16 v[48:51], v[156:159], v[164:167], v[48:51]
	v_mfma_f32_16x16x32_bf16 v[36:39], v[136:139], v[182:185], v[36:39]
	v_mfma_f32_16x16x32_bf16 v[32:35], v[156:159], v[182:185], v[32:35]
	v_mfma_f32_16x16x32_bf16 v[20:23], v[136:139], v[190:193], v[20:23]
	v_mfma_f32_16x16x32_bf16 v[16:19], v[156:159], v[190:193], v[16:19]
	v_mfma_f32_16x16x32_bf16 v[4:7], v[136:139], v[198:201], v[4:7]
	v_mfma_f32_16x16x32_bf16 v[0:3], v[156:159], v[198:201], v[0:3]
	s_barrier
	s_add_u32 s62, s34, 0x40000
	s_addc_u32 s63, s35, 0
	s_mov_b32 m0, s52
	v_lshl_add_u64 v[132:133], s[62:63], 0, v[144:145]
	global_load_lds_dwordx4 v[132:133], off
	s_mov_b32 m0, s53
	v_lshl_add_u64 v[132:133], s[62:63], 0, v[140:141]
	global_load_lds_dwordx4 v[132:133], off
	s_waitcnt vmcnt(6)
	s_barrier
	v_mfma_f32_16x16x32_bf16 v[60:63], v[202:205], v[160:163], v[60:63]
	v_mfma_f32_16x16x32_bf16 v[56:59], v[210:213], v[160:163], v[56:59]
	v_mfma_f32_16x16x32_bf16 v[44:47], v[202:205], v[178:181], v[44:47]
	v_mfma_f32_16x16x32_bf16 v[40:43], v[210:213], v[178:181], v[40:43]
	v_mfma_f32_16x16x32_bf16 v[28:31], v[202:205], v[186:189], v[28:31]
	v_mfma_f32_16x16x32_bf16 v[24:27], v[210:213], v[186:189], v[24:27]
	v_mfma_f32_16x16x32_bf16 v[12:15], v[202:205], v[194:197], v[12:15]
	v_mfma_f32_16x16x32_bf16 v[8:11], v[210:213], v[194:197], v[8:11]
	v_mfma_f32_16x16x32_bf16 v[60:63], v[206:209], v[164:167], v[60:63]
	v_mfma_f32_16x16x32_bf16 v[56:59], v[214:217], v[164:167], v[56:59]
	v_mfma_f32_16x16x32_bf16 v[44:47], v[206:209], v[182:185], v[44:47]
	v_mfma_f32_16x16x32_bf16 v[40:43], v[214:217], v[182:185], v[40:43]
	v_mfma_f32_16x16x32_bf16 v[28:31], v[206:209], v[190:193], v[28:31]
	v_mfma_f32_16x16x32_bf16 v[24:27], v[214:217], v[190:193], v[24:27]
	v_mfma_f32_16x16x32_bf16 v[12:15], v[206:209], v[198:201], v[12:15]
	v_mfma_f32_16x16x32_bf16 v[8:11], v[214:217], v[198:201], v[8:11]
	s_barrier
	ds_read_b128 v[132:135], v176
	ds_read_b128 v[136:139], v176 offset:1024
	ds_read_b128 v[152:155], v176 offset:2048
	ds_read_b128 v[156:159], v176 offset:3072
	s_add_u32 s60, s60, 0x40000
	s_addc_u32 s61, s61, 0
	s_mov_b32 m0, s43
	v_lshl_add_u64 v[202:203], s[60:61], 0, v[146:147]
	ds_read_b128 v[160:163], v173 offset:32768
	ds_read_b128 v[164:167], v173 offset:33792
	ds_read_b128 v[178:181], v173 offset:34816
	ds_read_b128 v[182:185], v173 offset:35840
	ds_read_b128 v[186:189], v173 offset:36864
	ds_read_b128 v[190:193], v173 offset:37888
	ds_read_b128 v[194:197], v173 offset:38912
	ds_read_b128 v[198:201], v173 offset:39936
	global_load_lds_dwordx4 v[202:203], off
	s_mov_b32 m0, s44
	v_lshl_add_u64 v[202:203], s[60:61], 0, v[142:143]
	global_load_lds_dwordx4 v[202:203], off
	s_waitcnt lgkmcnt(8)
	s_barrier
	s_waitcnt lgkmcnt(0)
	v_mfma_f32_16x16x32_bf16 v[116:119], v[132:135], v[160:163], v[116:119]
	v_mfma_f32_16x16x32_bf16 v[112:115], v[152:155], v[160:163], v[112:115]
	v_mfma_f32_16x16x32_bf16 v[100:103], v[132:135], v[178:181], v[100:103]
	v_mfma_f32_16x16x32_bf16 v[96:99], v[152:155], v[178:181], v[96:99]
	v_mfma_f32_16x16x32_bf16 v[84:87], v[132:135], v[186:189], v[84:87]
	v_mfma_f32_16x16x32_bf16 v[80:83], v[152:155], v[186:189], v[80:83]
	v_mfma_f32_16x16x32_bf16 v[68:71], v[132:135], v[194:197], v[68:71]
	v_mfma_f32_16x16x32_bf16 v[64:67], v[152:155], v[194:197], v[64:67]
	v_mfma_f32_16x16x32_bf16 v[116:119], v[136:139], v[164:167], v[116:119]
	v_mfma_f32_16x16x32_bf16 v[112:115], v[156:159], v[164:167], v[112:115]
	v_mfma_f32_16x16x32_bf16 v[100:103], v[136:139], v[182:185], v[100:103]
	v_mfma_f32_16x16x32_bf16 v[96:99], v[156:159], v[182:185], v[96:99]
	v_mfma_f32_16x16x32_bf16 v[84:87], v[136:139], v[190:193], v[84:87]
	v_mfma_f32_16x16x32_bf16 v[80:83], v[156:159], v[190:193], v[80:83]
	v_mfma_f32_16x16x32_bf16 v[68:71], v[136:139], v[198:201], v[68:71]
	v_mfma_f32_16x16x32_bf16 v[64:67], v[156:159], v[198:201], v[64:67]
	s_barrier
	s_mov_b32 m0, s54
	v_lshl_add_u64 v[168:169], v[168:169], 0, s[6:7]
	ds_read_b128 v[202:205], v177
	ds_read_b128 v[206:209], v177 offset:1024
	ds_read_b128 v[210:213], v177 offset:2048
	ds_read_b128 v[214:217], v177 offset:3072
	global_load_lds_dwordx4 v[168:169], off
	s_mov_b32 m0, s55
	v_lshl_add_u64 v[168:169], v[218:219], 0, s[6:7]
	global_load_lds_dwordx4 v[168:169], off
	s_barrier
	s_waitcnt lgkmcnt(0)
	v_mfma_f32_16x16x32_bf16 v[128:131], v[202:205], v[160:163], v[128:131]
	v_mfma_f32_16x16x32_bf16 v[124:127], v[210:213], v[160:163], v[124:127]
	v_mfma_f32_16x16x32_bf16 v[108:111], v[202:205], v[178:181], v[108:111]
	v_mfma_f32_16x16x32_bf16 v[104:107], v[210:213], v[178:181], v[104:107]
	v_mfma_f32_16x16x32_bf16 v[92:95], v[202:205], v[186:189], v[92:95]
	v_mfma_f32_16x16x32_bf16 v[88:91], v[210:213], v[186:189], v[88:91]
	v_mfma_f32_16x16x32_bf16 v[76:79], v[202:205], v[194:197], v[76:79]
	v_mfma_f32_16x16x32_bf16 v[72:75], v[210:213], v[194:197], v[72:75]
	v_mfma_f32_16x16x32_bf16 v[128:131], v[206:209], v[164:167], v[128:131]
	v_mfma_f32_16x16x32_bf16 v[124:127], v[214:217], v[164:167], v[124:127]
	v_mfma_f32_16x16x32_bf16 v[108:111], v[206:209], v[182:185], v[108:111]
	v_mfma_f32_16x16x32_bf16 v[104:107], v[214:217], v[182:185], v[104:107]
	v_mfma_f32_16x16x32_bf16 v[92:95], v[206:209], v[190:193], v[92:95]
	v_mfma_f32_16x16x32_bf16 v[88:91], v[214:217], v[190:193], v[88:91]
	v_mfma_f32_16x16x32_bf16 v[76:79], v[206:209], v[198:201], v[76:79]
	v_mfma_f32_16x16x32_bf16 v[72:75], v[214:217], v[198:201], v[72:75]
	s_mov_b32 m0, s46
	v_lshl_add_u64 v[168:169], v[222:223], 0, s[6:7]
	s_barrier
	ds_read_b128 v[160:163], v173 offset:49152
	ds_read_b128 v[164:167], v173 offset:50176
	ds_read_b128 v[178:181], v173 offset:51200
	ds_read_b128 v[182:185], v173 offset:52224
	ds_read_b128 v[186:189], v173 offset:53248
	ds_read_b128 v[190:193], v173 offset:54272
	ds_read_b128 v[194:197], v173 offset:55296
	ds_read_b128 v[198:201], v173 offset:56320
	global_load_lds_dwordx4 v[168:169], off
	s_mov_b32 m0, s47
	v_lshl_add_u64 v[168:169], v[224:225], 0, s[6:7]
	global_load_lds_dwordx4 v[168:169], off
	s_barrier
; __device__ __forceinline__ unsigned pk2(float lo, float hi) { unsigned r; asm volatile("v_cvt_pk_bf16_f32 %0, %1, %2" : "=v"(r) : "v"(lo), "v"(hi)); return r; }
; __device__ __forceinline__ unsigned pk2(float lo, float hi) { return f2bf(lo) | (f2bf(hi) << 16); }
; __device__ __forceinline__ float fast_sigmoid(float z) { return __builtin_amdgcn_rcpf(1.0f + __expf(-z)); }
;     ...
;         G_PAIR(0, 1);
; #pragma unroll 1
;         for (int t = 2; t < nt; t += 2) G_PAIR(t, 0);
;     __device__ __forceinline__ void epi(const f32x4 (&acc)[2][2][4][2], const Unit& u, int wr, int wc, int fr, int fq) const {
;     ...
;         for (int ai = 0; ai < 2; ++ai) {
;             u32x4 xo[4];
; #pragma unroll
;             for (int m = 0; m < 4; ++m) xo[m] = *(const u32x4*)(xb + (size_t)(row0 + ai * 128 + m * 16) * D + col0);
; #pragma unroll
;             for (int m = 0; m < 4; ++m) {
;                 const int row = row0 + ai * 128 + m * 16; const size_t off = (size_t)row * D + col0;
;                 const u32x4 o = xo[m]; const f32x4 a0v = acc[ai][0][m][0], a1v = acc[ai][0][m][1], b0v = acc[ai][1][m][0], b1v = acc[ai][1][m][1];
;                 const float v0 = bf_lo(o.x) + coef * a0v[0] * fast_sigmoid(b0v[0]), v1 = bf_hi(o.x) + coef * a0v[1] * fast_sigmoid(b0v[1]);
;                 const float v2 = bf_lo(o.y) + coef * a0v[2] * fast_sigmoid(b0v[2]), v3 = bf_hi(o.y) + coef * a0v[3] * fast_sigmoid(b0v[3]);
;                 const float v4 = bf_lo(o.z) + coef * a1v[0] * fast_sigmoid(b1v[0]), v5 = bf_hi(o.z) + coef * a1v[1] * fast_sigmoid(b1v[1]);
;                 const float v6 = bf_lo(o.w) + coef * a1v[2] * fast_sigmoid(b1v[2]), v7 = bf_hi(o.w) + coef * a1v[3] * fast_sigmoid(b1v[3]);
;                 u32x4 w; w.x = pk2(v0, v1); w.y = pk2(v2, v3); w.z = pk2(v4, v5); w.w = pk2(v6, v7);
;                 *(u32x4*)(xb + off) = w;
;                 float ss = ((v0 * v0 + v1 * v1) + (v2 * v2 + v3 * v3)) + ((v4 * v4 + v5 * v5) + (v6 * v6 + v7 * v7));
;                 ss += __shfl_xor(ss, 16); ss += __shfl_xor(ss, 32);
;                 if (fq == 0) rowss[(size_t)row * 32 + u.pn * 4 + wc] = ss;
	s_waitcnt lgkmcnt(0)
	v_mfma_f32_16x16x32_bf16 v[52:55], v[132:135], v[160:163], v[52:55]
	v_mfma_f32_16x16x32_bf16 v[48:51], v[152:155], v[160:163], v[48:51]
	v_mfma_f32_16x16x32_bf16 v[36:39], v[132:135], v[178:181], v[36:39]
	v_mfma_f32_16x16x32_bf16 v[32:35], v[152:155], v[178:181], v[32:35]
	v_mfma_f32_16x16x32_bf16 v[20:23], v[132:135], v[186:189], v[20:23]
	v_mfma_f32_16x16x32_bf16 v[16:19], v[152:155], v[186:189], v[16:19]
	v_mfma_f32_16x16x32_bf16 v[4:7], v[132:135], v[194:197], v[4:7]
	v_mfma_f32_16x16x32_bf16 v[0:3], v[152:155], v[194:197], v[0:3]
	v_mfma_f32_16x16x32_bf16 v[52:55], v[136:139], v[164:167], v[52:55]
	v_mfma_f32_16x16x32_bf16 v[48:51], v[156:159], v[164:167], v[48:51]
	v_mfma_f32_16x16x32_bf16 v[36:39], v[136:139], v[182:185], v[36:39]
	v_mfma_f32_16x16x32_bf16 v[32:35], v[156:159], v[182:185], v[32:35]
	v_mfma_f32_16x16x32_bf16 v[20:23], v[136:139], v[190:193], v[20:23]
	v_mfma_f32_16x16x32_bf16 v[16:19], v[156:159], v[190:193], v[16:19]
	v_mfma_f32_16x16x32_bf16 v[4:7], v[136:139], v[198:201], v[4:7]
	v_mfma_f32_16x16x32_bf16 v[0:3], v[156:159], v[198:201], v[0:3]
	s_barrier
	s_add_u32 s34, s34, 0x40080
	s_addc_u32 s35, s35, 0
	s_mov_b32 m0, s56
	v_lshl_add_u64 v[132:133], s[34:35], 0, v[144:145]
	global_load_lds_dwordx4 v[132:133], off
	s_mov_b32 m0, s57
	v_lshl_add_u64 v[132:133], s[34:35], 0, v[140:141]
	global_load_lds_dwordx4 v[132:133], off
	s_waitcnt vmcnt(6)
	s_barrier
	v_mfma_f32_16x16x32_bf16 v[60:63], v[202:205], v[160:163], v[60:63]
	v_mfma_f32_16x16x32_bf16 v[56:59], v[210:213], v[160:163], v[56:59]
	v_mfma_f32_16x16x32_bf16 v[44:47], v[202:205], v[178:181], v[44:47]
	v_mfma_f32_16x16x32_bf16 v[40:43], v[210:213], v[178:181], v[40:43]
	v_mfma_f32_16x16x32_bf16 v[28:31], v[202:205], v[186:189], v[28:31]
	v_mfma_f32_16x16x32_bf16 v[24:27], v[210:213], v[186:189], v[24:27]
	v_mfma_f32_16x16x32_bf16 v[12:15], v[202:205], v[194:197], v[12:15]
	v_mfma_f32_16x16x32_bf16 v[8:11], v[210:213], v[194:197], v[8:11]
	v_mfma_f32_16x16x32_bf16 v[60:63], v[206:209], v[164:167], v[60:63]
	v_mfma_f32_16x16x32_bf16 v[56:59], v[214:217], v[164:167], v[56:59]
	v_mfma_f32_16x16x32_bf16 v[44:47], v[206:209], v[182:185], v[44:47]
	v_mfma_f32_16x16x32_bf16 v[40:43], v[214:217], v[182:185], v[40:43]
	v_mfma_f32_16x16x32_bf16 v[28:31], v[206:209], v[190:193], v[28:31]
	v_mfma_f32_16x16x32_bf16 v[24:27], v[214:217], v[190:193], v[24:27]
	v_mfma_f32_16x16x32_bf16 v[12:15], v[206:209], v[198:201], v[12:15]
	v_mfma_f32_16x16x32_bf16 v[8:11], v[214:217], v[198:201], v[8:11]
	s_add_i32 s17, s17, 2
	s_add_u32 s30, s30, 0x100
	s_addc_u32 s31, s31, 0
	s_cmp_gt_u32 s17, 13
	s_cbranch_scc0 .Lrot_920
	s_barrier
	v_lshl_or_b32 v152, s59, 7, v171
	v_lshl_add_u32 v156, s8, 8, v170
	v_ashrrev_i32_e32 v153, 31, v152
	v_lshlrev_b64 v[182:183], 1, v[152:153]
	v_ashrrev_i32_e32 v157, 31, v156
	v_lshl_add_u64 v[154:155], s[0:1], 0, v[182:183]
	v_lshlrev_b64 v[184:185], 11, v[156:157]
	v_lshl_add_u64 v[120:121], v[154:155], 0, v[184:185]
	v_mov_b32_e32 v236, 0x40000
	v_mov_b32_e32 v237, 0
	v_lshl_add_u64 v[234:235], v[120:121], 0, v[236:237]
	v_mov_b32_e32 v236, 0x8000
	global_load_dwordx4 v[178:181], v[120:121], off
	v_or_b32_e32 v166, 16, v156
	v_or_b32_e32 v162, 32, v156
	v_or_b32_e32 v158, 48, v156
	v_ashrrev_i32_e32 v167, 31, v166
	v_ashrrev_i32_e32 v163, 31, v162
	v_ashrrev_i32_e32 v159, 31, v158
	v_lshlrev_b64 v[168:169], 11, v[166:167]
	v_lshlrev_b64 v[164:165], 11, v[162:163]
	v_lshlrev_b64 v[160:161], 11, v[158:159]
	v_lshl_add_u64 v[120:121], v[154:155], 0, v[168:169]
	v_lshl_add_u64 v[122:123], v[154:155], 0, v[164:165]
	v_lshl_add_u64 v[186:187], v[154:155], 0, v[160:161]
	global_load_dwordx4 v[136:139], v[120:121], off
	global_load_dwordx4 v[132:135], v[122:123], off
	s_nop 0
	global_load_dwordx4 v[120:123], v[186:187], off
	global_load_dwordx4 v[238:241], v[234:235], off
	v_lshl_add_u64 v[234:235], v[234:235], 0, v[236:237]
	global_load_dwordx4 v[242:245], v[234:235], off
	v_lshl_add_u64 v[234:235], v[234:235], 0, v[236:237]
	global_load_dwordx4 v[246:249], v[234:235], off
	v_lshl_add_u64 v[234:235], v[234:235], 0, v[236:237]
	global_load_dwordx4 v[250:253], v[234:235], off
	v_mul_f32_e32 v129, 0xbfb8aa3b, v129
	v_mul_f32_e32 v131, 0xbfb8aa3b, v131
	v_mul_f32_e32 v125, 0xbfb8aa3b, v125
	v_mul_f32_e32 v127, 0xbfb8aa3b, v127
	v_mul_f32_e32 v128, 0xbfb8aa3b, v128
	v_mul_f32_e32 v130, 0xbfb8aa3b, v130
	v_mul_f32_e32 v124, 0xbfb8aa3b, v124
	v_mul_f32_e32 v126, 0xbfb8aa3b, v126
	v_exp_f32_e32 v129, v129
	v_exp_f32_e32 v131, v131
	v_exp_f32_e32 v125, v125
	v_exp_f32_e32 v127, v127
	v_exp_f32_e32 v128, v128
	v_exp_f32_e32 v130, v130
	v_exp_f32_e32 v189, v124
	v_exp_f32_e32 v126, v126
	v_and_b32_e32 v187, 64, v175
	v_xor_b32_e32 v186, 16, v175
	v_add_u32_e32 v187, 64, v187
	v_cmp_lt_i32_e32 vcc, v186, v187
	v_add_f32_e32 v129, 1.0, v129
	v_add_f32_e32 v131, 1.0, v131
	v_add_f32_e32 v125, 1.0, v125
	v_add_f32_e32 v127, 1.0, v127
	v_cndmask_b32_e32 v124, v175, v186, vcc
	v_add_f32_e32 v128, 1.0, v128
	v_add_f32_e32 v130, 1.0, v130
	v_add_f32_e32 v186, 1.0, v189
	v_add_f32_e32 v126, 1.0, v126
	v_rcp_f32_e32 v129, v129
	v_rcp_f32_e32 v131, v131
	v_rcp_f32_e32 v125, v125
	v_rcp_f32_e32 v127, v127
	v_rcp_f32_e32 v128, v128
	v_rcp_f32_e32 v130, v130
	v_rcp_f32_e32 v186, v186
	v_rcp_f32_e32 v126, v126
	v_lshlrev_b32_e32 v124, 2, v124
	v_xor_b32_e32 v188, 32, v175
	v_cmp_lt_i32_e32 vcc, v188, v187
	s_lshl_b32 s24, s59, 2
	s_ashr_i32 s25, s24, 31
	s_waitcnt vmcnt(4)
	v_lshlrev_b32_e32 v189, 16, v178
	v_and_b32_e32 v178, 0xffff0000, v178
	v_lshlrev_b32_e32 v190, 16, v179
	v_and_b32_e32 v179, 0xffff0000, v179
	v_lshlrev_b32_e32 v191, 16, v180
	v_and_b32_e32 v180, 0xffff0000, v180
	v_lshlrev_b32_e32 v192, 16, v181
	v_and_b32_e32 v181, 0xffff0000, v181
	v_fmac_f32_e32 v178, v117, v129
	v_fmac_f32_e32 v179, v119, v131
	v_fmac_f32_e32 v180, v113, v125
	v_fmac_f32_e32 v181, v115, v127
	v_fmac_f32_e32 v189, v116, v128
	v_fmac_f32_e32 v190, v118, v130
	v_fmac_f32_e32 v191, v112, v186
	v_fmac_f32_e32 v192, v114, v126
	v_mul_f32_e32 v112, v178, v178
	v_mul_f32_e32 v113, v179, v179
	v_mul_f32_e32 v114, v180, v180
	v_mul_f32_e32 v115, v181, v181
	v_fmac_f32_e32 v112, v189, v189
	v_fmac_f32_e32 v113, v190, v190
	v_fmac_f32_e32 v114, v191, v191
	v_fmac_f32_e32 v115, v192, v192
	v_add_f32_e32 v112, v112, v113
	v_add_f32_e32 v113, v114, v115
	v_add_f32_e32 v112, v112, v113
	v_mov_b32_e32 v113, v112
	s_nop 1
	v_permlane16_swap_b32 v113, v112
	v_lshl_add_u64 v[126:127], s[0:1], 0, v[184:185]
	v_lshl_add_u64 v[126:127], v[126:127], 0, v[182:183]
	v_cvt_pk_bf16_f32 v116, v189, v178
	v_cvt_pk_bf16_f32 v117, v190, v179
	s_waitcnt lgkmcnt(0)
	v_add_f32_e32 v113, v112, v113
	v_cndmask_b32_e32 v112, v175, v188, vcc
	v_lshlrev_b32_e32 v112, 2, v112
	v_mov_b32_e32 v114, v113
	s_nop 1
	v_permlane32_swap_b32 v114, v113
	v_cvt_pk_bf16_f32 v118, v191, v180
	v_cvt_pk_bf16_f32 v119, v192, v181
	global_store_dwordx4 v[126:127], v[116:119], off
	s_and_saveexec_b64 s[26:27], s[4:5]
	s_cbranch_execz .LBB0_923
; __device__ __forceinline__ unsigned pk2(float lo, float hi) { unsigned r; asm volatile("v_cvt_pk_bf16_f32 %0, %1, %2" : "=v"(r) : "v"(lo), "v"(hi)); return r; }
; __device__ __forceinline__ unsigned pk2(float lo, float hi) { return f2bf(lo) | (f2bf(hi) << 16); }
; __device__ __forceinline__ float fast_sigmoid(float z) { return __builtin_amdgcn_rcpf(1.0f + __expf(-z)); }
;     __device__ __forceinline__ void epi(const f32x4 (&acc)[2][2][4][2], const Unit& u, int wr, int wc, int fr, int fq) const {
;     ...
;         for (int ai = 0; ai < 2; ++ai) {
;             u32x4 xo[4];
; #pragma unroll
;             for (int m = 0; m < 4; ++m) xo[m] = *(const u32x4*)(xb + (size_t)(row0 + ai * 128 + m * 16) * D + col0);
; #pragma unroll
;             for (int m = 0; m < 4; ++m) {
;                 const int row = row0 + ai * 128 + m * 16; const size_t off = (size_t)row * D + col0;
;                 const u32x4 o = xo[m]; const f32x4 a0v = acc[ai][0][m][0], a1v = acc[ai][0][m][1], b0v = acc[ai][1][m][0], b1v = acc[ai][1][m][1];
;                 const float v0 = bf_lo(o.x) + coef * a0v[0] * fast_sigmoid(b0v[0]), v1 = bf_hi(o.x) + coef * a0v[1] * fast_sigmoid(b0v[1]);
;                 const float v2 = bf_lo(o.y) + coef * a0v[2] * fast_sigmoid(b0v[2]), v3 = bf_hi(o.y) + coef * a0v[3] * fast_sigmoid(b0v[3]);
;                 const float v4 = bf_lo(o.z) + coef * a1v[0] * fast_sigmoid(b1v[0]), v5 = bf_hi(o.z) + coef * a1v[1] * fast_sigmoid(b1v[1]);
;                 const float v6 = bf_lo(o.w) + coef * a1v[2] * fast_sigmoid(b1v[2]), v7 = bf_hi(o.w) + coef * a1v[3] * fast_sigmoid(b1v[3]);
;                 u32x4 w; w.x = pk2(v0, v1); w.y = pk2(v2, v3); w.z = pk2(v4, v5); w.w = pk2(v6, v7);
;                 *(u32x4*)(xb + off) = w;
;                 float ss = ((v0 * v0 + v1 * v1) + (v2 * v2 + v3 * v3)) + ((v4 * v4 + v5 * v5) + (v6 * v6 + v7 * v7));
;                 ss += __shfl_xor(ss, 16); ss += __shfl_xor(ss, 32);
;                 if (fq == 0) rowss[(size_t)row * 32 + u.pn * 4 + wc] = ss;
	v_lshlrev_b64 v[116:117], 7, v[156:157]
	v_lshl_add_u64 v[116:117], s[2:3], 0, v[116:117]
	v_lshl_add_u64 v[116:117], s[24:25], 2, v[116:117]
	s_lshl_b32 s8, s45, 2
	v_lshl_add_u64 v[116:117], v[116:117], 0, s[8:9]
	s_waitcnt lgkmcnt(0)
	v_add_f32_e32 v113, v113, v114
	global_store_dword v[116:117], v113, off
.LBB0_923:
	s_or_b64 exec, exec, s[26:27]
	v_mul_f32_e32 v108, 0xbfb8aa3b, v108
	v_exp_f32_e32 v108, v108
	v_mul_f32_e32 v109, 0xbfb8aa3b, v109
	v_exp_f32_e32 v109, v109
	v_lshlrev_b32_e32 v113, 16, v136
	v_add_f32_e32 v108, 1.0, v108
	v_rcp_f32_e32 v108, v108
	v_add_f32_e32 v109, 1.0, v109
	v_rcp_f32_e32 v109, v109
	s_waitcnt lgkmcnt(0)
	v_and_b32_e32 v114, 0xffff0000, v136
	v_fmac_f32_e32 v113, v100, v108
	v_mul_f32_e32 v100, 0xbfb8aa3b, v110
	v_fmac_f32_e32 v114, v101, v109
	v_exp_f32_e32 v100, v100
	v_mul_f32_e32 v101, 0xbfb8aa3b, v111
	v_exp_f32_e32 v101, v101
	v_mul_f32_e32 v104, 0xbfb8aa3b, v104
	v_add_f32_e32 v100, 1.0, v100
	v_rcp_f32_e32 v100, v100
	v_add_f32_e32 v101, 1.0, v101
	v_rcp_f32_e32 v101, v101
	v_exp_f32_e32 v104, v104
	v_lshlrev_b32_e32 v108, 16, v137
	v_fmac_f32_e32 v108, v102, v100
	v_and_b32_e32 v100, 0xffff0000, v137
	v_fmac_f32_e32 v100, v103, v101
	v_add_f32_e32 v101, 1.0, v104
	v_mul_f32_e32 v102, 0xbfb8aa3b, v105
	v_rcp_f32_e32 v101, v101
	v_exp_f32_e32 v102, v102
	v_lshlrev_b32_e32 v103, 16, v138
	v_mul_f32_e32 v104, 0xbfb8aa3b, v107
	v_fmac_f32_e32 v103, v96, v101
	v_add_f32_e32 v101, 1.0, v102
	v_mul_f32_e32 v102, 0xbfb8aa3b, v106
	v_rcp_f32_e32 v101, v101
	v_exp_f32_e32 v102, v102
	v_exp_f32_e32 v104, v104
	v_and_b32_e32 v96, 0xffff0000, v138
	v_fmac_f32_e32 v96, v97, v101
	v_add_f32_e32 v97, 1.0, v102
	v_rcp_f32_e32 v97, v97
	v_add_f32_e32 v101, 1.0, v104
	v_rcp_f32_e32 v101, v101
	v_lshlrev_b32_e32 v102, 16, v139
	v_fmac_f32_e32 v102, v98, v97
	v_and_b32_e32 v104, 0xffff0000, v139
	v_mul_f32_e32 v97, v114, v114
	v_mul_f32_e32 v98, v100, v100
	v_fmac_f32_e32 v104, v99, v101
	v_fmac_f32_e32 v97, v113, v113
	v_fmac_f32_e32 v98, v108, v108
	v_add_f32_e32 v97, v97, v98
	v_mul_f32_e32 v98, v96, v96
	v_mul_f32_e32 v99, v104, v104
	v_fmac_f32_e32 v98, v103, v103
	v_fmac_f32_e32 v99, v102, v102
	v_add_f32_e32 v98, v98, v99
	v_add_f32_e32 v97, v97, v98
	v_mov_b32_e32 v101, v97
	s_nop 1
	v_permlane16_swap_b32 v101, v97
	v_cvt_pk_bf16_f32 v98, v113, v114
	v_cvt_pk_bf16_f32 v99, v108, v100
	v_cvt_pk_bf16_f32 v100, v103, v96
	s_waitcnt lgkmcnt(0)
	v_add_f32_e32 v96, v97, v101
	v_mov_b32_e32 v97, v96
	s_nop 1
	v_permlane32_swap_b32 v97, v96
	v_cvt_pk_bf16_f32 v101, v102, v104
	v_lshl_add_u64 v[102:103], s[0:1], 0, v[168:169]
	v_lshl_add_u64 v[102:103], v[152:153], 1, v[102:103]
	global_store_dwordx4 v[102:103], v[98:101], off
	s_and_saveexec_b64 s[26:27], s[4:5]
	s_cbranch_execz .LBB0_925
	v_lshlrev_b64 v[98:99], 7, v[166:167]
	v_lshl_add_u64 v[98:99], s[2:3], 0, v[98:99]
	v_lshl_add_u64 v[98:99], s[24:25], 2, v[98:99]
	s_lshl_b32 s8, s45, 2
	v_lshl_add_u64 v[98:99], v[98:99], 0, s[8:9]
	s_waitcnt lgkmcnt(0)
	v_add_f32_e32 v96, v96, v97
	global_store_dword v[98:99], v96, off
.LBB0_925:
	s_or_b64 exec, exec, s[26:27]
	v_mul_f32_e32 v92, 0xbfb8aa3b, v92
	v_exp_f32_e32 v92, v92
	v_mul_f32_e32 v93, 0xbfb8aa3b, v93
	v_exp_f32_e32 v93, v93
	v_lshlrev_b32_e32 v96, 16, v132
	v_add_f32_e32 v92, 1.0, v92
	v_rcp_f32_e32 v92, v92
	v_add_f32_e32 v93, 1.0, v93
	v_rcp_f32_e32 v93, v93
	s_waitcnt lgkmcnt(0)
	v_and_b32_e32 v97, 0xffff0000, v132
	v_fmac_f32_e32 v96, v84, v92
	v_mul_f32_e32 v84, 0xbfb8aa3b, v94
	v_fmac_f32_e32 v97, v85, v93
	v_exp_f32_e32 v84, v84
	v_mul_f32_e32 v85, 0xbfb8aa3b, v95
	v_exp_f32_e32 v85, v85
	v_mul_f32_e32 v88, 0xbfb8aa3b, v88
	v_add_f32_e32 v84, 1.0, v84
	v_rcp_f32_e32 v84, v84
	v_add_f32_e32 v85, 1.0, v85
	v_rcp_f32_e32 v85, v85
	v_exp_f32_e32 v88, v88
	v_lshlrev_b32_e32 v92, 16, v133
	v_fmac_f32_e32 v92, v86, v84
	v_and_b32_e32 v84, 0xffff0000, v133
	v_fmac_f32_e32 v84, v87, v85
	v_add_f32_e32 v85, 1.0, v88
	v_mul_f32_e32 v86, 0xbfb8aa3b, v89
	v_rcp_f32_e32 v85, v85
	v_exp_f32_e32 v86, v86
	v_lshlrev_b32_e32 v87, 16, v134
	v_mul_f32_e32 v88, 0xbfb8aa3b, v91
	v_fmac_f32_e32 v87, v80, v85
	v_add_f32_e32 v85, 1.0, v86
	v_mul_f32_e32 v86, 0xbfb8aa3b, v90
	v_rcp_f32_e32 v85, v85
	v_exp_f32_e32 v86, v86
	v_exp_f32_e32 v88, v88
	v_and_b32_e32 v80, 0xffff0000, v134
	v_fmac_f32_e32 v80, v81, v85
	v_add_f32_e32 v81, 1.0, v86
	v_rcp_f32_e32 v81, v81
	v_add_f32_e32 v85, 1.0, v88
	v_rcp_f32_e32 v85, v85
	v_lshlrev_b32_e32 v86, 16, v135
	v_fmac_f32_e32 v86, v82, v81
	v_and_b32_e32 v88, 0xffff0000, v135
	v_mul_f32_e32 v81, v97, v97
	v_mul_f32_e32 v82, v84, v84
	v_fmac_f32_e32 v88, v83, v85
	v_fmac_f32_e32 v81, v96, v96
	v_fmac_f32_e32 v82, v92, v92
	v_add_f32_e32 v81, v81, v82
	v_mul_f32_e32 v82, v80, v80
	v_mul_f32_e32 v83, v88, v88
	v_fmac_f32_e32 v82, v87, v87
	v_fmac_f32_e32 v83, v86, v86
	v_add_f32_e32 v82, v82, v83
	v_add_f32_e32 v81, v81, v82
	v_mov_b32_e32 v85, v81
	s_nop 1
	v_permlane16_swap_b32 v85, v81
	v_cvt_pk_bf16_f32 v82, v96, v97
	v_cvt_pk_bf16_f32 v83, v92, v84
	v_cvt_pk_bf16_f32 v84, v87, v80
	s_waitcnt lgkmcnt(0)
	v_add_f32_e32 v80, v81, v85
	v_mov_b32_e32 v81, v80
	s_nop 1
	v_permlane32_swap_b32 v81, v80
	v_cvt_pk_bf16_f32 v85, v86, v88
	v_lshl_add_u64 v[86:87], s[0:1], 0, v[164:165]
	v_lshl_add_u64 v[86:87], v[152:153], 1, v[86:87]
	global_store_dwordx4 v[86:87], v[82:85], off
	s_and_saveexec_b64 s[26:27], s[4:5]
	s_cbranch_execz .LBB0_927
	v_lshlrev_b64 v[82:83], 7, v[162:163]
	v_lshl_add_u64 v[82:83], s[2:3], 0, v[82:83]
	v_lshl_add_u64 v[82:83], s[24:25], 2, v[82:83]
	s_lshl_b32 s8, s45, 2
	v_lshl_add_u64 v[82:83], v[82:83], 0, s[8:9]
	s_waitcnt lgkmcnt(0)
	v_add_f32_e32 v80, v80, v81
	global_store_dword v[82:83], v80, off
; __device__ __forceinline__ unsigned pk2(float lo, float hi) { unsigned r; asm volatile("v_cvt_pk_bf16_f32 %0, %1, %2" : "=v"(r) : "v"(lo), "v"(hi)); return r; }
; __device__ __forceinline__ unsigned pk2(float lo, float hi) { return f2bf(lo) | (f2bf(hi) << 16); }
; __device__ __forceinline__ float fast_sigmoid(float z) { return __builtin_amdgcn_rcpf(1.0f + __expf(-z)); }
;     __device__ __forceinline__ void epi(const f32x4 (&acc)[2][2][4][2], const Unit& u, int wr, int wc, int fr, int fq) const {
;     ...
;         for (int ai = 0; ai < 2; ++ai) {
;             u32x4 xo[4];
; #pragma unroll
;             for (int m = 0; m < 4; ++m) xo[m] = *(const u32x4*)(xb + (size_t)(row0 + ai * 128 + m * 16) * D + col0);
; #pragma unroll
;             for (int m = 0; m < 4; ++m) {
;                 const int row = row0 + ai * 128 + m * 16; const size_t off = (size_t)row * D + col0;
;                 const u32x4 o = xo[m]; const f32x4 a0v = acc[ai][0][m][0], a1v = acc[ai][0][m][1], b0v = acc[ai][1][m][0], b1v = acc[ai][1][m][1];
;                 const float v0 = bf_lo(o.x) + coef * a0v[0] * fast_sigmoid(b0v[0]), v1 = bf_hi(o.x) + coef * a0v[1] * fast_sigmoid(b0v[1]);
;                 const float v2 = bf_lo(o.y) + coef * a0v[2] * fast_sigmoid(b0v[2]), v3 = bf_hi(o.y) + coef * a0v[3] * fast_sigmoid(b0v[3]);
;                 const float v4 = bf_lo(o.z) + coef * a1v[0] * fast_sigmoid(b1v[0]), v5 = bf_hi(o.z) + coef * a1v[1] * fast_sigmoid(b1v[1]);
;                 const float v6 = bf_lo(o.w) + coef * a1v[2] * fast_sigmoid(b1v[2]), v7 = bf_hi(o.w) + coef * a1v[3] * fast_sigmoid(b1v[3]);
;                 u32x4 w; w.x = pk2(v0, v1); w.y = pk2(v2, v3); w.z = pk2(v4, v5); w.w = pk2(v6, v7);
;                 *(u32x4*)(xb + off) = w;
;                 float ss = ((v0 * v0 + v1 * v1) + (v2 * v2 + v3 * v3)) + ((v4 * v4 + v5 * v5) + (v6 * v6 + v7 * v7));
;                 ss += __shfl_xor(ss, 16); ss += __shfl_xor(ss, 32);
;                 if (fq == 0) rowss[(size_t)row * 32 + u.pn * 4 + wc] = ss;
.LBB0_927:
	s_or_b64 exec, exec, s[26:27]
	v_mul_f32_e32 v76, 0xbfb8aa3b, v76
	v_exp_f32_e32 v76, v76
	v_mul_f32_e32 v77, 0xbfb8aa3b, v77
	v_exp_f32_e32 v77, v77
	v_lshlrev_b32_e32 v80, 16, v120
	v_add_f32_e32 v76, 1.0, v76
	v_rcp_f32_e32 v76, v76
	v_add_f32_e32 v77, 1.0, v77
	v_rcp_f32_e32 v77, v77
	s_waitcnt lgkmcnt(0)
	v_and_b32_e32 v81, 0xffff0000, v120
	v_fmac_f32_e32 v80, v68, v76
	v_mul_f32_e32 v68, 0xbfb8aa3b, v78
	v_fmac_f32_e32 v81, v69, v77
	v_exp_f32_e32 v68, v68
	v_mul_f32_e32 v69, 0xbfb8aa3b, v79
	v_exp_f32_e32 v69, v69
	v_mul_f32_e32 v72, 0xbfb8aa3b, v72
	v_add_f32_e32 v68, 1.0, v68
	v_rcp_f32_e32 v68, v68
	v_add_f32_e32 v69, 1.0, v69
	v_rcp_f32_e32 v69, v69
	v_exp_f32_e32 v72, v72
	v_lshlrev_b32_e32 v76, 16, v121
	v_fmac_f32_e32 v76, v70, v68
	v_and_b32_e32 v68, 0xffff0000, v121
	v_fmac_f32_e32 v68, v71, v69
	v_add_f32_e32 v69, 1.0, v72
	v_mul_f32_e32 v70, 0xbfb8aa3b, v73
	v_rcp_f32_e32 v69, v69
	v_exp_f32_e32 v70, v70
	v_lshlrev_b32_e32 v71, 16, v122
	v_mul_f32_e32 v72, 0xbfb8aa3b, v75
	v_fmac_f32_e32 v71, v64, v69
	v_add_f32_e32 v69, 1.0, v70
	v_mul_f32_e32 v70, 0xbfb8aa3b, v74
	v_rcp_f32_e32 v69, v69
	v_exp_f32_e32 v70, v70
	v_exp_f32_e32 v72, v72
	v_and_b32_e32 v64, 0xffff0000, v122
	v_fmac_f32_e32 v64, v65, v69
	v_add_f32_e32 v65, 1.0, v70
	v_rcp_f32_e32 v65, v65
	v_add_f32_e32 v69, 1.0, v72
	v_rcp_f32_e32 v69, v69
	v_lshlrev_b32_e32 v70, 16, v123
	v_fmac_f32_e32 v70, v66, v65
	v_and_b32_e32 v72, 0xffff0000, v123
	v_mul_f32_e32 v65, v81, v81
	v_mul_f32_e32 v66, v68, v68
	v_fmac_f32_e32 v72, v67, v69
	v_fmac_f32_e32 v65, v80, v80
	v_fmac_f32_e32 v66, v76, v76
	v_add_f32_e32 v65, v65, v66
	v_mul_f32_e32 v66, v64, v64
	v_mul_f32_e32 v67, v72, v72
	v_fmac_f32_e32 v66, v71, v71
	v_fmac_f32_e32 v67, v70, v70
	v_add_f32_e32 v66, v66, v67
	v_add_f32_e32 v65, v65, v66
	v_mov_b32_e32 v69, v65
	s_nop 1
	v_permlane16_swap_b32 v69, v65
	v_cvt_pk_bf16_f32 v66, v80, v81
	v_cvt_pk_bf16_f32 v67, v76, v68
	v_cvt_pk_bf16_f32 v68, v71, v64
	s_waitcnt lgkmcnt(0)
	v_add_f32_e32 v64, v65, v69
	v_mov_b32_e32 v65, v64
	s_nop 1
	v_permlane32_swap_b32 v65, v64
	v_cvt_pk_bf16_f32 v69, v70, v72
	v_lshl_add_u64 v[70:71], s[0:1], 0, v[160:161]
	v_lshl_add_u64 v[70:71], v[152:153], 1, v[70:71]
	global_store_dwordx4 v[70:71], v[66:69], off
	s_and_saveexec_b64 s[26:27], s[4:5]
	s_cbranch_execz .LBB0_929
	v_lshlrev_b64 v[66:67], 7, v[158:159]
	v_lshl_add_u64 v[66:67], s[2:3], 0, v[66:67]
	v_lshl_add_u64 v[66:67], s[24:25], 2, v[66:67]
	s_lshl_b32 s8, s45, 2
	v_lshl_add_u64 v[66:67], v[66:67], 0, s[8:9]
	s_waitcnt lgkmcnt(0)
	v_add_f32_e32 v64, v64, v65
	global_store_dword v[66:67], v64, off
.LBB0_929:
	s_or_b64 exec, exec, s[26:27]
	v_add_u32_e32 v88, 0x80, v156
	v_ashrrev_i32_e32 v89, 31, v88
	v_lshlrev_b64 v[94:95], 11, v[88:89]
	s_waitcnt lgkmcnt(0)
	v_lshl_add_u64 v[64:65], v[154:155], 0, v[94:95]
	s_waitcnt vmcnt(4)
	v_mov_b64_e32 v[90:91], v[238:239]
	v_mov_b64_e32 v[92:93], v[240:241]
	v_add_u32_e32 v84, 0x90, v156
	v_add_u32_e32 v80, 0xa0, v156
	v_add_u32_e32 v76, 0xb0, v156
	v_ashrrev_i32_e32 v85, 31, v84
	v_ashrrev_i32_e32 v81, 31, v80
	v_ashrrev_i32_e32 v77, 31, v76
	v_lshlrev_b64 v[86:87], 11, v[84:85]
	v_lshlrev_b64 v[82:83], 11, v[80:81]
	v_lshlrev_b64 v[78:79], 11, v[76:77]
	v_lshl_add_u64 v[64:65], v[154:155], 0, v[86:87]
	v_lshl_add_u64 v[66:67], v[154:155], 0, v[82:83]
	v_lshl_add_u64 v[96:97], v[154:155], 0, v[78:79]
	v_mov_b64_e32 v[72:73], v[242:243]
	v_mov_b64_e32 v[74:75], v[244:245]
	v_mov_b64_e32 v[68:69], v[246:247]
	v_mov_b64_e32 v[70:71], v[248:249]
	s_nop 0
	v_mov_b64_e32 v[64:65], v[250:251]
	v_mov_b64_e32 v[66:67], v[252:253]
	v_mul_f32_e32 v61, 0xbfb8aa3b, v61
	v_mul_f32_e32 v63, 0xbfb8aa3b, v63
	v_mul_f32_e32 v57, 0xbfb8aa3b, v57
	v_mul_f32_e32 v59, 0xbfb8aa3b, v59
	v_mul_f32_e32 v60, 0xbfb8aa3b, v60
	v_mul_f32_e32 v62, 0xbfb8aa3b, v62
	v_mul_f32_e32 v56, 0xbfb8aa3b, v56
	v_mul_f32_e32 v58, 0xbfb8aa3b, v58
	v_exp_f32_e32 v61, v61
	v_exp_f32_e32 v63, v63
	v_exp_f32_e32 v57, v57
	v_exp_f32_e32 v59, v59
	v_exp_f32_e32 v60, v60
	v_exp_f32_e32 v62, v62
	v_exp_f32_e32 v56, v56
	v_exp_f32_e32 v58, v58
	v_add_f32_e32 v61, 1.0, v61
	v_add_f32_e32 v63, 1.0, v63
	v_add_f32_e32 v57, 1.0, v57
	v_add_f32_e32 v59, 1.0, v59
	v_add_f32_e32 v60, 1.0, v60
	v_add_f32_e32 v62, 1.0, v62
	v_add_f32_e32 v56, 1.0, v56
	v_add_f32_e32 v58, 1.0, v58
	v_rcp_f32_e32 v61, v61
	v_rcp_f32_e32 v63, v63
	v_rcp_f32_e32 v57, v57
	v_rcp_f32_e32 v59, v59
	v_rcp_f32_e32 v60, v60
	v_rcp_f32_e32 v62, v62
	v_rcp_f32_e32 v56, v56
	v_rcp_f32_e32 v58, v58
	v_lshlrev_b32_e32 v96, 16, v90
	v_and_b32_e32 v90, 0xffff0000, v90
	v_lshlrev_b32_e32 v97, 16, v91
	v_and_b32_e32 v91, 0xffff0000, v91
	v_lshlrev_b32_e32 v98, 16, v92
	v_and_b32_e32 v92, 0xffff0000, v92
	v_lshlrev_b32_e32 v99, 16, v93
	v_and_b32_e32 v93, 0xffff0000, v93
	v_fmac_f32_e32 v90, v53, v61
	v_fmac_f32_e32 v91, v55, v63
	v_fmac_f32_e32 v92, v49, v57
	v_fmac_f32_e32 v93, v51, v59
	v_fmac_f32_e32 v96, v52, v60
	v_fmac_f32_e32 v97, v54, v62
	v_fmac_f32_e32 v98, v48, v56
	v_fmac_f32_e32 v99, v50, v58
	v_mul_f32_e32 v48, v90, v90
	v_mul_f32_e32 v49, v91, v91
	v_mul_f32_e32 v50, v92, v92
	v_mul_f32_e32 v51, v93, v93
	v_fmac_f32_e32 v48, v96, v96
	v_fmac_f32_e32 v49, v97, v97
	v_fmac_f32_e32 v50, v98, v98
	v_fmac_f32_e32 v51, v99, v99
	v_add_f32_e32 v48, v48, v49
	v_add_f32_e32 v49, v50, v51
	v_add_f32_e32 v48, v48, v49
	v_mov_b32_e32 v49, v48
	s_nop 1
	v_permlane16_swap_b32 v49, v48
	v_lshl_add_u64 v[54:55], s[0:1], 0, v[94:95]
	v_lshl_add_u64 v[54:55], v[152:153], 1, v[54:55]
	v_cvt_pk_bf16_f32 v50, v96, v90
	v_cvt_pk_bf16_f32 v51, v97, v91
	s_waitcnt lgkmcnt(0)
	v_add_f32_e32 v48, v48, v49
	v_mov_b32_e32 v49, v48
	s_nop 1
	v_permlane32_swap_b32 v49, v48
	v_cvt_pk_bf16_f32 v52, v98, v92
	v_cvt_pk_bf16_f32 v53, v99, v93
	global_store_dwordx4 v[54:55], v[50:53], off
	s_and_saveexec_b64 s[26:27], s[4:5]
	s_cbranch_execz .LBB0_931
	v_lshlrev_b64 v[50:51], 7, v[88:89]
	v_lshl_add_u64 v[50:51], s[2:3], 0, v[50:51]
	v_lshl_add_u64 v[50:51], s[24:25], 2, v[50:51]
	s_lshl_b32 s8, s45, 2
	v_lshl_add_u64 v[50:51], v[50:51], 0, s[8:9]
	s_waitcnt lgkmcnt(0)
	v_add_f32_e32 v48, v48, v49
	global_store_dword v[50:51], v48, off
; __device__ __forceinline__ unsigned pk2(float lo, float hi) { unsigned r; asm volatile("v_cvt_pk_bf16_f32 %0, %1, %2" : "=v"(r) : "v"(lo), "v"(hi)); return r; }
; __device__ __forceinline__ unsigned pk2(float lo, float hi) { return f2bf(lo) | (f2bf(hi) << 16); }
; __device__ __forceinline__ float fast_sigmoid(float z) { return __builtin_amdgcn_rcpf(1.0f + __expf(-z)); }
;     __device__ __forceinline__ void epi(const f32x4 (&acc)[2][2][4][2], const Unit& u, int wr, int wc, int fr, int fq) const {
;     ...
;         for (int ai = 0; ai < 2; ++ai) {
;             u32x4 xo[4];
; #pragma unroll
;             for (int m = 0; m < 4; ++m) xo[m] = *(const u32x4*)(xb + (size_t)(row0 + ai * 128 + m * 16) * D + col0);
; #pragma unroll
;             for (int m = 0; m < 4; ++m) {
;                 const int row = row0 + ai * 128 + m * 16; const size_t off = (size_t)row * D + col0;
;                 const u32x4 o = xo[m]; const f32x4 a0v = acc[ai][0][m][0], a1v = acc[ai][0][m][1], b0v = acc[ai][1][m][0], b1v = acc[ai][1][m][1];
;                 const float v0 = bf_lo(o.x) + coef * a0v[0] * fast_sigmoid(b0v[0]), v1 = bf_hi(o.x) + coef * a0v[1] * fast_sigmoid(b0v[1]);
;                 const float v2 = bf_lo(o.y) + coef * a0v[2] * fast_sigmoid(b0v[2]), v3 = bf_hi(o.y) + coef * a0v[3] * fast_sigmoid(b0v[3]);
;                 const float v4 = bf_lo(o.z) + coef * a1v[0] * fast_sigmoid(b1v[0]), v5 = bf_hi(o.z) + coef * a1v[1] * fast_sigmoid(b1v[1]);
;                 const float v6 = bf_lo(o.w) + coef * a1v[2] * fast_sigmoid(b1v[2]), v7 = bf_hi(o.w) + coef * a1v[3] * fast_sigmoid(b1v[3]);
;                 u32x4 w; w.x = pk2(v0, v1); w.y = pk2(v2, v3); w.z = pk2(v4, v5); w.w = pk2(v6, v7);
;                 *(u32x4*)(xb + off) = w;
;                 float ss = ((v0 * v0 + v1 * v1) + (v2 * v2 + v3 * v3)) + ((v4 * v4 + v5 * v5) + (v6 * v6 + v7 * v7));
;                 ss += __shfl_xor(ss, 16); ss += __shfl_xor(ss, 32);
;                 if (fq == 0) rowss[(size_t)row * 32 + u.pn * 4 + wc] = ss;
.LBB0_931:
	s_or_b64 exec, exec, s[26:27]
	v_mul_f32_e32 v44, 0xbfb8aa3b, v44
	v_exp_f32_e32 v44, v44
	v_mul_f32_e32 v45, 0xbfb8aa3b, v45
	v_exp_f32_e32 v45, v45
	v_lshlrev_b32_e32 v48, 16, v72
	v_add_f32_e32 v44, 1.0, v44
	v_rcp_f32_e32 v44, v44
	v_add_f32_e32 v45, 1.0, v45
	v_rcp_f32_e32 v45, v45
	s_waitcnt lgkmcnt(0)
	v_and_b32_e32 v49, 0xffff0000, v72
	v_fmac_f32_e32 v48, v36, v44
	v_mul_f32_e32 v36, 0xbfb8aa3b, v46
	v_fmac_f32_e32 v49, v37, v45
	v_exp_f32_e32 v36, v36
	v_mul_f32_e32 v37, 0xbfb8aa3b, v47
	v_exp_f32_e32 v37, v37
	v_mul_f32_e32 v40, 0xbfb8aa3b, v40
	v_add_f32_e32 v36, 1.0, v36
	v_rcp_f32_e32 v36, v36
	v_add_f32_e32 v37, 1.0, v37
	v_rcp_f32_e32 v37, v37
	v_exp_f32_e32 v40, v40
	v_lshlrev_b32_e32 v44, 16, v73
	v_fmac_f32_e32 v44, v38, v36
	v_and_b32_e32 v36, 0xffff0000, v73
	v_fmac_f32_e32 v36, v39, v37
	v_add_f32_e32 v37, 1.0, v40
	v_mul_f32_e32 v38, 0xbfb8aa3b, v41
	v_rcp_f32_e32 v37, v37
	v_exp_f32_e32 v38, v38
	v_lshlrev_b32_e32 v39, 16, v74
	v_mul_f32_e32 v40, 0xbfb8aa3b, v43
	v_fmac_f32_e32 v39, v32, v37
	v_add_f32_e32 v37, 1.0, v38
	v_mul_f32_e32 v38, 0xbfb8aa3b, v42
	v_rcp_f32_e32 v37, v37
	v_exp_f32_e32 v38, v38
	v_exp_f32_e32 v40, v40
	v_and_b32_e32 v32, 0xffff0000, v74
	v_fmac_f32_e32 v32, v33, v37
	v_add_f32_e32 v33, 1.0, v38
	v_rcp_f32_e32 v33, v33
	v_add_f32_e32 v37, 1.0, v40
	v_rcp_f32_e32 v37, v37
	v_lshlrev_b32_e32 v38, 16, v75
	v_fmac_f32_e32 v38, v34, v33
	v_and_b32_e32 v40, 0xffff0000, v75
	v_mul_f32_e32 v33, v49, v49
	v_mul_f32_e32 v34, v36, v36
	v_fmac_f32_e32 v40, v35, v37
	v_fmac_f32_e32 v33, v48, v48
	v_fmac_f32_e32 v34, v44, v44
	v_add_f32_e32 v33, v33, v34
	v_mul_f32_e32 v34, v32, v32
	v_mul_f32_e32 v35, v40, v40
	v_fmac_f32_e32 v34, v39, v39
	v_fmac_f32_e32 v35, v38, v38
	v_add_f32_e32 v34, v34, v35
	v_add_f32_e32 v33, v33, v34
	v_mov_b32_e32 v37, v33
	s_nop 1
	v_permlane16_swap_b32 v37, v33
	v_cvt_pk_bf16_f32 v34, v48, v49
	v_cvt_pk_bf16_f32 v35, v44, v36
	v_cvt_pk_bf16_f32 v36, v39, v32
	s_waitcnt lgkmcnt(0)
	v_add_f32_e32 v32, v33, v37
	v_mov_b32_e32 v33, v32
	s_nop 1
	v_permlane32_swap_b32 v33, v32
	v_cvt_pk_bf16_f32 v37, v38, v40
	v_lshl_add_u64 v[38:39], s[0:1], 0, v[86:87]
	v_lshl_add_u64 v[38:39], v[152:153], 1, v[38:39]
	global_store_dwordx4 v[38:39], v[34:37], off
	s_and_saveexec_b64 s[26:27], s[4:5]
	s_cbranch_execz .LBB0_933
	v_lshlrev_b64 v[34:35], 7, v[84:85]
	v_lshl_add_u64 v[34:35], s[2:3], 0, v[34:35]
	v_lshl_add_u64 v[34:35], s[24:25], 2, v[34:35]
	s_lshl_b32 s8, s45, 2
	v_lshl_add_u64 v[34:35], v[34:35], 0, s[8:9]
	s_waitcnt lgkmcnt(0)
	v_add_f32_e32 v32, v32, v33
	global_store_dword v[34:35], v32, off
; __device__ __forceinline__ unsigned pk2(float lo, float hi) { unsigned r; asm volatile("v_cvt_pk_bf16_f32 %0, %1, %2" : "=v"(r) : "v"(lo), "v"(hi)); return r; }
; __device__ __forceinline__ unsigned pk2(float lo, float hi) { return f2bf(lo) | (f2bf(hi) << 16); }
; __device__ __forceinline__ float fast_sigmoid(float z) { return __builtin_amdgcn_rcpf(1.0f + __expf(-z)); }
;     __device__ __forceinline__ void epi(const f32x4 (&acc)[2][2][4][2], const Unit& u, int wr, int wc, int fr, int fq) const {
;     ...
;         for (int ai = 0; ai < 2; ++ai) {
;             u32x4 xo[4];
; #pragma unroll
;             for (int m = 0; m < 4; ++m) xo[m] = *(const u32x4*)(xb + (size_t)(row0 + ai * 128 + m * 16) * D + col0);
; #pragma unroll
;             for (int m = 0; m < 4; ++m) {
;                 const int row = row0 + ai * 128 + m * 16; const size_t off = (size_t)row * D + col0;
;                 const u32x4 o = xo[m]; const f32x4 a0v = acc[ai][0][m][0], a1v = acc[ai][0][m][1], b0v = acc[ai][1][m][0], b1v = acc[ai][1][m][1];
;                 const float v0 = bf_lo(o.x) + coef * a0v[0] * fast_sigmoid(b0v[0]), v1 = bf_hi(o.x) + coef * a0v[1] * fast_sigmoid(b0v[1]);
;                 const float v2 = bf_lo(o.y) + coef * a0v[2] * fast_sigmoid(b0v[2]), v3 = bf_hi(o.y) + coef * a0v[3] * fast_sigmoid(b0v[3]);
;                 const float v4 = bf_lo(o.z) + coef * a1v[0] * fast_sigmoid(b1v[0]), v5 = bf_hi(o.z) + coef * a1v[1] * fast_sigmoid(b1v[1]);
;                 const float v6 = bf_lo(o.w) + coef * a1v[2] * fast_sigmoid(b1v[2]), v7 = bf_hi(o.w) + coef * a1v[3] * fast_sigmoid(b1v[3]);
;                 u32x4 w; w.x = pk2(v0, v1); w.y = pk2(v2, v3); w.z = pk2(v4, v5); w.w = pk2(v6, v7);
;                 *(u32x4*)(xb + off) = w;
;                 float ss = ((v0 * v0 + v1 * v1) + (v2 * v2 + v3 * v3)) + ((v4 * v4 + v5 * v5) + (v6 * v6 + v7 * v7));
;                 ss += __shfl_xor(ss, 16); ss += __shfl_xor(ss, 32);
;                 if (fq == 0) rowss[(size_t)row * 32 + u.pn * 4 + wc] = ss;
.LBB0_933:
	s_or_b64 exec, exec, s[26:27]
	v_mul_f32_e32 v28, 0xbfb8aa3b, v28
	v_exp_f32_e32 v28, v28
	v_mul_f32_e32 v29, 0xbfb8aa3b, v29
	v_exp_f32_e32 v29, v29
	v_lshlrev_b32_e32 v32, 16, v68
	v_add_f32_e32 v28, 1.0, v28
	v_rcp_f32_e32 v28, v28
	v_add_f32_e32 v29, 1.0, v29
	v_rcp_f32_e32 v29, v29
	s_waitcnt lgkmcnt(0)
	v_and_b32_e32 v33, 0xffff0000, v68
	v_fmac_f32_e32 v32, v20, v28
	v_mul_f32_e32 v20, 0xbfb8aa3b, v30
	v_fmac_f32_e32 v33, v21, v29
	v_exp_f32_e32 v20, v20
	v_mul_f32_e32 v21, 0xbfb8aa3b, v31
	v_exp_f32_e32 v21, v21
	v_mul_f32_e32 v24, 0xbfb8aa3b, v24
	v_add_f32_e32 v20, 1.0, v20
	v_rcp_f32_e32 v20, v20
	v_add_f32_e32 v21, 1.0, v21
	v_rcp_f32_e32 v21, v21
	v_exp_f32_e32 v24, v24
	v_lshlrev_b32_e32 v28, 16, v69
	v_fmac_f32_e32 v28, v22, v20
	v_and_b32_e32 v20, 0xffff0000, v69
	v_fmac_f32_e32 v20, v23, v21
	v_add_f32_e32 v21, 1.0, v24
	v_mul_f32_e32 v22, 0xbfb8aa3b, v25
	v_rcp_f32_e32 v21, v21
	v_exp_f32_e32 v22, v22
	v_lshlrev_b32_e32 v23, 16, v70
	v_mul_f32_e32 v24, 0xbfb8aa3b, v27
	v_fmac_f32_e32 v23, v16, v21
	v_add_f32_e32 v21, 1.0, v22
	v_mul_f32_e32 v22, 0xbfb8aa3b, v26
	v_rcp_f32_e32 v21, v21
	v_exp_f32_e32 v22, v22
	v_exp_f32_e32 v24, v24
	v_and_b32_e32 v16, 0xffff0000, v70
	v_fmac_f32_e32 v16, v17, v21
	v_add_f32_e32 v17, 1.0, v22
	v_rcp_f32_e32 v17, v17
	v_add_f32_e32 v21, 1.0, v24
	v_rcp_f32_e32 v21, v21
	v_lshlrev_b32_e32 v22, 16, v71
	v_fmac_f32_e32 v22, v18, v17
	v_and_b32_e32 v24, 0xffff0000, v71
	v_mul_f32_e32 v17, v33, v33
	v_mul_f32_e32 v18, v20, v20
	v_fmac_f32_e32 v24, v19, v21
	v_fmac_f32_e32 v17, v32, v32
	v_fmac_f32_e32 v18, v28, v28
	v_add_f32_e32 v17, v17, v18
	v_mul_f32_e32 v18, v16, v16
	v_mul_f32_e32 v19, v24, v24
	v_fmac_f32_e32 v18, v23, v23
	v_fmac_f32_e32 v19, v22, v22
	v_add_f32_e32 v18, v18, v19
	v_add_f32_e32 v17, v17, v18
	v_mov_b32_e32 v21, v17
	s_nop 1
	v_permlane16_swap_b32 v21, v17
	v_cvt_pk_bf16_f32 v18, v32, v33
	v_cvt_pk_bf16_f32 v19, v28, v20
	v_cvt_pk_bf16_f32 v20, v23, v16
	s_waitcnt lgkmcnt(0)
	v_add_f32_e32 v16, v17, v21
	v_mov_b32_e32 v17, v16
	s_nop 1
	v_permlane32_swap_b32 v17, v16
	v_cvt_pk_bf16_f32 v21, v22, v24
	v_lshl_add_u64 v[22:23], s[0:1], 0, v[82:83]
	v_lshl_add_u64 v[22:23], v[152:153], 1, v[22:23]
	global_store_dwordx4 v[22:23], v[18:21], off
	s_and_saveexec_b64 s[26:27], s[4:5]
	s_cbranch_execz .LBB0_935
	v_lshlrev_b64 v[18:19], 7, v[80:81]
	v_lshl_add_u64 v[18:19], s[2:3], 0, v[18:19]
	v_lshl_add_u64 v[18:19], s[24:25], 2, v[18:19]
	s_lshl_b32 s8, s45, 2
	v_lshl_add_u64 v[18:19], v[18:19], 0, s[8:9]
	s_waitcnt lgkmcnt(0)
	v_add_f32_e32 v16, v16, v17
	global_store_dword v[18:19], v16, off
.LBB0_935:
	s_or_b64 exec, exec, s[26:27]
	v_mul_f32_e32 v12, 0xbfb8aa3b, v12
	v_exp_f32_e32 v12, v12
	v_mul_f32_e32 v13, 0xbfb8aa3b, v13
	v_exp_f32_e32 v13, v13
	v_lshlrev_b32_e32 v16, 16, v64
	v_add_f32_e32 v12, 1.0, v12
	v_rcp_f32_e32 v12, v12
	v_add_f32_e32 v13, 1.0, v13
	v_rcp_f32_e32 v13, v13
	s_waitcnt lgkmcnt(0)
	v_and_b32_e32 v17, 0xffff0000, v64
	v_fmac_f32_e32 v16, v4, v12
	v_mul_f32_e32 v4, 0xbfb8aa3b, v14
	v_fmac_f32_e32 v17, v5, v13
	v_exp_f32_e32 v4, v4
	v_mul_f32_e32 v5, 0xbfb8aa3b, v15
	v_exp_f32_e32 v5, v5
	v_mul_f32_e32 v8, 0xbfb8aa3b, v8
	v_add_f32_e32 v4, 1.0, v4
	v_rcp_f32_e32 v4, v4
	v_add_f32_e32 v5, 1.0, v5
	v_rcp_f32_e32 v5, v5
	v_exp_f32_e32 v8, v8
	v_lshlrev_b32_e32 v12, 16, v65
	v_fmac_f32_e32 v12, v6, v4
	v_and_b32_e32 v4, 0xffff0000, v65
	v_fmac_f32_e32 v4, v7, v5
	v_add_f32_e32 v5, 1.0, v8
	v_mul_f32_e32 v6, 0xbfb8aa3b, v9
	v_rcp_f32_e32 v5, v5
	v_exp_f32_e32 v6, v6
	v_lshlrev_b32_e32 v7, 16, v66
	v_mul_f32_e32 v8, 0xbfb8aa3b, v11
	v_fmac_f32_e32 v7, v0, v5
	v_add_f32_e32 v5, 1.0, v6
	v_mul_f32_e32 v6, 0xbfb8aa3b, v10
	v_rcp_f32_e32 v5, v5
	v_exp_f32_e32 v6, v6
	v_exp_f32_e32 v8, v8
	v_and_b32_e32 v0, 0xffff0000, v66
	v_fmac_f32_e32 v0, v1, v5
	v_add_f32_e32 v1, 1.0, v6
	v_rcp_f32_e32 v1, v1
	v_add_f32_e32 v5, 1.0, v8
	v_rcp_f32_e32 v5, v5
	v_lshlrev_b32_e32 v6, 16, v67
	v_fmac_f32_e32 v6, v2, v1
	v_and_b32_e32 v8, 0xffff0000, v67
	v_mul_f32_e32 v1, v17, v17
	v_mul_f32_e32 v2, v4, v4
	v_fmac_f32_e32 v8, v3, v5
	v_fmac_f32_e32 v1, v16, v16
	v_fmac_f32_e32 v2, v12, v12
	v_add_f32_e32 v1, v1, v2
	v_mul_f32_e32 v2, v0, v0
	v_mul_f32_e32 v3, v8, v8
	v_fmac_f32_e32 v2, v7, v7
	v_fmac_f32_e32 v3, v6, v6
	v_add_f32_e32 v2, v2, v3
	v_add_f32_e32 v1, v1, v2
	v_mov_b32_e32 v5, v1
	s_nop 1
	v_permlane16_swap_b32 v5, v1
	v_cvt_pk_bf16_f32 v2, v16, v17
	v_cvt_pk_bf16_f32 v3, v12, v4
	v_cvt_pk_bf16_f32 v4, v7, v0
	s_waitcnt lgkmcnt(0)
	v_add_f32_e32 v0, v1, v5
	v_mov_b32_e32 v1, v0
	s_nop 1
	v_permlane32_swap_b32 v1, v0
	v_cvt_pk_bf16_f32 v5, v6, v8
	v_lshl_add_u64 v[6:7], s[0:1], 0, v[78:79]
	v_lshl_add_u64 v[6:7], v[152:153], 1, v[6:7]
	global_store_dwordx4 v[6:7], v[2:5], off
	s_and_saveexec_b64 s[26:27], s[4:5]
	s_cbranch_execz .LBB0_916
	v_lshlrev_b64 v[2:3], 7, v[76:77]
	v_lshl_add_u64 v[2:3], s[2:3], 0, v[2:3]
	v_lshl_add_u64 v[2:3], s[24:25], 2, v[2:3]
	s_lshl_b32 s8, s45, 2
	v_lshl_add_u64 v[2:3], v[2:3], 0, s[8:9]
	s_waitcnt lgkmcnt(0)
	v_add_f32_e32 v0, v0, v1
	global_store_dword v[2:3], v0, off
	s_branch .LBB0_916

.LBB0_1670:
	s_waitcnt lgkmcnt(0)
	ds_read_b128 v[0:3], v173
	ds_read_b128 v[4:7], v173 offset:1024
	ds_read_b128 v[8:11], v173 offset:2048
	ds_read_b128 v[12:15], v173 offset:3072
	s_lshl_b64 s[22:23], s[16:17], 17
	s_add_u32 s22, s35, s22
	s_addc_u32 s23, s36, s23
	s_add_u32 s52, s24, 0x40080
	s_addc_u32 s53, s25, 0
	s_mov_b32 m0, s47
	v_lshl_add_u64 v[48:49], s[52:53], 0, v[150:151]
	ds_read_b128 v[16:19], v174
	ds_read_b128 v[20:23], v174 offset:1024
	ds_read_b128 v[24:27], v174 offset:2048
	ds_read_b128 v[28:31], v174 offset:3072
	ds_read_b128 v[32:35], v174 offset:4096
	ds_read_b128 v[36:39], v174 offset:5120
	ds_read_b128 v[40:43], v174 offset:6144
	ds_read_b128 v[44:47], v174 offset:7168
	global_load_lds_dwordx4 v[48:49], off
	s_mov_b32 m0, s48
	v_lshl_add_u64 v[48:49], s[52:53], 0, v[146:147]
	global_load_lds_dwordx4 v[48:49], off
	s_waitcnt lgkmcnt(8)
	s_barrier
	s_waitcnt lgkmcnt(0)
	v_mfma_f32_16x16x32_bf16 v[48:51], v[0:3], v[16:19], 0
	v_mfma_f32_16x16x32_bf16 v[52:55], v[8:11], v[16:19], 0
	v_mfma_f32_16x16x32_bf16 v[56:59], v[0:3], v[24:27], 0
	v_mfma_f32_16x16x32_bf16 v[60:63], v[8:11], v[24:27], 0
	v_mfma_f32_16x16x32_bf16 v[64:67], v[0:3], v[32:35], 0
	v_mfma_f32_16x16x32_bf16 v[68:71], v[8:11], v[32:35], 0
	v_mfma_f32_16x16x32_bf16 v[72:75], v[0:3], v[40:43], 0
	v_mfma_f32_16x16x32_bf16 v[76:79], v[8:11], v[40:43], 0
	v_mfma_f32_16x16x32_bf16 v[48:51], v[4:7], v[20:23], v[48:51]
	v_mfma_f32_16x16x32_bf16 v[52:55], v[12:15], v[20:23], v[52:55]
	v_mfma_f32_16x16x32_bf16 v[56:59], v[4:7], v[28:31], v[56:59]
	v_mfma_f32_16x16x32_bf16 v[60:63], v[12:15], v[28:31], v[60:63]
	v_mfma_f32_16x16x32_bf16 v[64:67], v[4:7], v[36:39], v[64:67]
	v_mfma_f32_16x16x32_bf16 v[68:71], v[12:15], v[36:39], v[68:71]
	v_mfma_f32_16x16x32_bf16 v[72:75], v[4:7], v[44:47], v[72:75]
	v_mfma_f32_16x16x32_bf16 v[76:79], v[12:15], v[44:47], v[76:79]
	s_barrier
	v_lshl_add_u64 v[168:169], s[26:27], 0, v[148:149]
	s_mov_b32 m0, s49
	v_lshl_add_u64 v[96:97], v[168:169], 0, s[10:11]
	v_lshl_add_u64 v[212:213], s[26:27], 0, v[144:145]
	ds_read_b128 v[80:83], v175
	ds_read_b128 v[84:87], v175 offset:1024
	ds_read_b128 v[88:91], v175 offset:2048
	ds_read_b128 v[92:95], v175 offset:3072
	global_load_lds_dwordx4 v[96:97], off
	s_mov_b32 m0, s50
	v_lshl_add_u64 v[96:97], v[212:213], 0, s[10:11]
	global_load_lds_dwordx4 v[96:97], off
	s_barrier
	s_waitcnt lgkmcnt(0)
	v_mfma_f32_16x16x32_bf16 v[96:99], v[80:83], v[16:19], 0
	v_mfma_f32_16x16x32_bf16 v[16:19], v[88:91], v[16:19], 0
	v_mfma_f32_16x16x32_bf16 v[100:103], v[80:83], v[24:27], 0
	v_mfma_f32_16x16x32_bf16 v[24:27], v[88:91], v[24:27], 0
	v_mfma_f32_16x16x32_bf16 v[104:107], v[80:83], v[32:35], 0
	v_mfma_f32_16x16x32_bf16 v[32:35], v[88:91], v[32:35], 0
	v_mfma_f32_16x16x32_bf16 v[108:111], v[80:83], v[40:43], 0
	v_mfma_f32_16x16x32_bf16 v[40:43], v[88:91], v[40:43], 0
	v_mfma_f32_16x16x32_bf16 v[96:99], v[84:87], v[20:23], v[96:99]
	v_mfma_f32_16x16x32_bf16 v[16:19], v[92:95], v[20:23], v[16:19]
	v_mfma_f32_16x16x32_bf16 v[20:23], v[84:87], v[28:31], v[100:103]
	v_mfma_f32_16x16x32_bf16 v[24:27], v[92:95], v[28:31], v[24:27]
	v_mfma_f32_16x16x32_bf16 v[28:31], v[84:87], v[36:39], v[104:107]
	v_mfma_f32_16x16x32_bf16 v[32:35], v[92:95], v[36:39], v[32:35]
	v_mfma_f32_16x16x32_bf16 v[36:39], v[84:87], v[44:47], v[108:111]
	v_mfma_f32_16x16x32_bf16 v[40:43], v[92:95], v[44:47], v[40:43]
	v_lshl_add_u64 v[214:215], s[24:25], 0, v[150:151]
	s_mov_b32 m0, s38
	v_lshl_add_u64 v[128:129], v[214:215], 0, s[10:11]
	v_lshl_add_u64 v[216:217], s[24:25], 0, v[146:147]
	s_barrier
	ds_read_b128 v[44:47], v174 offset:16384
	ds_read_b128 v[100:103], v174 offset:17408
	ds_read_b128 v[104:107], v174 offset:18432
	ds_read_b128 v[108:111], v174 offset:19456
	ds_read_b128 v[112:115], v174 offset:20480
	ds_read_b128 v[116:119], v174 offset:21504
	ds_read_b128 v[120:123], v174 offset:22528
	ds_read_b128 v[124:127], v174 offset:23552
	global_load_lds_dwordx4 v[128:129], off
	s_mov_b32 m0, s39
	v_lshl_add_u64 v[128:129], v[216:217], 0, s[10:11]
	global_load_lds_dwordx4 v[128:129], off
	s_barrier
	s_waitcnt lgkmcnt(0)
	v_mfma_f32_16x16x32_bf16 v[128:131], v[0:3], v[44:47], 0
	v_mfma_f32_16x16x32_bf16 v[132:135], v[8:11], v[44:47], 0
	v_mfma_f32_16x16x32_bf16 v[136:139], v[0:3], v[104:107], 0
	v_mfma_f32_16x16x32_bf16 v[140:143], v[8:11], v[104:107], 0
	v_mfma_f32_16x16x32_bf16 v[152:155], v[0:3], v[112:115], 0
	v_mfma_f32_16x16x32_bf16 v[156:159], v[8:11], v[112:115], 0
	v_mfma_f32_16x16x32_bf16 v[0:3], v[0:3], v[120:123], 0
	v_mfma_f32_16x16x32_bf16 v[8:11], v[8:11], v[120:123], 0
	v_mfma_f32_16x16x32_bf16 v[128:131], v[4:7], v[100:103], v[128:131]
	v_mfma_f32_16x16x32_bf16 v[136:139], v[4:7], v[108:111], v[136:139]
	v_mfma_f32_16x16x32_bf16 v[140:143], v[12:15], v[108:111], v[140:143]
	v_mfma_f32_16x16x32_bf16 v[152:155], v[4:7], v[116:119], v[152:155]
	v_mfma_f32_16x16x32_bf16 v[156:159], v[12:15], v[116:119], v[156:159]
	v_mfma_f32_16x16x32_bf16 v[0:3], v[4:7], v[124:127], v[0:3]
	v_mfma_f32_16x16x32_bf16 v[4:7], v[12:15], v[124:127], v[8:11]
	v_mfma_f32_16x16x32_bf16 v[132:135], v[12:15], v[100:103], v[132:135]
	s_barrier
	s_add_u32 s52, s26, 0x10100
	s_addc_u32 s53, s27, 0
	s_add_i32 s19, s46, s37
	v_lshl_add_u64 v[8:9], s[52:53], 0, v[148:149]
	s_mov_b32 m0, s19
	s_add_i32 s17, s19, 0x2000
	global_load_lds_dwordx4 v[8:9], off
	s_mov_b32 m0, s17
	v_lshl_add_u64 v[8:9], s[52:53], 0, v[144:145]
	global_load_lds_dwordx4 v[8:9], off
	s_waitcnt vmcnt(6)
	s_barrier
	v_mfma_f32_16x16x32_bf16 v[8:11], v[80:83], v[44:47], 0
	v_mfma_f32_16x16x32_bf16 v[12:15], v[88:91], v[44:47], 0
	v_mfma_f32_16x16x32_bf16 v[44:47], v[80:83], v[104:107], 0
	v_mfma_f32_16x16x32_bf16 v[104:107], v[88:91], v[104:107], 0
	v_mfma_f32_16x16x32_bf16 v[160:163], v[80:83], v[112:115], 0
	v_mfma_f32_16x16x32_bf16 v[112:115], v[88:91], v[112:115], 0
	v_mfma_f32_16x16x32_bf16 v[80:83], v[80:83], v[120:123], 0
	v_mfma_f32_16x16x32_bf16 v[88:91], v[88:91], v[120:123], 0
	v_mfma_f32_16x16x32_bf16 v[8:11], v[84:87], v[100:103], v[8:11]
	v_mfma_f32_16x16x32_bf16 v[12:15], v[92:95], v[100:103], v[12:15]
	v_mfma_f32_16x16x32_bf16 v[44:47], v[84:87], v[108:111], v[44:47]
	v_mfma_f32_16x16x32_bf16 v[100:103], v[92:95], v[108:111], v[104:107]
	v_mfma_f32_16x16x32_bf16 v[104:107], v[84:87], v[116:119], v[160:163]
	v_mfma_f32_16x16x32_bf16 v[108:111], v[92:95], v[116:119], v[112:115]
	v_mfma_f32_16x16x32_bf16 v[80:83], v[84:87], v[124:127], v[80:83]
	v_mfma_f32_16x16x32_bf16 v[84:87], v[92:95], v[124:127], v[88:91]
	s_add_i32 s51, 0, 0x18000
	v_add_u32_e32 v221, s51, v171
	s_barrier
	ds_read_b128 v[88:91], v221
	ds_read_b128 v[92:95], v221 offset:1024
	ds_read_b128 v[112:115], v221 offset:2048
	ds_read_b128 v[116:119], v221 offset:3072
	s_add_u32 s52, s24, 0x40100
	s_addc_u32 s53, s25, 0
	s_mov_b32 m0, s40
	v_lshl_add_u64 v[196:197], s[52:53], 0, v[150:151]
	ds_read_b128 v[120:123], v174 offset:32768
	ds_read_b128 v[124:127], v174 offset:33792
	ds_read_b128 v[160:163], v174 offset:34816
	ds_read_b128 v[164:167], v174 offset:35840
	ds_read_b128 v[180:183], v174 offset:36864
	ds_read_b128 v[184:187], v174 offset:37888
	ds_read_b128 v[188:191], v174 offset:38912
	ds_read_b128 v[192:195], v174 offset:39936
	global_load_lds_dwordx4 v[196:197], off
	s_mov_b32 m0, s41
	v_lshl_add_u64 v[196:197], s[52:53], 0, v[146:147]
	global_load_lds_dwordx4 v[196:197], off
	s_waitcnt lgkmcnt(8)
	s_barrier
	s_waitcnt lgkmcnt(0)
	v_mfma_f32_16x16x32_bf16 v[48:51], v[88:91], v[120:123], v[48:51]
	v_mfma_f32_16x16x32_bf16 v[52:55], v[112:115], v[120:123], v[52:55]
	v_mfma_f32_16x16x32_bf16 v[56:59], v[88:91], v[160:163], v[56:59]
	v_mfma_f32_16x16x32_bf16 v[60:63], v[112:115], v[160:163], v[60:63]
	v_mfma_f32_16x16x32_bf16 v[64:67], v[88:91], v[180:183], v[64:67]
	v_mfma_f32_16x16x32_bf16 v[68:71], v[112:115], v[180:183], v[68:71]
	v_mfma_f32_16x16x32_bf16 v[72:75], v[88:91], v[188:191], v[72:75]
	v_mfma_f32_16x16x32_bf16 v[76:79], v[112:115], v[188:191], v[76:79]
	v_mfma_f32_16x16x32_bf16 v[48:51], v[92:95], v[124:127], v[48:51]
	v_mfma_f32_16x16x32_bf16 v[52:55], v[116:119], v[124:127], v[52:55]
	v_mfma_f32_16x16x32_bf16 v[56:59], v[92:95], v[164:167], v[56:59]
	v_mfma_f32_16x16x32_bf16 v[60:63], v[116:119], v[164:167], v[60:63]
	v_mfma_f32_16x16x32_bf16 v[64:67], v[92:95], v[184:187], v[64:67]
	v_mfma_f32_16x16x32_bf16 v[68:71], v[116:119], v[184:187], v[68:71]
	v_mfma_f32_16x16x32_bf16 v[72:75], v[92:95], v[192:195], v[72:75]
	v_mfma_f32_16x16x32_bf16 v[76:79], v[116:119], v[192:195], v[76:79]
	s_barrier
	s_add_i32 s54, 0, 0x1c000
	s_add_i32 s53, s51, s37
	v_add_u32_e32 v226, s54, v171
	v_lshl_add_u64 v[168:169], v[168:169], 0, s[12:13]
	s_mov_b32 m0, s53
	s_add_i32 s51, s53, 0x2000
	ds_read_b128 v[196:199], v226
	ds_read_b128 v[200:203], v226 offset:1024
	ds_read_b128 v[204:207], v226 offset:2048
	ds_read_b128 v[208:211], v226 offset:3072
	global_load_lds_dwordx4 v[168:169], off
	s_mov_b32 m0, s51
	v_lshl_add_u64 v[168:169], v[212:213], 0, s[12:13]
	global_load_lds_dwordx4 v[168:169], off
	s_barrier
	s_waitcnt lgkmcnt(0)
	v_mfma_f32_16x16x32_bf16 v[96:99], v[196:199], v[120:123], v[96:99]
	v_mfma_f32_16x16x32_bf16 v[16:19], v[204:207], v[120:123], v[16:19]
	v_mfma_f32_16x16x32_bf16 v[20:23], v[196:199], v[160:163], v[20:23]
	v_mfma_f32_16x16x32_bf16 v[24:27], v[204:207], v[160:163], v[24:27]
	v_mfma_f32_16x16x32_bf16 v[28:31], v[196:199], v[180:183], v[28:31]
	v_mfma_f32_16x16x32_bf16 v[32:35], v[204:207], v[180:183], v[32:35]
	v_mfma_f32_16x16x32_bf16 v[36:39], v[196:199], v[188:191], v[36:39]
	v_mfma_f32_16x16x32_bf16 v[40:43], v[204:207], v[188:191], v[40:43]
	v_mfma_f32_16x16x32_bf16 v[96:99], v[200:203], v[124:127], v[96:99]
	v_mfma_f32_16x16x32_bf16 v[16:19], v[208:211], v[124:127], v[16:19]
	v_mfma_f32_16x16x32_bf16 v[20:23], v[200:203], v[164:167], v[20:23]
	v_mfma_f32_16x16x32_bf16 v[24:27], v[208:211], v[164:167], v[24:27]
	v_mfma_f32_16x16x32_bf16 v[28:31], v[200:203], v[184:187], v[28:31]
	v_mfma_f32_16x16x32_bf16 v[32:35], v[208:211], v[184:187], v[32:35]
	v_mfma_f32_16x16x32_bf16 v[36:39], v[200:203], v[192:195], v[36:39]
	v_mfma_f32_16x16x32_bf16 v[40:43], v[208:211], v[192:195], v[40:43]
	s_mov_b32 m0, s43
	v_lshl_add_u64 v[168:169], v[214:215], 0, s[12:13]
	s_barrier
	ds_read_b128 v[120:123], v174 offset:49152
	ds_read_b128 v[124:127], v174 offset:50176
	ds_read_b128 v[160:163], v174 offset:51200
	ds_read_b128 v[164:167], v174 offset:52224
	ds_read_b128 v[180:183], v174 offset:53248
	ds_read_b128 v[184:187], v174 offset:54272
	ds_read_b128 v[188:191], v174 offset:55296
	ds_read_b128 v[192:195], v174 offset:56320
	global_load_lds_dwordx4 v[168:169], off
	s_mov_b32 m0, s44
	v_lshl_add_u64 v[168:169], v[216:217], 0, s[12:13]
	global_load_lds_dwordx4 v[168:169], off
	s_barrier
	s_waitcnt lgkmcnt(0)
	v_mfma_f32_16x16x32_bf16 v[128:131], v[88:91], v[120:123], v[128:131]
	v_mfma_f32_16x16x32_bf16 v[132:135], v[112:115], v[120:123], v[132:135]
	v_mfma_f32_16x16x32_bf16 v[136:139], v[88:91], v[160:163], v[136:139]
	v_mfma_f32_16x16x32_bf16 v[140:143], v[112:115], v[160:163], v[140:143]
	v_mfma_f32_16x16x32_bf16 v[152:155], v[88:91], v[180:183], v[152:155]
	v_mfma_f32_16x16x32_bf16 v[156:159], v[112:115], v[180:183], v[156:159]
	v_mfma_f32_16x16x32_bf16 v[0:3], v[88:91], v[188:191], v[0:3]
	v_mfma_f32_16x16x32_bf16 v[4:7], v[112:115], v[188:191], v[4:7]
	v_mfma_f32_16x16x32_bf16 v[88:91], v[92:95], v[124:127], v[128:131]
	v_mfma_f32_16x16x32_bf16 v[112:115], v[116:119], v[124:127], v[132:135]
	v_mfma_f32_16x16x32_bf16 v[128:131], v[92:95], v[164:167], v[136:139]
	v_mfma_f32_16x16x32_bf16 v[132:135], v[116:119], v[164:167], v[140:143]
	v_mfma_f32_16x16x32_bf16 v[136:139], v[92:95], v[184:187], v[152:155]
	v_mfma_f32_16x16x32_bf16 v[140:143], v[116:119], v[184:187], v[156:159]
	v_mfma_f32_16x16x32_bf16 v[0:3], v[92:95], v[192:195], v[0:3]
	v_mfma_f32_16x16x32_bf16 v[4:7], v[116:119], v[192:195], v[4:7]
	s_barrier
	s_add_u32 s56, s26, 0x10180
	s_addc_u32 s57, s27, 0
	s_add_i32 s54, s54, s37
	v_lshl_add_u64 v[92:93], s[56:57], 0, v[148:149]
	s_mov_b32 m0, s54
	s_add_i32 s52, s54, 0x2000
	global_load_lds_dwordx4 v[92:93], off
	s_mov_b32 m0, s52
	v_lshl_add_u64 v[92:93], s[56:57], 0, v[144:145]
	global_load_lds_dwordx4 v[92:93], off
	s_waitcnt vmcnt(6)
	s_barrier
	v_mfma_f32_16x16x32_bf16 v[8:11], v[196:199], v[120:123], v[8:11]
	s_and_b64 s[28:29], s[28:29], exec
	s_cselect_b32 s27, s23, s27
	s_cselect_b32 s26, s22, s26
	v_mfma_f32_16x16x32_bf16 v[12:15], v[204:207], v[120:123], v[12:15]
	v_mfma_f32_16x16x32_bf16 v[44:47], v[196:199], v[160:163], v[44:47]
	v_mfma_f32_16x16x32_bf16 v[92:95], v[204:207], v[160:163], v[100:103]
	v_mfma_f32_16x16x32_bf16 v[100:103], v[196:199], v[180:183], v[104:107]
	v_mfma_f32_16x16x32_bf16 v[104:107], v[204:207], v[180:183], v[108:111]
	v_mfma_f32_16x16x32_bf16 v[80:83], v[196:199], v[188:191], v[80:83]
	v_mfma_f32_16x16x32_bf16 v[84:87], v[204:207], v[188:191], v[84:87]
	v_mfma_f32_16x16x32_bf16 v[8:11], v[200:203], v[124:127], v[8:11]
	v_mfma_f32_16x16x32_bf16 v[12:15], v[208:211], v[124:127], v[12:15]
	v_mfma_f32_16x16x32_bf16 v[44:47], v[200:203], v[164:167], v[44:47]
	v_mfma_f32_16x16x32_bf16 v[92:95], v[208:211], v[164:167], v[92:95]
	v_mfma_f32_16x16x32_bf16 v[100:103], v[200:203], v[184:187], v[100:103]
	v_mfma_f32_16x16x32_bf16 v[104:107], v[208:211], v[184:187], v[104:107]
	v_mfma_f32_16x16x32_bf16 v[80:83], v[200:203], v[192:195], v[80:83]
	v_mfma_f32_16x16x32_bf16 v[84:87], v[208:211], v[192:195], v[84:87]
	s_barrier
	ds_read_b128 v[108:111], v173
	ds_read_b128 v[116:119], v173 offset:1024
	ds_read_b128 v[120:123], v173 offset:2048
	ds_read_b128 v[124:127], v173 offset:3072
	s_add_u32 s24, s24, 0x40180
	s_addc_u32 s25, s25, 0
	s_mov_b32 m0, s47
	v_lshl_add_u64 v[168:169], s[24:25], 0, v[150:151]
	ds_read_b128 v[152:155], v174
	ds_read_b128 v[156:159], v174 offset:1024
	ds_read_b128 v[160:163], v174 offset:2048
	ds_read_b128 v[164:167], v174 offset:3072
	ds_read_b128 v[180:183], v174 offset:4096
	ds_read_b128 v[184:187], v174 offset:5120
	ds_read_b128 v[188:191], v174 offset:6144
	ds_read_b128 v[192:195], v174 offset:7168
	global_load_lds_dwordx4 v[168:169], off
	s_mov_b32 m0, s48
	v_lshl_add_u64 v[168:169], s[24:25], 0, v[146:147]
	global_load_lds_dwordx4 v[168:169], off
	s_waitcnt lgkmcnt(8)
	s_barrier
	s_waitcnt lgkmcnt(0)
	v_mfma_f32_16x16x32_bf16 v[48:51], v[108:111], v[152:155], v[48:51]
	v_mfma_f32_16x16x32_bf16 v[52:55], v[120:123], v[152:155], v[52:55]
	v_mfma_f32_16x16x32_bf16 v[56:59], v[108:111], v[160:163], v[56:59]
	v_mfma_f32_16x16x32_bf16 v[60:63], v[120:123], v[160:163], v[60:63]
	v_mfma_f32_16x16x32_bf16 v[64:67], v[108:111], v[180:183], v[64:67]
	v_mfma_f32_16x16x32_bf16 v[68:71], v[120:123], v[180:183], v[68:71]
	v_mfma_f32_16x16x32_bf16 v[72:75], v[108:111], v[188:191], v[72:75]
	v_mfma_f32_16x16x32_bf16 v[76:79], v[120:123], v[188:191], v[76:79]
	v_mfma_f32_16x16x32_bf16 v[48:51], v[116:119], v[156:159], v[48:51]
	v_mfma_f32_16x16x32_bf16 v[52:55], v[124:127], v[156:159], v[52:55]
	v_mfma_f32_16x16x32_bf16 v[56:59], v[116:119], v[164:167], v[56:59]
	v_mfma_f32_16x16x32_bf16 v[60:63], v[124:127], v[164:167], v[60:63]
	v_mfma_f32_16x16x32_bf16 v[64:67], v[116:119], v[184:187], v[64:67]
	v_mfma_f32_16x16x32_bf16 v[68:71], v[124:127], v[184:187], v[68:71]
	v_mfma_f32_16x16x32_bf16 v[72:75], v[116:119], v[192:195], v[72:75]
	v_mfma_f32_16x16x32_bf16 v[76:79], v[124:127], v[192:195], v[76:79]
	s_barrier
	s_mov_b32 m0, s49
	v_lshl_add_u64 v[168:169], s[26:27], 0, v[148:149]
	ds_read_b128 v[196:199], v175
	ds_read_b128 v[200:203], v175 offset:1024
	ds_read_b128 v[204:207], v175 offset:2048
	ds_read_b128 v[208:211], v175 offset:3072
	global_load_lds_dwordx4 v[168:169], off
	s_mov_b32 m0, s50
	v_lshl_add_u64 v[230:231], s[26:27], 0, v[144:145]
	global_load_lds_dwordx4 v[230:231], off
	s_barrier
	s_waitcnt lgkmcnt(0)
	v_mfma_f32_16x16x32_bf16 v[96:99], v[196:199], v[152:155], v[96:99]
	v_mfma_f32_16x16x32_bf16 v[16:19], v[204:207], v[152:155], v[16:19]
	v_mfma_f32_16x16x32_bf16 v[20:23], v[196:199], v[160:163], v[20:23]
	v_mfma_f32_16x16x32_bf16 v[24:27], v[204:207], v[160:163], v[24:27]
	v_mfma_f32_16x16x32_bf16 v[28:31], v[196:199], v[180:183], v[28:31]
	v_mfma_f32_16x16x32_bf16 v[32:35], v[204:207], v[180:183], v[32:35]
	v_mfma_f32_16x16x32_bf16 v[36:39], v[196:199], v[188:191], v[36:39]
	v_mfma_f32_16x16x32_bf16 v[40:43], v[204:207], v[188:191], v[40:43]
	v_mfma_f32_16x16x32_bf16 v[152:155], v[200:203], v[156:159], v[96:99]
	v_mfma_f32_16x16x32_bf16 v[16:19], v[208:211], v[156:159], v[16:19]
	v_mfma_f32_16x16x32_bf16 v[20:23], v[200:203], v[164:167], v[20:23]
	v_mfma_f32_16x16x32_bf16 v[24:27], v[208:211], v[164:167], v[24:27]
	v_mfma_f32_16x16x32_bf16 v[28:31], v[200:203], v[184:187], v[28:31]
	v_mfma_f32_16x16x32_bf16 v[32:35], v[208:211], v[184:187], v[32:35]
	v_mfma_f32_16x16x32_bf16 v[36:39], v[200:203], v[192:195], v[36:39]
	v_mfma_f32_16x16x32_bf16 v[40:43], v[208:211], v[192:195], v[40:43]
	s_mov_b32 m0, s38
	v_lshl_add_u64 v[234:235], s[20:21], 0, v[150:151]
	s_barrier
	ds_read_b128 v[96:99], v174 offset:16384
	ds_read_b128 v[156:159], v174 offset:17408
	ds_read_b128 v[160:163], v174 offset:18432
	ds_read_b128 v[164:167], v174 offset:19456
	ds_read_b128 v[180:183], v174 offset:20480
	ds_read_b128 v[184:187], v174 offset:21504
	ds_read_b128 v[188:191], v174 offset:22528
	ds_read_b128 v[192:195], v174 offset:23552
	global_load_lds_dwordx4 v[234:235], off
	s_mov_b32 m0, s39
	v_lshl_add_u64 v[236:237], s[20:21], 0, v[146:147]
	global_load_lds_dwordx4 v[236:237], off
	s_barrier
	s_waitcnt lgkmcnt(0)
	v_mfma_f32_16x16x32_bf16 v[88:91], v[108:111], v[96:99], v[88:91]
	v_mfma_f32_16x16x32_bf16 v[112:115], v[120:123], v[96:99], v[112:115]
	v_mfma_f32_16x16x32_bf16 v[136:139], v[108:111], v[180:183], v[136:139]
	v_mfma_f32_16x16x32_bf16 v[140:143], v[120:123], v[180:183], v[140:143]
	v_mfma_f32_16x16x32_bf16 v[0:3], v[108:111], v[188:191], v[0:3]
	v_mfma_f32_16x16x32_bf16 v[4:7], v[120:123], v[188:191], v[4:7]
	v_mfma_f32_16x16x32_bf16 v[128:131], v[108:111], v[160:163], v[128:131]
	v_mfma_f32_16x16x32_bf16 v[132:135], v[120:123], v[160:163], v[132:135]
	v_mfma_f32_16x16x32_bf16 v[88:91], v[116:119], v[156:159], v[88:91]
	v_mfma_f32_16x16x32_bf16 v[112:115], v[124:127], v[156:159], v[112:115]
	v_mfma_f32_16x16x32_bf16 v[136:139], v[116:119], v[184:187], v[136:139]
	v_mfma_f32_16x16x32_bf16 v[140:143], v[124:127], v[184:187], v[140:143]
	v_mfma_f32_16x16x32_bf16 v[0:3], v[116:119], v[192:195], v[0:3]
	v_mfma_f32_16x16x32_bf16 v[4:7], v[124:127], v[192:195], v[4:7]
	v_mfma_f32_16x16x32_bf16 v[212:215], v[116:119], v[164:167], v[128:131]
	v_mfma_f32_16x16x32_bf16 v[216:219], v[124:127], v[164:167], v[132:135]
	s_barrier
	s_add_u32 s24, s26, 0x10000
	s_addc_u32 s25, s27, 0
	s_mov_b32 m0, s19
	v_lshl_add_u64 v[108:109], s[24:25], 0, v[148:149]
	global_load_lds_dwordx4 v[108:109], off
	s_mov_b32 m0, s17
	v_lshl_add_u64 v[108:109], s[24:25], 0, v[144:145]
	global_load_lds_dwordx4 v[108:109], off
	s_waitcnt vmcnt(6)
	s_barrier
	v_mfma_f32_16x16x32_bf16 v[8:11], v[196:199], v[96:99], v[8:11]
	v_mfma_f32_16x16x32_bf16 v[12:15], v[204:207], v[96:99], v[12:15]
	v_mfma_f32_16x16x32_bf16 v[44:47], v[196:199], v[160:163], v[44:47]
	v_mfma_f32_16x16x32_bf16 v[92:95], v[204:207], v[160:163], v[92:95]
	v_mfma_f32_16x16x32_bf16 v[96:99], v[196:199], v[180:183], v[100:103]
	v_mfma_f32_16x16x32_bf16 v[100:103], v[204:207], v[180:183], v[104:107]
	v_mfma_f32_16x16x32_bf16 v[80:83], v[196:199], v[188:191], v[80:83]
	v_mfma_f32_16x16x32_bf16 v[84:87], v[204:207], v[188:191], v[84:87]
	v_mfma_f32_16x16x32_bf16 v[124:127], v[200:203], v[156:159], v[8:11]
	v_mfma_f32_16x16x32_bf16 v[156:159], v[208:211], v[156:159], v[12:15]
	v_mfma_f32_16x16x32_bf16 v[160:163], v[200:203], v[164:167], v[44:47]
	v_mfma_f32_16x16x32_bf16 v[164:167], v[208:211], v[164:167], v[92:95]
	v_mfma_f32_16x16x32_bf16 v[180:183], v[200:203], v[184:187], v[96:99]
	v_mfma_f32_16x16x32_bf16 v[100:103], v[208:211], v[184:187], v[100:103]
	v_mfma_f32_16x16x32_bf16 v[184:187], v[200:203], v[192:195], v[80:83]
	v_mfma_f32_16x16x32_bf16 v[188:191], v[208:211], v[192:195], v[84:87]
	s_barrier
	ds_read_b128 v[8:11], v221
	ds_read_b128 v[12:15], v221 offset:1024
	ds_read_b128 v[44:47], v221 offset:2048
	ds_read_b128 v[192:195], v221 offset:3072
	s_add_u32 s24, s20, 0x40000
	s_addc_u32 s25, s21, 0
	s_mov_b32 m0, s40
	v_lshl_add_u64 v[92:93], s[24:25], 0, v[150:151]
	ds_read_b128 v[80:83], v174 offset:32768
	ds_read_b128 v[84:87], v174 offset:33792
	ds_read_b128 v[104:107], v174 offset:34816
	ds_read_b128 v[196:199], v174 offset:35840
	ds_read_b128 v[108:111], v174 offset:36864
	ds_read_b128 v[200:203], v174 offset:37888
	ds_read_b128 v[204:207], v174 offset:38912
	ds_read_b128 v[208:211], v174 offset:39936
	global_load_lds_dwordx4 v[92:93], off
	s_mov_b32 m0, s41
	v_lshl_add_u64 v[92:93], s[24:25], 0, v[146:147]
	global_load_lds_dwordx4 v[92:93], off
	s_waitcnt lgkmcnt(8)
	s_barrier
;     __device__ __forceinline__ void epi(const f32x4 (&acc)[2][2][4][2], const Unit& u, int wr, int wc, int fr, int fq) const {
;     ...
;         const int row0 = u.pm * 256 + wr * 64 + fr, col0 = u.pn * 256 + wc * 32 + 8 * fq;
; #pragma unroll
;         for (int ai = 0; ai < 2; ++ai) {
;             u32x4 xo[4][2];
; #pragma unroll
;             for (int m = 0; m < 4; ++m)
; #pragma unroll
;                 for (int bj = 0; bj < 2; ++bj) xo[m][bj] = *(const u32x4*)(xb + (size_t)(row0 + ai * 128 + m * 16) * D + col0 + bj * 128);
	s_waitcnt lgkmcnt(0)
	v_mfma_f32_16x16x32_bf16 v[52:55], v[44:47], v[80:83], v[52:55]
	v_mfma_f32_16x16x32_bf16 v[56:59], v[8:11], v[104:107], v[56:59]
	v_mfma_f32_16x16x32_bf16 v[60:63], v[44:47], v[104:107], v[60:63]
	v_mfma_f32_16x16x32_bf16 v[64:67], v[8:11], v[108:111], v[64:67]
	v_mfma_f32_16x16x32_bf16 v[68:71], v[44:47], v[108:111], v[68:71]
	v_mfma_f32_16x16x32_bf16 v[72:75], v[8:11], v[204:207], v[72:75]
	v_mfma_f32_16x16x32_bf16 v[222:225], v[44:47], v[204:207], v[76:79]
	v_mfma_f32_16x16x32_bf16 v[48:51], v[8:11], v[80:83], v[48:51]
	v_mfma_f32_16x16x32_bf16 v[128:131], v[192:195], v[84:87], v[52:55]
	v_mfma_f32_16x16x32_bf16 v[120:123], v[12:15], v[196:199], v[56:59]
	v_mfma_f32_16x16x32_bf16 v[116:119], v[192:195], v[196:199], v[60:63]
	v_mfma_f32_16x16x32_bf16 v[96:99], v[12:15], v[200:203], v[64:67]
	v_mfma_f32_16x16x32_bf16 v[92:95], v[192:195], v[200:203], v[68:71]
	v_mfma_f32_16x16x32_bf16 v[76:79], v[12:15], v[208:211], v[72:75]
	v_mfma_f32_16x16x32_bf16 v[72:75], v[192:195], v[208:211], v[222:225]
	v_mfma_f32_16x16x32_bf16 v[132:135], v[12:15], v[84:87], v[48:51]
	s_barrier
	s_mov_b32 m0, s53
	v_lshl_add_u64 v[48:49], v[168:169], 0, s[6:7]
	ds_read_b128 v[56:59], v226
	ds_read_b128 v[222:225], v226 offset:1024
	ds_read_b128 v[60:63], v226 offset:2048
	ds_read_b128 v[226:229], v226 offset:3072
	global_load_lds_dwordx4 v[48:49], off
	s_mov_b32 m0, s51
	v_lshl_add_u64 v[48:49], v[230:231], 0, s[6:7]
	global_load_lds_dwordx4 v[48:49], off
	s_barrier
	s_waitcnt lgkmcnt(0)
	v_mfma_f32_16x16x32_bf16 v[48:51], v[56:59], v[80:83], v[152:155]
	v_mfma_f32_16x16x32_bf16 v[16:19], v[60:63], v[80:83], v[16:19]
	v_mfma_f32_16x16x32_bf16 v[20:23], v[56:59], v[104:107], v[20:23]
	v_mfma_f32_16x16x32_bf16 v[24:27], v[60:63], v[104:107], v[24:27]
	v_mfma_f32_16x16x32_bf16 v[28:31], v[56:59], v[108:111], v[28:31]
	v_mfma_f32_16x16x32_bf16 v[32:35], v[60:63], v[108:111], v[32:35]
	v_mfma_f32_16x16x32_bf16 v[36:39], v[56:59], v[204:207], v[36:39]
	v_mfma_f32_16x16x32_bf16 v[40:43], v[60:63], v[204:207], v[40:43]
	v_mfma_f32_16x16x32_bf16 v[204:207], v[222:225], v[84:87], v[48:51]
	v_mfma_f32_16x16x32_bf16 v[230:233], v[226:229], v[84:87], v[16:19]
	v_mfma_f32_16x16x32_bf16 v[108:111], v[222:225], v[196:199], v[20:23]
	v_mfma_f32_16x16x32_bf16 v[104:107], v[226:229], v[196:199], v[24:27]
	v_mfma_f32_16x16x32_bf16 v[84:87], v[222:225], v[200:203], v[28:31]
	v_mfma_f32_16x16x32_bf16 v[80:83], v[226:229], v[200:203], v[32:35]
	v_mfma_f32_16x16x32_bf16 v[68:71], v[222:225], v[208:211], v[36:39]
	v_mfma_f32_16x16x32_bf16 v[64:67], v[226:229], v[208:211], v[40:43]
	s_mov_b32 m0, s43
	v_lshl_add_u64 v[24:25], v[234:235], 0, s[6:7]
	s_barrier
	ds_read_b128 v[16:19], v174 offset:49152
	ds_read_b128 v[20:23], v174 offset:50176
	ds_read_b128 v[32:35], v174 offset:51200
	ds_read_b128 v[152:155], v174 offset:52224
	ds_read_b128 v[36:39], v174 offset:53248
	ds_read_b128 v[196:199], v174 offset:54272
	ds_read_b128 v[200:203], v174 offset:55296
	ds_read_b128 v[208:211], v174 offset:56320
	global_load_lds_dwordx4 v[24:25], off
	s_mov_b32 m0, s44
	v_lshl_add_u64 v[24:25], v[236:237], 0, s[6:7]
	global_load_lds_dwordx4 v[24:25], off
	s_barrier
	s_waitcnt lgkmcnt(0)
	v_mfma_f32_16x16x32_bf16 v[24:27], v[8:11], v[16:19], v[88:91]
	v_mfma_f32_16x16x32_bf16 v[28:31], v[44:47], v[16:19], v[112:115]
	v_mfma_f32_16x16x32_bf16 v[40:43], v[8:11], v[32:35], v[212:215]
	v_mfma_f32_16x16x32_bf16 v[88:91], v[44:47], v[32:35], v[216:219]
	v_mfma_f32_16x16x32_bf16 v[112:115], v[8:11], v[36:39], v[136:139]
	v_mfma_f32_16x16x32_bf16 v[136:139], v[44:47], v[36:39], v[140:143]
	v_mfma_f32_16x16x32_bf16 v[0:3], v[8:11], v[200:203], v[0:3]
	v_mfma_f32_16x16x32_bf16 v[4:7], v[44:47], v[200:203], v[4:7]
	v_mfma_f32_16x16x32_bf16 v[52:55], v[12:15], v[20:23], v[24:27]
	v_mfma_f32_16x16x32_bf16 v[48:51], v[192:195], v[20:23], v[28:31]
	v_mfma_f32_16x16x32_bf16 v[44:47], v[12:15], v[152:155], v[40:43]
	v_mfma_f32_16x16x32_bf16 v[40:43], v[192:195], v[152:155], v[88:91]
	v_mfma_f32_16x16x32_bf16 v[28:31], v[12:15], v[196:199], v[112:115]
	v_mfma_f32_16x16x32_bf16 v[24:27], v[192:195], v[196:199], v[136:139]
	v_mfma_f32_16x16x32_bf16 v[12:15], v[12:15], v[208:211], v[0:3]
	v_mfma_f32_16x16x32_bf16 v[8:11], v[192:195], v[208:211], v[4:7]
	s_barrier
	s_add_u32 s24, s26, 0x10080
	s_addc_u32 s25, s27, 0
	s_mov_b32 m0, s54
	v_lshl_add_u64 v[0:1], s[24:25], 0, v[148:149]
	global_load_lds_dwordx4 v[0:1], off
	s_mov_b32 m0, s52
	v_lshl_add_u64 v[0:1], s[24:25], 0, v[144:145]
	global_load_lds_dwordx4 v[0:1], off
	s_waitcnt vmcnt(6)
	s_barrier
	v_mfma_f32_16x16x32_bf16 v[0:3], v[56:59], v[16:19], v[124:127]
	v_mfma_f32_16x16x32_bf16 v[4:7], v[60:63], v[16:19], v[156:159]
	v_mfma_f32_16x16x32_bf16 v[16:19], v[56:59], v[32:35], v[160:163]
	v_mfma_f32_16x16x32_bf16 v[32:35], v[60:63], v[32:35], v[164:167]
	v_mfma_f32_16x16x32_bf16 v[88:91], v[56:59], v[36:39], v[180:183]
	v_mfma_f32_16x16x32_bf16 v[100:103], v[60:63], v[36:39], v[100:103]
	v_mfma_f32_16x16x32_bf16 v[112:115], v[56:59], v[200:203], v[184:187]
	v_mfma_f32_16x16x32_bf16 v[124:127], v[60:63], v[200:203], v[188:191]
	v_mfma_f32_16x16x32_bf16 v[60:63], v[222:225], v[20:23], v[0:3]
	v_mfma_f32_16x16x32_bf16 v[56:59], v[226:229], v[20:23], v[4:7]
	v_mfma_f32_16x16x32_bf16 v[36:39], v[222:225], v[152:155], v[16:19]
	v_mfma_f32_16x16x32_bf16 v[32:35], v[226:229], v[152:155], v[32:35]
	v_mfma_f32_16x16x32_bf16 v[20:23], v[222:225], v[196:199], v[88:91]
	v_mfma_f32_16x16x32_bf16 v[16:19], v[226:229], v[196:199], v[100:103]
	v_mfma_f32_16x16x32_bf16 v[4:7], v[222:225], v[208:211], v[112:115]
	v_mfma_f32_16x16x32_bf16 v[0:3], v[226:229], v[208:211], v[124:127]
	v_lshl_or_b32 v152, s45, 8, v172
	v_lshl_add_u32 v156, s8, 8, v170
	v_ashrrev_i32_e32 v153, 31, v152
	v_lshlrev_b64 v[190:191], 1, v[152:153]
	v_ashrrev_i32_e32 v157, 31, v156
	v_lshl_add_u64 v[154:155], s[0:1], 0, v[190:191]
	v_lshlrev_b64 v[192:193], 11, v[156:157]
	v_lshl_add_u64 v[88:89], v[154:155], 0, v[192:193]
	s_barrier
; __device__ __forceinline__ unsigned pk2(float lo, float hi) { unsigned r; asm volatile("v_cvt_pk_bf16_f32 %0, %1, %2" : "=v"(r) : "v"(lo), "v"(hi)); return r; }
; __device__ __forceinline__ unsigned pk2(float lo, float hi) { return f2bf(lo) | (f2bf(hi) << 16); }
;     __device__ __forceinline__ void epi(const f32x4 (&acc)[2][2][4][2], const Unit& u, int wr, int wc, int fr, int fq) const {
;     ...
;         const int row0 = u.pm * 256 + wr * 64 + fr, col0 = u.pn * 256 + wc * 32 + 8 * fq;
; #pragma unroll
;         for (int ai = 0; ai < 2; ++ai) {
;             u32x4 xo[4][2];
; #pragma unroll
;             for (int m = 0; m < 4; ++m)
; #pragma unroll
;                 for (int bj = 0; bj < 2; ++bj) xo[m][bj] = *(const u32x4*)(xb + (size_t)(row0 + ai * 128 + m * 16) * D + col0 + bj * 128);
; #pragma unroll
;             for (int m = 0; m < 4; ++m) {
;                 const int row = row0 + ai * 128 + m * 16; const size_t off = (size_t)row * D + col0; float ss = 0.f;
; #pragma unroll
;                 for (int bj = 0; bj < 2; ++bj) {
;                     const u32x4 o = xo[m][bj]; const f32x4 a0v = acc[ai][bj][m][0], a1v = acc[ai][bj][m][1];
;                     const float v0 = bf_lo(o.x) + coef * a0v[0], v1 = bf_hi(o.x) + coef * a0v[1], v2 = bf_lo(o.y) + coef * a0v[2], v3 = bf_hi(o.y) + coef * a0v[3];
;                     const float v4 = bf_lo(o.z) + coef * a1v[0], v5 = bf_hi(o.z) + coef * a1v[1], v6 = bf_lo(o.w) + coef * a1v[2], v7 = bf_hi(o.w) + coef * a1v[3];
;                     u32x4 w; w.x = pk2(v0, v1); w.y = pk2(v2, v3); w.z = pk2(v4, v5); w.w = pk2(v6, v7);
;                     *(u32x4*)(xb + off + bj * 128) = w;
;                     ss += ((v0 * v0 + v1 * v1) + (v2 * v2 + v3 * v3)) + ((v4 * v4 + v5 * v5) + (v6 * v6 + v7 * v7));
;                 }
;                 ss += __shfl_xor(ss, 16); ss += __shfl_xor(ss, 32);
;                 if (fq == 0) rowss[(size_t)row * 32 + u.pn * 4 + wc] = ss;
;             }
	v_mov_b32_e32 v214, 0x40000
	v_mov_b32_e32 v215, 0
	v_lshl_add_u64 v[212:213], v[88:89], 0, v[214:215]
	v_mov_b32_e32 v214, 0x8000
	global_load_dwordx4 v[182:185], v[88:89], off
	global_load_dwordx4 v[186:189], v[88:89], off offset:256
	v_or_b32_e32 v166, 16, v156
	v_or_b32_e32 v162, 32, v156
	v_or_b32_e32 v158, 48, v156
	v_ashrrev_i32_e32 v167, 31, v166
	v_ashrrev_i32_e32 v163, 31, v162
	v_ashrrev_i32_e32 v159, 31, v158
	v_lshlrev_b64 v[168:169], 11, v[166:167]
	v_lshlrev_b64 v[164:165], 11, v[162:163]
	v_lshlrev_b64 v[160:161], 11, v[158:159]
	v_lshl_add_u64 v[88:89], v[154:155], 0, v[168:169]
	v_lshl_add_u64 v[90:91], v[154:155], 0, v[164:165]
	v_lshl_add_u64 v[180:181], v[154:155], 0, v[160:161]
	global_load_dwordx4 v[140:143], v[88:89], off
	global_load_dwordx4 v[136:139], v[88:89], off offset:256
	global_load_dwordx4 v[124:127], v[90:91], off
	global_load_dwordx4 v[112:115], v[90:91], off offset:256
	global_load_dwordx4 v[100:103], v[180:181], off
	s_nop 0
	global_load_dwordx4 v[88:91], v[180:181], off offset:256
	global_load_dwordx4 v[216:219], v[212:213], off
	global_load_dwordx4 v[222:225], v[212:213], off offset:256
	v_lshl_add_u64 v[212:213], v[212:213], 0, v[214:215]
	global_load_dwordx4 v[226:229], v[212:213], off
	global_load_dwordx4 v[234:237], v[212:213], off offset:256
	v_lshl_add_u64 v[212:213], v[212:213], 0, v[214:215]
	global_load_dwordx4 v[238:241], v[212:213], off
	global_load_dwordx4 v[242:245], v[212:213], off offset:256
	v_lshl_add_u64 v[212:213], v[212:213], 0, v[214:215]
	global_load_dwordx4 v[246:249], v[212:213], off
	global_load_dwordx4 v[250:253], v[212:213], off offset:256
	v_lshl_add_u64 v[192:193], s[0:1], 0, v[192:193]
	v_lshl_add_u64 v[190:191], v[192:193], 0, v[190:191]
	v_cmp_lt_i32_e32 vcc, v177, v178
	s_waitcnt vmcnt(8)
	v_lshlrev_b32_e32 v181, 16, v182
	v_and_b32_e32 v182, 0xffff0000, v182
	v_lshlrev_b32_e32 v192, 16, v183
	v_and_b32_e32 v183, 0xffff0000, v183
	v_lshlrev_b32_e32 v193, 16, v184
	v_and_b32_e32 v184, 0xffff0000, v184
	v_lshlrev_b32_e32 v194, 16, v185
	v_and_b32_e32 v185, 0xffff0000, v185
	v_lshlrev_b32_e32 v195, 16, v186
	v_and_b32_e32 v186, 0xffff0000, v186
	v_lshlrev_b32_e32 v196, 16, v187
	v_and_b32_e32 v187, 0xffff0000, v187
	v_lshlrev_b32_e32 v197, 16, v188
	v_and_b32_e32 v188, 0xffff0000, v188
	v_lshlrev_b32_e32 v198, 16, v189
	v_and_b32_e32 v189, 0xffff0000, v189
	v_add_f32_e32 v133, v133, v182
	v_add_f32_e32 v135, v135, v183
	v_add_f32_e32 v182, v129, v184
	v_add_f32_e32 v131, v131, v185
	v_add_f32_e32 v185, v205, v186
	v_add_f32_e32 v187, v207, v187
	v_add_f32_e32 v188, v231, v188
	v_add_f32_e32 v189, v233, v189
	v_add_f32_e32 v132, v132, v181
	v_add_f32_e32 v134, v134, v192
	v_add_f32_e32 v181, v128, v193
	v_add_f32_e32 v183, v130, v194
	v_add_f32_e32 v184, v204, v195
	v_add_f32_e32 v186, v206, v196
	v_add_f32_e32 v192, v230, v197
	v_add_f32_e32 v193, v232, v198
	v_cvt_pk_bf16_f32 v128, v132, v133
	v_cvt_pk_bf16_f32 v129, v134, v135
	v_mul_f32_e32 v130, v133, v133
	v_mul_f32_e32 v133, v135, v135
	v_mul_f32_e32 v135, v182, v182
	v_mul_f32_e32 v194, v131, v131
	v_mul_f32_e32 v195, v185, v185
	v_mul_f32_e32 v196, v187, v187
	v_mul_f32_e32 v197, v188, v188
	v_mul_f32_e32 v198, v189, v189
	v_fmac_f32_e32 v130, v132, v132
	v_fmac_f32_e32 v133, v134, v134
	v_fmac_f32_e32 v135, v181, v181
	v_fmac_f32_e32 v194, v183, v183
	v_fmac_f32_e32 v195, v184, v184
	v_fmac_f32_e32 v196, v186, v186
	v_fmac_f32_e32 v197, v192, v192
	v_fmac_f32_e32 v198, v193, v193
	v_add_f32_e32 v130, v130, v133
	v_add_f32_e32 v132, v135, v194
	v_add_f32_e32 v133, v195, v196
	v_add_f32_e32 v134, v197, v198
	v_cndmask_b32_e32 v180, v176, v177, vcc
	v_add_f32_e32 v130, v130, v132
	v_add_f32_e32 v132, v133, v134
	v_lshlrev_b32_e32 v180, 2, v180
	v_add_f32_e32 v133, v130, v132
	v_mov_b32_e32 v134, v133
	s_nop 1
	v_permlane16_swap_b32 v134, v133
	v_cmp_lt_i32_e32 vcc, v179, v178
	v_cvt_pk_bf16_f32 v130, v181, v182
	v_cvt_pk_bf16_f32 v131, v183, v131
	global_store_dwordx4 v[190:191], v[128:131], off
	v_cvt_pk_bf16_f32 v132, v184, v185
	s_nop 1
	v_cndmask_b32_e32 v128, v176, v179, vcc
	s_waitcnt lgkmcnt(0)
	v_add_f32_e32 v129, v133, v134
	v_lshlrev_b32_e32 v128, 2, v128
	v_mov_b32_e32 v130, v129
	s_nop 1
	v_permlane32_swap_b32 v130, v129
	v_cvt_pk_bf16_f32 v133, v186, v187
	v_cvt_pk_bf16_f32 v134, v192, v188
	v_cvt_pk_bf16_f32 v135, v193, v189
	global_store_dwordx4 v[190:191], v[132:135], off offset:256
	s_and_saveexec_b64 s[24:25], s[4:5]
	s_cbranch_execz .LBB0_1672
	s_waitcnt lgkmcnt(0)
	v_add_f32_e32 v129, v129, v130
	s_lshl_b32 s26, s45, 2
	v_lshlrev_b64 v[130:131], 7, v[156:157]
	s_ashr_i32 s27, s26, 31
	v_lshl_add_u64 v[130:131], s[2:3], 0, v[130:131]
	v_lshl_add_u64 v[130:131], s[26:27], 2, v[130:131]
	s_lshl_b32 s8, s42, 2
	v_lshl_add_u64 v[130:131], v[130:131], 0, s[8:9]
	global_store_dword v[130:131], v129, off
; __device__ __forceinline__ unsigned pk2(float lo, float hi) { unsigned r; asm volatile("v_cvt_pk_bf16_f32 %0, %1, %2" : "=v"(r) : "v"(lo), "v"(hi)); return r; }
; __device__ __forceinline__ unsigned pk2(float lo, float hi) { return f2bf(lo) | (f2bf(hi) << 16); }
;     __device__ __forceinline__ void epi(const f32x4 (&acc)[2][2][4][2], const Unit& u, int wr, int wc, int fr, int fq) const {
;     ...
;             for (int m = 0; m < 4; ++m) {
;                 const int row = row0 + ai * 128 + m * 16; const size_t off = (size_t)row * D + col0; float ss = 0.f;
; #pragma unroll
;                 for (int bj = 0; bj < 2; ++bj) {
;                     const u32x4 o = xo[m][bj]; const f32x4 a0v = acc[ai][bj][m][0], a1v = acc[ai][bj][m][1];
;                     const float v0 = bf_lo(o.x) + coef * a0v[0], v1 = bf_hi(o.x) + coef * a0v[1], v2 = bf_lo(o.y) + coef * a0v[2], v3 = bf_hi(o.y) + coef * a0v[3];
;                     const float v4 = bf_lo(o.z) + coef * a1v[0], v5 = bf_hi(o.z) + coef * a1v[1], v6 = bf_lo(o.w) + coef * a1v[2], v7 = bf_hi(o.w) + coef * a1v[3];
;                     u32x4 w; w.x = pk2(v0, v1); w.y = pk2(v2, v3); w.z = pk2(v4, v5); w.w = pk2(v6, v7);
;                     *(u32x4*)(xb + off + bj * 128) = w;
;                     ss += ((v0 * v0 + v1 * v1) + (v2 * v2 + v3 * v3)) + ((v4 * v4 + v5 * v5) + (v6 * v6 + v7 * v7));
;                 }
;                 ss += __shfl_xor(ss, 16); ss += __shfl_xor(ss, 32);
;                 if (fq == 0) rowss[(size_t)row * 32 + u.pn * 4 + wc] = ss;
;             }
.LBB0_1672:
	s_or_b64 exec, exec, s[24:25]
	v_lshlrev_b32_e32 v129, 16, v140
	v_add_f32_e32 v120, v120, v129
	v_and_b32_e32 v129, 0xffff0000, v140
	v_add_f32_e32 v121, v121, v129
	v_lshlrev_b32_e32 v129, 16, v141
	v_add_f32_e32 v122, v122, v129
	v_and_b32_e32 v129, 0xffff0000, v141
	v_add_f32_e32 v123, v123, v129
	v_lshlrev_b32_e32 v129, 16, v142
	v_add_f32_e32 v129, v116, v129
	v_and_b32_e32 v116, 0xffff0000, v142
	s_waitcnt lgkmcnt(0)
	v_add_f32_e32 v130, v117, v116
	v_lshlrev_b32_e32 v116, 16, v143
	v_add_f32_e32 v131, v118, v116
	v_and_b32_e32 v116, 0xffff0000, v143
	v_add_f32_e32 v132, v119, v116
	v_cvt_pk_bf16_f32 v116, v120, v121
	v_mul_f32_e32 v121, v121, v121
	v_fmac_f32_e32 v121, v120, v120
	v_mul_f32_e32 v120, v123, v123
	v_fmac_f32_e32 v120, v122, v122
	v_cvt_pk_bf16_f32 v117, v122, v123
	v_add_f32_e32 v120, v121, v120
	v_mul_f32_e32 v121, v130, v130
	v_mul_f32_e32 v122, v132, v132
	v_fmac_f32_e32 v121, v129, v129
	v_fmac_f32_e32 v122, v131, v131
	v_add_f32_e32 v121, v121, v122
	v_add_f32_e32 v120, v120, v121
	v_lshlrev_b32_e32 v121, 16, v136
	v_add_f32_e32 v108, v108, v121
	v_and_b32_e32 v121, 0xffff0000, v136
	v_add_f32_e32 v109, v109, v121
	v_lshlrev_b32_e32 v121, 16, v137
	v_add_f32_e32 v121, v110, v121
	v_and_b32_e32 v110, 0xffff0000, v137
	v_add_f32_e32 v122, v111, v110
	v_lshlrev_b32_e32 v110, 16, v138
	v_add_f32_e32 v123, v104, v110
	v_and_b32_e32 v104, 0xffff0000, v138
	v_cvt_pk_bf16_f32 v118, v129, v130
	v_add_f32_e32 v129, v105, v104
	v_lshlrev_b32_e32 v104, 16, v139
	v_add_f32_e32 v130, v106, v104
	v_and_b32_e32 v104, 0xffff0000, v139
	v_cvt_pk_bf16_f32 v119, v131, v132
	v_add_f32_e32 v131, v107, v104
	v_mul_f32_e32 v104, v109, v109
	v_mul_f32_e32 v105, v122, v122
	v_fmac_f32_e32 v104, v108, v108
	v_fmac_f32_e32 v105, v121, v121
	v_add_f32_e32 v104, v104, v105
	v_mul_f32_e32 v105, v129, v129
	v_mul_f32_e32 v106, v131, v131
	v_fmac_f32_e32 v105, v123, v123
	v_fmac_f32_e32 v106, v130, v130
	v_add_f32_e32 v105, v105, v106
	v_add_f32_e32 v104, v104, v105
	v_add_f32_e32 v107, v120, v104
	v_mov_b32_e32 v120, v107
	s_nop 1
	v_permlane16_swap_b32 v120, v107
	v_lshl_add_u64 v[104:105], s[0:1], 0, v[168:169]
	v_lshl_add_u64 v[110:111], v[152:153], 1, v[104:105]
	global_store_dwordx4 v[110:111], v[116:119], off
	v_cvt_pk_bf16_f32 v106, v108, v109
	s_waitcnt lgkmcnt(0)
	v_add_f32_e32 v104, v107, v120
	v_mov_b32_e32 v105, v104
	s_nop 1
	v_permlane32_swap_b32 v105, v104
	v_cvt_pk_bf16_f32 v107, v121, v122
	v_cvt_pk_bf16_f32 v108, v123, v129
	v_cvt_pk_bf16_f32 v109, v130, v131
	global_store_dwordx4 v[110:111], v[106:109], off offset:256
	s_and_saveexec_b64 s[24:25], s[4:5]
	s_cbranch_execz .LBB0_1674
	s_waitcnt lgkmcnt(0)
	v_add_f32_e32 v106, v104, v105
	s_lshl_b32 s26, s45, 2
	v_lshlrev_b64 v[104:105], 7, v[166:167]
	s_ashr_i32 s27, s26, 31
	v_lshl_add_u64 v[104:105], s[2:3], 0, v[104:105]
	v_lshl_add_u64 v[104:105], s[26:27], 2, v[104:105]
	s_lshl_b32 s8, s42, 2
	v_lshl_add_u64 v[104:105], v[104:105], 0, s[8:9]
	global_store_dword v[104:105], v106, off
.LBB0_1674:
	s_or_b64 exec, exec, s[24:25]
	v_lshlrev_b32_e32 v104, 16, v124
	v_add_f32_e32 v96, v96, v104
	v_and_b32_e32 v104, 0xffff0000, v124
	v_add_f32_e32 v97, v97, v104
	v_lshlrev_b32_e32 v104, 16, v125
	v_add_f32_e32 v98, v98, v104
	v_and_b32_e32 v104, 0xffff0000, v125
	v_add_f32_e32 v99, v99, v104
	v_lshlrev_b32_e32 v104, 16, v126
	v_add_f32_e32 v104, v92, v104
	v_and_b32_e32 v92, 0xffff0000, v126
	s_waitcnt lgkmcnt(0)
	v_add_f32_e32 v105, v93, v92
	v_lshlrev_b32_e32 v92, 16, v127
	v_add_f32_e32 v106, v94, v92
	v_and_b32_e32 v92, 0xffff0000, v127
	v_add_f32_e32 v107, v95, v92
	v_cvt_pk_bf16_f32 v92, v96, v97
	v_mul_f32_e32 v97, v97, v97
	v_fmac_f32_e32 v97, v96, v96
	v_mul_f32_e32 v96, v99, v99
	v_fmac_f32_e32 v96, v98, v98
	v_cvt_pk_bf16_f32 v93, v98, v99
	v_add_f32_e32 v96, v97, v96
	v_mul_f32_e32 v97, v105, v105
	v_mul_f32_e32 v98, v107, v107
	v_fmac_f32_e32 v97, v104, v104
	v_fmac_f32_e32 v98, v106, v106
	v_add_f32_e32 v97, v97, v98
	v_add_f32_e32 v96, v96, v97
	v_lshlrev_b32_e32 v97, 16, v112
	v_add_f32_e32 v84, v84, v97
	v_and_b32_e32 v97, 0xffff0000, v112
	v_add_f32_e32 v85, v85, v97
	v_lshlrev_b32_e32 v97, 16, v113
	v_add_f32_e32 v97, v86, v97
	v_and_b32_e32 v86, 0xffff0000, v113
	v_add_f32_e32 v98, v87, v86
	v_lshlrev_b32_e32 v86, 16, v114
	v_add_f32_e32 v99, v80, v86
	v_and_b32_e32 v80, 0xffff0000, v114
	v_cvt_pk_bf16_f32 v94, v104, v105
	v_add_f32_e32 v104, v81, v80
	v_lshlrev_b32_e32 v80, 16, v115
	v_add_f32_e32 v105, v82, v80
	v_and_b32_e32 v80, 0xffff0000, v115
	v_cvt_pk_bf16_f32 v95, v106, v107
	v_add_f32_e32 v106, v83, v80
	v_mul_f32_e32 v80, v85, v85
	v_mul_f32_e32 v81, v98, v98
	v_fmac_f32_e32 v80, v84, v84
	v_fmac_f32_e32 v81, v97, v97
	v_add_f32_e32 v80, v80, v81
	v_mul_f32_e32 v81, v104, v104
	v_mul_f32_e32 v82, v106, v106
	v_fmac_f32_e32 v81, v99, v99
	v_fmac_f32_e32 v82, v105, v105
	v_add_f32_e32 v81, v81, v82
	v_add_f32_e32 v80, v80, v81
	v_add_f32_e32 v83, v96, v80
	v_mov_b32_e32 v96, v83
	s_nop 1
	v_permlane16_swap_b32 v96, v83
	v_lshl_add_u64 v[80:81], s[0:1], 0, v[164:165]
	v_lshl_add_u64 v[86:87], v[152:153], 1, v[80:81]
	global_store_dwordx4 v[86:87], v[92:95], off
	v_cvt_pk_bf16_f32 v82, v84, v85
	s_waitcnt lgkmcnt(0)
	v_add_f32_e32 v80, v83, v96
	v_mov_b32_e32 v81, v80
	s_nop 1
	v_permlane32_swap_b32 v81, v80
	v_cvt_pk_bf16_f32 v83, v97, v98
	v_cvt_pk_bf16_f32 v84, v99, v104
	v_cvt_pk_bf16_f32 v85, v105, v106
	global_store_dwordx4 v[86:87], v[82:85], off offset:256
	s_and_saveexec_b64 s[24:25], s[4:5]
	s_cbranch_execz .LBB0_1676
	s_waitcnt lgkmcnt(0)
	v_add_f32_e32 v82, v80, v81
	s_lshl_b32 s26, s45, 2
	v_lshlrev_b64 v[80:81], 7, v[162:163]
	s_ashr_i32 s27, s26, 31
	v_lshl_add_u64 v[80:81], s[2:3], 0, v[80:81]
	v_lshl_add_u64 v[80:81], s[26:27], 2, v[80:81]
	s_lshl_b32 s8, s42, 2
	v_lshl_add_u64 v[80:81], v[80:81], 0, s[8:9]
	global_store_dword v[80:81], v82, off
; __device__ __forceinline__ unsigned pk2(float lo, float hi) { unsigned r; asm volatile("v_cvt_pk_bf16_f32 %0, %1, %2" : "=v"(r) : "v"(lo), "v"(hi)); return r; }
; __device__ __forceinline__ unsigned pk2(float lo, float hi) { return f2bf(lo) | (f2bf(hi) << 16); }
;     __device__ __forceinline__ void epi(const f32x4 (&acc)[2][2][4][2], const Unit& u, int wr, int wc, int fr, int fq) const {
;     ...
;                 for (int bj = 0; bj < 2; ++bj) xo[m][bj] = *(const u32x4*)(xb + (size_t)(row0 + ai * 128 + m * 16) * D + col0 + bj * 128);
; #pragma unroll
;             for (int m = 0; m < 4; ++m) {
;                 const int row = row0 + ai * 128 + m * 16; const size_t off = (size_t)row * D + col0; float ss = 0.f;
; #pragma unroll
;                 for (int bj = 0; bj < 2; ++bj) {
;                     const u32x4 o = xo[m][bj]; const f32x4 a0v = acc[ai][bj][m][0], a1v = acc[ai][bj][m][1];
;                     const float v0 = bf_lo(o.x) + coef * a0v[0], v1 = bf_hi(o.x) + coef * a0v[1], v2 = bf_lo(o.y) + coef * a0v[2], v3 = bf_hi(o.y) + coef * a0v[3];
;                     const float v4 = bf_lo(o.z) + coef * a1v[0], v5 = bf_hi(o.z) + coef * a1v[1], v6 = bf_lo(o.w) + coef * a1v[2], v7 = bf_hi(o.w) + coef * a1v[3];
;                     u32x4 w; w.x = pk2(v0, v1); w.y = pk2(v2, v3); w.z = pk2(v4, v5); w.w = pk2(v6, v7);
;                     *(u32x4*)(xb + off + bj * 128) = w;
;                     ss += ((v0 * v0 + v1 * v1) + (v2 * v2 + v3 * v3)) + ((v4 * v4 + v5 * v5) + (v6 * v6 + v7 * v7));
;                 }
;                 ss += __shfl_xor(ss, 16); ss += __shfl_xor(ss, 32);
;                 if (fq == 0) rowss[(size_t)row * 32 + u.pn * 4 + wc] = ss;
;             }
.LBB0_1676:
	s_or_b64 exec, exec, s[24:25]
	v_lshlrev_b32_e32 v80, 16, v100
	v_add_f32_e32 v76, v76, v80
	v_and_b32_e32 v80, 0xffff0000, v100
	v_add_f32_e32 v77, v77, v80
	v_lshlrev_b32_e32 v80, 16, v101
	v_add_f32_e32 v78, v78, v80
	v_and_b32_e32 v80, 0xffff0000, v101
	v_add_f32_e32 v79, v79, v80
	v_lshlrev_b32_e32 v80, 16, v102
	v_add_f32_e32 v80, v72, v80
	v_and_b32_e32 v72, 0xffff0000, v102
	s_waitcnt lgkmcnt(0)
	v_add_f32_e32 v81, v73, v72
	v_lshlrev_b32_e32 v72, 16, v103
	v_add_f32_e32 v82, v74, v72
	v_and_b32_e32 v72, 0xffff0000, v103
	v_add_f32_e32 v83, v75, v72
	v_cvt_pk_bf16_f32 v72, v76, v77
	v_mul_f32_e32 v77, v77, v77
	v_fmac_f32_e32 v77, v76, v76
	v_mul_f32_e32 v76, v79, v79
	v_fmac_f32_e32 v76, v78, v78
	v_cvt_pk_bf16_f32 v73, v78, v79
	v_add_f32_e32 v76, v77, v76
	v_mul_f32_e32 v77, v81, v81
	v_mul_f32_e32 v78, v83, v83
	v_fmac_f32_e32 v77, v80, v80
	v_fmac_f32_e32 v78, v82, v82
	v_add_f32_e32 v77, v77, v78
	v_add_f32_e32 v76, v76, v77
	v_lshlrev_b32_e32 v77, 16, v88
	v_add_f32_e32 v68, v68, v77
	v_and_b32_e32 v77, 0xffff0000, v88
	v_add_f32_e32 v69, v69, v77
	v_lshlrev_b32_e32 v77, 16, v89
	v_add_f32_e32 v77, v70, v77
	v_and_b32_e32 v70, 0xffff0000, v89
	v_add_f32_e32 v78, v71, v70
	v_lshlrev_b32_e32 v70, 16, v90
	v_add_f32_e32 v79, v64, v70
	v_and_b32_e32 v64, 0xffff0000, v90
	v_cvt_pk_bf16_f32 v74, v80, v81
	v_add_f32_e32 v80, v65, v64
	v_lshlrev_b32_e32 v64, 16, v91
	v_add_f32_e32 v81, v66, v64
	v_and_b32_e32 v64, 0xffff0000, v91
	v_cvt_pk_bf16_f32 v75, v82, v83
	v_add_f32_e32 v82, v67, v64
	v_mul_f32_e32 v64, v69, v69
	v_mul_f32_e32 v65, v78, v78
	v_fmac_f32_e32 v64, v68, v68
	v_fmac_f32_e32 v65, v77, v77
	v_add_f32_e32 v64, v64, v65
	v_mul_f32_e32 v65, v80, v80
	v_mul_f32_e32 v66, v82, v82
	v_fmac_f32_e32 v65, v79, v79
	v_fmac_f32_e32 v66, v81, v81
	v_add_f32_e32 v65, v65, v66
	v_add_f32_e32 v64, v64, v65
	v_add_f32_e32 v67, v76, v64
	v_mov_b32_e32 v76, v67
	s_nop 1
	v_permlane16_swap_b32 v76, v67
	v_lshl_add_u64 v[64:65], s[0:1], 0, v[160:161]
	v_lshl_add_u64 v[70:71], v[152:153], 1, v[64:65]
	global_store_dwordx4 v[70:71], v[72:75], off
	v_cvt_pk_bf16_f32 v66, v68, v69
	s_waitcnt lgkmcnt(0)
	v_add_f32_e32 v64, v67, v76
	v_mov_b32_e32 v65, v64
	s_nop 1
	v_permlane32_swap_b32 v65, v64
	v_cvt_pk_bf16_f32 v67, v77, v78
	v_cvt_pk_bf16_f32 v68, v79, v80
	v_cvt_pk_bf16_f32 v69, v81, v82
	global_store_dwordx4 v[70:71], v[66:69], off offset:256
	s_and_saveexec_b64 s[24:25], s[4:5]
	s_cbranch_execz .LBB0_1678
	s_waitcnt lgkmcnt(0)
	v_add_f32_e32 v66, v64, v65
	s_lshl_b32 s26, s45, 2
	v_lshlrev_b64 v[64:65], 7, v[158:159]
	s_ashr_i32 s27, s26, 31
	v_lshl_add_u64 v[64:65], s[2:3], 0, v[64:65]
	v_lshl_add_u64 v[64:65], s[26:27], 2, v[64:65]
	s_lshl_b32 s8, s42, 2
	v_lshl_add_u64 v[64:65], v[64:65], 0, s[8:9]
	global_store_dword v[64:65], v66, off
.LBB0_1678:
	s_or_b64 exec, exec, s[24:25]
	v_add_u32_e32 v100, 0x80, v156
	v_ashrrev_i32_e32 v101, 31, v100
	v_lshlrev_b64 v[110:111], 11, v[100:101]
	s_waitcnt lgkmcnt(0)
	v_lshl_add_u64 v[64:65], v[154:155], 0, v[110:111]
	s_waitcnt vmcnt(8)
	v_mov_b64_e32 v[102:103], v[216:217]
	v_mov_b64_e32 v[104:105], v[218:219]
	v_mov_b64_e32 v[106:107], v[222:223]
	v_mov_b64_e32 v[108:109], v[224:225]
	v_add_u32_e32 v96, 0x90, v156
	v_add_u32_e32 v92, 0xa0, v156
	v_add_u32_e32 v88, 0xb0, v156
	v_ashrrev_i32_e32 v97, 31, v96
	v_ashrrev_i32_e32 v93, 31, v92
	v_ashrrev_i32_e32 v89, 31, v88
	v_lshlrev_b64 v[98:99], 11, v[96:97]
	v_lshlrev_b64 v[94:95], 11, v[92:93]
	v_lshlrev_b64 v[90:91], 11, v[88:89]
	v_lshl_add_u64 v[64:65], v[154:155], 0, v[98:99]
	v_lshl_add_u64 v[66:67], v[154:155], 0, v[94:95]
	v_lshl_add_u64 v[112:113], v[154:155], 0, v[90:91]
	v_mov_b64_e32 v[84:85], v[226:227]
	v_mov_b64_e32 v[86:87], v[228:229]
	v_mov_b64_e32 v[80:81], v[234:235]
	v_mov_b64_e32 v[82:83], v[236:237]
	v_mov_b64_e32 v[76:77], v[238:239]
	v_mov_b64_e32 v[78:79], v[240:241]
	v_mov_b64_e32 v[72:73], v[242:243]
	v_mov_b64_e32 v[74:75], v[244:245]
	v_mov_b64_e32 v[68:69], v[246:247]
	v_mov_b64_e32 v[70:71], v[248:249]
	s_nop 0
	v_mov_b64_e32 v[64:65], v[250:251]
	v_mov_b64_e32 v[66:67], v[252:253]
	v_lshlrev_b32_e32 v112, 16, v102
	v_and_b32_e32 v102, 0xffff0000, v102
	v_lshlrev_b32_e32 v113, 16, v103
	v_and_b32_e32 v103, 0xffff0000, v103
	v_lshlrev_b32_e32 v114, 16, v104
	v_and_b32_e32 v104, 0xffff0000, v104
	v_lshlrev_b32_e32 v115, 16, v105
	v_and_b32_e32 v105, 0xffff0000, v105
	v_lshlrev_b32_e32 v116, 16, v106
	v_and_b32_e32 v106, 0xffff0000, v106
	v_lshlrev_b32_e32 v117, 16, v107
	v_and_b32_e32 v107, 0xffff0000, v107
	v_lshlrev_b32_e32 v118, 16, v108
	v_and_b32_e32 v108, 0xffff0000, v108
	v_lshlrev_b32_e32 v119, 16, v109
	v_and_b32_e32 v109, 0xffff0000, v109
	v_add_f32_e32 v53, v53, v102
	v_add_f32_e32 v55, v55, v103
	v_add_f32_e32 v103, v49, v104
	v_add_f32_e32 v105, v51, v105
	v_add_f32_e32 v61, v61, v106
	v_add_f32_e32 v63, v63, v107
	v_add_f32_e32 v57, v57, v108
	v_add_f32_e32 v59, v59, v109
	v_add_f32_e32 v52, v52, v112
	v_add_f32_e32 v54, v54, v113
	v_add_f32_e32 v102, v48, v114
	v_add_f32_e32 v104, v50, v115
	v_add_f32_e32 v60, v60, v116
	v_add_f32_e32 v62, v62, v117
	v_add_f32_e32 v56, v56, v118
	v_add_f32_e32 v58, v58, v119
	v_cvt_pk_bf16_f32 v48, v52, v53
	v_cvt_pk_bf16_f32 v49, v54, v55
	v_cvt_pk_bf16_f32 v50, v102, v103
	v_cvt_pk_bf16_f32 v51, v104, v105
	v_mul_f32_e32 v53, v53, v53
	v_mul_f32_e32 v55, v55, v55
	v_mul_f32_e32 v103, v103, v103
	v_mul_f32_e32 v105, v105, v105
	v_mul_f32_e32 v106, v61, v61
	v_mul_f32_e32 v107, v63, v63
	v_mul_f32_e32 v108, v57, v57
	v_mul_f32_e32 v109, v59, v59
	v_fmac_f32_e32 v53, v52, v52
	v_fmac_f32_e32 v55, v54, v54
	v_fmac_f32_e32 v103, v102, v102
	v_fmac_f32_e32 v105, v104, v104
	v_fmac_f32_e32 v106, v60, v60
	v_fmac_f32_e32 v107, v62, v62
	v_fmac_f32_e32 v108, v56, v56
	v_fmac_f32_e32 v109, v58, v58
	v_add_f32_e32 v52, v53, v55
	v_add_f32_e32 v53, v103, v105
	v_add_f32_e32 v54, v106, v107
	v_add_f32_e32 v55, v108, v109
	v_add_f32_e32 v52, v52, v53
	v_add_f32_e32 v53, v54, v55
	v_add_f32_e32 v102, v52, v53
	v_mov_b32_e32 v103, v102
	s_nop 1
	v_permlane16_swap_b32 v103, v102
	v_lshl_add_u64 v[52:53], s[0:1], 0, v[110:111]
	v_lshl_add_u64 v[54:55], v[152:153], 1, v[52:53]
	global_store_dwordx4 v[54:55], v[48:51], off
	s_waitcnt lgkmcnt(0)
	s_nop 0
	v_add_f32_e32 v48, v102, v103
	v_mov_b32_e32 v49, v48
	s_nop 1
	v_permlane32_swap_b32 v49, v48
	v_cvt_pk_bf16_f32 v50, v60, v61
	v_cvt_pk_bf16_f32 v51, v62, v63
	v_cvt_pk_bf16_f32 v52, v56, v57
	v_cvt_pk_bf16_f32 v53, v58, v59
	global_store_dwordx4 v[54:55], v[50:53], off offset:256
	s_and_saveexec_b64 s[24:25], s[4:5]
	s_cbranch_execz .LBB0_1680
	s_waitcnt lgkmcnt(0)
	v_add_f32_e32 v50, v48, v49
	s_lshl_b32 s26, s45, 2
	v_lshlrev_b64 v[48:49], 7, v[100:101]
	s_ashr_i32 s27, s26, 31
	v_lshl_add_u64 v[48:49], s[2:3], 0, v[48:49]
	v_lshl_add_u64 v[48:49], s[26:27], 2, v[48:49]
	s_lshl_b32 s8, s42, 2
	v_lshl_add_u64 v[48:49], v[48:49], 0, s[8:9]
	global_store_dword v[48:49], v50, off
; __device__ __forceinline__ unsigned pk2(float lo, float hi) { unsigned r; asm volatile("v_cvt_pk_bf16_f32 %0, %1, %2" : "=v"(r) : "v"(lo), "v"(hi)); return r; }
; __device__ __forceinline__ unsigned pk2(float lo, float hi) { return f2bf(lo) | (f2bf(hi) << 16); }
;     __device__ __forceinline__ void epi(const f32x4 (&acc)[2][2][4][2], const Unit& u, int wr, int wc, int fr, int fq) const {
;     ...
;             for (int m = 0; m < 4; ++m) {
;                 const int row = row0 + ai * 128 + m * 16; const size_t off = (size_t)row * D + col0; float ss = 0.f;
; #pragma unroll
;                 for (int bj = 0; bj < 2; ++bj) {
;                     const u32x4 o = xo[m][bj]; const f32x4 a0v = acc[ai][bj][m][0], a1v = acc[ai][bj][m][1];
;                     const float v0 = bf_lo(o.x) + coef * a0v[0], v1 = bf_hi(o.x) + coef * a0v[1], v2 = bf_lo(o.y) + coef * a0v[2], v3 = bf_hi(o.y) + coef * a0v[3];
;                     const float v4 = bf_lo(o.z) + coef * a1v[0], v5 = bf_hi(o.z) + coef * a1v[1], v6 = bf_lo(o.w) + coef * a1v[2], v7 = bf_hi(o.w) + coef * a1v[3];
;                     u32x4 w; w.x = pk2(v0, v1); w.y = pk2(v2, v3); w.z = pk2(v4, v5); w.w = pk2(v6, v7);
;                     *(u32x4*)(xb + off + bj * 128) = w;
;                     ss += ((v0 * v0 + v1 * v1) + (v2 * v2 + v3 * v3)) + ((v4 * v4 + v5 * v5) + (v6 * v6 + v7 * v7));
;                 }
;                 ss += __shfl_xor(ss, 16); ss += __shfl_xor(ss, 32);
;                 if (fq == 0) rowss[(size_t)row * 32 + u.pn * 4 + wc] = ss;
;             }
.LBB0_1680:
	s_or_b64 exec, exec, s[24:25]
	v_lshlrev_b32_e32 v48, 16, v84
	v_add_f32_e32 v44, v44, v48
	v_and_b32_e32 v48, 0xffff0000, v84
	v_add_f32_e32 v45, v45, v48
	v_lshlrev_b32_e32 v48, 16, v85
	v_add_f32_e32 v46, v46, v48
	v_and_b32_e32 v48, 0xffff0000, v85
	v_add_f32_e32 v47, v47, v48
	v_lshlrev_b32_e32 v48, 16, v86
	v_add_f32_e32 v48, v40, v48
	v_and_b32_e32 v40, 0xffff0000, v86
	s_waitcnt lgkmcnt(0)
	v_add_f32_e32 v49, v41, v40
	v_lshlrev_b32_e32 v40, 16, v87
	v_add_f32_e32 v50, v42, v40
	v_and_b32_e32 v40, 0xffff0000, v87
	v_add_f32_e32 v51, v43, v40
	v_cvt_pk_bf16_f32 v40, v44, v45
	v_mul_f32_e32 v45, v45, v45
	v_fmac_f32_e32 v45, v44, v44
	v_mul_f32_e32 v44, v47, v47
	v_fmac_f32_e32 v44, v46, v46
	v_cvt_pk_bf16_f32 v41, v46, v47
	v_add_f32_e32 v44, v45, v44
	v_mul_f32_e32 v45, v49, v49
	v_mul_f32_e32 v46, v51, v51
	v_fmac_f32_e32 v45, v48, v48
	v_fmac_f32_e32 v46, v50, v50
	v_add_f32_e32 v45, v45, v46
	v_add_f32_e32 v44, v44, v45
	v_lshlrev_b32_e32 v45, 16, v80
	v_add_f32_e32 v36, v36, v45
	v_and_b32_e32 v45, 0xffff0000, v80
	v_add_f32_e32 v37, v37, v45
	v_lshlrev_b32_e32 v45, 16, v81
	v_add_f32_e32 v45, v38, v45
	v_and_b32_e32 v38, 0xffff0000, v81
	v_add_f32_e32 v46, v39, v38
	v_lshlrev_b32_e32 v38, 16, v82
	v_add_f32_e32 v47, v32, v38
	v_and_b32_e32 v32, 0xffff0000, v82
	v_cvt_pk_bf16_f32 v42, v48, v49
	v_add_f32_e32 v48, v33, v32
	v_lshlrev_b32_e32 v32, 16, v83
	v_add_f32_e32 v49, v34, v32
	v_and_b32_e32 v32, 0xffff0000, v83
	v_cvt_pk_bf16_f32 v43, v50, v51
	v_add_f32_e32 v50, v35, v32
	v_mul_f32_e32 v32, v37, v37
	v_mul_f32_e32 v33, v46, v46
	v_fmac_f32_e32 v32, v36, v36
	v_fmac_f32_e32 v33, v45, v45
	v_add_f32_e32 v32, v32, v33
	v_mul_f32_e32 v33, v48, v48
	v_mul_f32_e32 v34, v50, v50
	v_fmac_f32_e32 v33, v47, v47
	v_fmac_f32_e32 v34, v49, v49
	v_add_f32_e32 v33, v33, v34
	v_add_f32_e32 v32, v32, v33
	v_add_f32_e32 v35, v44, v32
	v_mov_b32_e32 v44, v35
	s_nop 1
	v_permlane16_swap_b32 v44, v35
	v_lshl_add_u64 v[32:33], s[0:1], 0, v[98:99]
	v_lshl_add_u64 v[38:39], v[152:153], 1, v[32:33]
	global_store_dwordx4 v[38:39], v[40:43], off
	v_cvt_pk_bf16_f32 v34, v36, v37
	s_waitcnt lgkmcnt(0)
	v_add_f32_e32 v32, v35, v44
	v_mov_b32_e32 v33, v32
	s_nop 1
	v_permlane32_swap_b32 v33, v32
	v_cvt_pk_bf16_f32 v35, v45, v46
	v_cvt_pk_bf16_f32 v36, v47, v48
	v_cvt_pk_bf16_f32 v37, v49, v50
	global_store_dwordx4 v[38:39], v[34:37], off offset:256
	s_and_saveexec_b64 s[24:25], s[4:5]
	s_cbranch_execz .LBB0_1682
	s_waitcnt lgkmcnt(0)
	v_add_f32_e32 v34, v32, v33
	s_lshl_b32 s26, s45, 2
	v_lshlrev_b64 v[32:33], 7, v[96:97]
	s_ashr_i32 s27, s26, 31
	v_lshl_add_u64 v[32:33], s[2:3], 0, v[32:33]
	v_lshl_add_u64 v[32:33], s[26:27], 2, v[32:33]
	s_lshl_b32 s8, s42, 2
	v_lshl_add_u64 v[32:33], v[32:33], 0, s[8:9]
	global_store_dword v[32:33], v34, off
; __device__ __forceinline__ unsigned pk2(float lo, float hi) { unsigned r; asm volatile("v_cvt_pk_bf16_f32 %0, %1, %2" : "=v"(r) : "v"(lo), "v"(hi)); return r; }
; __device__ __forceinline__ unsigned pk2(float lo, float hi) { return f2bf(lo) | (f2bf(hi) << 16); }
;     __device__ __forceinline__ void epi(const f32x4 (&acc)[2][2][4][2], const Unit& u, int wr, int wc, int fr, int fq) const {
;     ...
;             for (int m = 0; m < 4; ++m) {
;                 const int row = row0 + ai * 128 + m * 16; const size_t off = (size_t)row * D + col0; float ss = 0.f;
; #pragma unroll
;                 for (int bj = 0; bj < 2; ++bj) {
;                     const u32x4 o = xo[m][bj]; const f32x4 a0v = acc[ai][bj][m][0], a1v = acc[ai][bj][m][1];
;                     const float v0 = bf_lo(o.x) + coef * a0v[0], v1 = bf_hi(o.x) + coef * a0v[1], v2 = bf_lo(o.y) + coef * a0v[2], v3 = bf_hi(o.y) + coef * a0v[3];
;                     const float v4 = bf_lo(o.z) + coef * a1v[0], v5 = bf_hi(o.z) + coef * a1v[1], v6 = bf_lo(o.w) + coef * a1v[2], v7 = bf_hi(o.w) + coef * a1v[3];
;                     u32x4 w; w.x = pk2(v0, v1); w.y = pk2(v2, v3); w.z = pk2(v4, v5); w.w = pk2(v6, v7);
;                     *(u32x4*)(xb + off + bj * 128) = w;
;                     ss += ((v0 * v0 + v1 * v1) + (v2 * v2 + v3 * v3)) + ((v4 * v4 + v5 * v5) + (v6 * v6 + v7 * v7));
;                 }
;                 ss += __shfl_xor(ss, 16); ss += __shfl_xor(ss, 32);
;                 if (fq == 0) rowss[(size_t)row * 32 + u.pn * 4 + wc] = ss;
;             }
.LBB0_1682:
	s_or_b64 exec, exec, s[24:25]
	v_lshlrev_b32_e32 v32, 16, v76
	v_add_f32_e32 v28, v28, v32
	v_and_b32_e32 v32, 0xffff0000, v76
	v_add_f32_e32 v29, v29, v32
	v_lshlrev_b32_e32 v32, 16, v77
	v_add_f32_e32 v30, v30, v32
	v_and_b32_e32 v32, 0xffff0000, v77
	v_add_f32_e32 v31, v31, v32
	v_lshlrev_b32_e32 v32, 16, v78
	v_add_f32_e32 v32, v24, v32
	v_and_b32_e32 v24, 0xffff0000, v78
	s_waitcnt lgkmcnt(0)
	v_add_f32_e32 v33, v25, v24
	v_lshlrev_b32_e32 v24, 16, v79
	v_add_f32_e32 v34, v26, v24
	v_and_b32_e32 v24, 0xffff0000, v79
	v_add_f32_e32 v35, v27, v24
	v_cvt_pk_bf16_f32 v24, v28, v29
	v_mul_f32_e32 v29, v29, v29
	v_fmac_f32_e32 v29, v28, v28
	v_mul_f32_e32 v28, v31, v31
	v_fmac_f32_e32 v28, v30, v30
	v_cvt_pk_bf16_f32 v25, v30, v31
	v_add_f32_e32 v28, v29, v28
	v_mul_f32_e32 v29, v33, v33
	v_mul_f32_e32 v30, v35, v35
	v_fmac_f32_e32 v29, v32, v32
	v_fmac_f32_e32 v30, v34, v34
	v_add_f32_e32 v29, v29, v30
	v_add_f32_e32 v28, v28, v29
	v_lshlrev_b32_e32 v29, 16, v72
	v_add_f32_e32 v20, v20, v29
	v_and_b32_e32 v29, 0xffff0000, v72
	v_add_f32_e32 v21, v21, v29
	v_lshlrev_b32_e32 v29, 16, v73
	v_add_f32_e32 v29, v22, v29
	v_and_b32_e32 v22, 0xffff0000, v73
	v_add_f32_e32 v30, v23, v22
	v_lshlrev_b32_e32 v22, 16, v74
	v_add_f32_e32 v31, v16, v22
	v_and_b32_e32 v16, 0xffff0000, v74
	v_cvt_pk_bf16_f32 v26, v32, v33
	v_add_f32_e32 v32, v17, v16
	v_lshlrev_b32_e32 v16, 16, v75
	v_add_f32_e32 v33, v18, v16
	v_and_b32_e32 v16, 0xffff0000, v75
	v_cvt_pk_bf16_f32 v27, v34, v35
	v_add_f32_e32 v34, v19, v16
	v_mul_f32_e32 v16, v21, v21
	v_mul_f32_e32 v17, v30, v30
	v_fmac_f32_e32 v16, v20, v20
	v_fmac_f32_e32 v17, v29, v29
	v_add_f32_e32 v16, v16, v17
	v_mul_f32_e32 v17, v32, v32
	v_mul_f32_e32 v18, v34, v34
	v_fmac_f32_e32 v17, v31, v31
	v_fmac_f32_e32 v18, v33, v33
	v_add_f32_e32 v17, v17, v18
	v_add_f32_e32 v16, v16, v17
	v_add_f32_e32 v19, v28, v16
	v_mov_b32_e32 v28, v19
	s_nop 1
	v_permlane16_swap_b32 v28, v19
	v_lshl_add_u64 v[16:17], s[0:1], 0, v[94:95]
	v_lshl_add_u64 v[22:23], v[152:153], 1, v[16:17]
	global_store_dwordx4 v[22:23], v[24:27], off
	v_cvt_pk_bf16_f32 v18, v20, v21
	s_waitcnt lgkmcnt(0)
	v_add_f32_e32 v16, v19, v28
	v_mov_b32_e32 v17, v16
	s_nop 1
	v_permlane32_swap_b32 v17, v16
	v_cvt_pk_bf16_f32 v19, v29, v30
	v_cvt_pk_bf16_f32 v20, v31, v32
	v_cvt_pk_bf16_f32 v21, v33, v34
	global_store_dwordx4 v[22:23], v[18:21], off offset:256
	s_and_saveexec_b64 s[24:25], s[4:5]
	s_cbranch_execz .LBB0_1684
	s_waitcnt lgkmcnt(0)
	v_add_f32_e32 v18, v16, v17
	s_lshl_b32 s26, s45, 2
	v_lshlrev_b64 v[16:17], 7, v[92:93]
	s_ashr_i32 s27, s26, 31
	v_lshl_add_u64 v[16:17], s[2:3], 0, v[16:17]
	v_lshl_add_u64 v[16:17], s[26:27], 2, v[16:17]
	s_lshl_b32 s8, s42, 2
	v_lshl_add_u64 v[16:17], v[16:17], 0, s[8:9]
	global_store_dword v[16:17], v18, off
.LBB0_1684:
	s_or_b64 exec, exec, s[24:25]
	v_lshlrev_b32_e32 v16, 16, v68
	v_add_f32_e32 v12, v12, v16
	v_and_b32_e32 v16, 0xffff0000, v68
	v_add_f32_e32 v13, v13, v16
	v_lshlrev_b32_e32 v16, 16, v69
	v_add_f32_e32 v14, v14, v16
	v_and_b32_e32 v16, 0xffff0000, v69
	v_add_f32_e32 v15, v15, v16
	v_lshlrev_b32_e32 v16, 16, v70
	v_add_f32_e32 v16, v8, v16
	v_and_b32_e32 v8, 0xffff0000, v70
	s_waitcnt lgkmcnt(0)
	v_add_f32_e32 v17, v9, v8
	v_lshlrev_b32_e32 v8, 16, v71
	v_add_f32_e32 v18, v10, v8
	v_and_b32_e32 v8, 0xffff0000, v71
	v_add_f32_e32 v19, v11, v8
	v_cvt_pk_bf16_f32 v8, v12, v13
	v_mul_f32_e32 v13, v13, v13
	v_fmac_f32_e32 v13, v12, v12
	v_mul_f32_e32 v12, v15, v15
	v_fmac_f32_e32 v12, v14, v14
	v_cvt_pk_bf16_f32 v9, v14, v15
	v_add_f32_e32 v12, v13, v12
	v_mul_f32_e32 v13, v17, v17
	v_mul_f32_e32 v14, v19, v19
	v_fmac_f32_e32 v13, v16, v16
	v_fmac_f32_e32 v14, v18, v18
	v_add_f32_e32 v13, v13, v14
	v_add_f32_e32 v12, v12, v13
	v_lshlrev_b32_e32 v13, 16, v64
	v_add_f32_e32 v4, v4, v13
	v_and_b32_e32 v13, 0xffff0000, v64
	v_add_f32_e32 v5, v5, v13
	v_lshlrev_b32_e32 v13, 16, v65
	v_add_f32_e32 v13, v6, v13
	v_and_b32_e32 v6, 0xffff0000, v65
	v_add_f32_e32 v14, v7, v6
	v_lshlrev_b32_e32 v6, 16, v66
	v_add_f32_e32 v15, v0, v6
	v_and_b32_e32 v0, 0xffff0000, v66
	v_cvt_pk_bf16_f32 v10, v16, v17
	v_add_f32_e32 v16, v1, v0
	v_lshlrev_b32_e32 v0, 16, v67
	v_add_f32_e32 v17, v2, v0
	v_and_b32_e32 v0, 0xffff0000, v67
	v_cvt_pk_bf16_f32 v11, v18, v19
	v_add_f32_e32 v18, v3, v0
	v_mul_f32_e32 v0, v5, v5
	v_mul_f32_e32 v1, v14, v14
	v_fmac_f32_e32 v0, v4, v4
	v_fmac_f32_e32 v1, v13, v13
	v_add_f32_e32 v0, v0, v1
	v_mul_f32_e32 v1, v16, v16
	v_mul_f32_e32 v2, v18, v18
	v_fmac_f32_e32 v1, v15, v15
	v_fmac_f32_e32 v2, v17, v17
	v_add_f32_e32 v1, v1, v2
	v_add_f32_e32 v0, v0, v1
	v_add_f32_e32 v3, v12, v0
	v_mov_b32_e32 v12, v3
	s_nop 1
	v_permlane16_swap_b32 v12, v3
	v_lshl_add_u64 v[0:1], s[0:1], 0, v[90:91]
	v_lshl_add_u64 v[6:7], v[152:153], 1, v[0:1]
	global_store_dwordx4 v[6:7], v[8:11], off
	v_cvt_pk_bf16_f32 v2, v4, v5
	s_waitcnt lgkmcnt(0)
	v_add_f32_e32 v0, v3, v12
	v_mov_b32_e32 v1, v0
	s_nop 1
	v_permlane32_swap_b32 v1, v0
	v_cvt_pk_bf16_f32 v3, v13, v14
	v_cvt_pk_bf16_f32 v4, v15, v16
	v_cvt_pk_bf16_f32 v5, v17, v18
	global_store_dwordx4 v[6:7], v[2:5], off offset:256
	s_and_saveexec_b64 s[24:25], s[4:5]
	s_cbranch_execz .LBB0_1665
	s_waitcnt lgkmcnt(0)
	v_add_f32_e32 v2, v0, v1
	s_lshl_b32 s26, s45, 2
	v_lshlrev_b64 v[0:1], 7, v[88:89]
	s_ashr_i32 s27, s26, 31
	v_lshl_add_u64 v[0:1], s[2:3], 0, v[0:1]
	v_lshl_add_u64 v[0:1], s[26:27], 2, v[0:1]
	s_lshl_b32 s8, s42, 2
	v_lshl_add_u64 v[0:1], v[0:1], 0, s[8:9]
	global_store_dword v[0:1], v2, off
	s_branch .LBB0_1665

;     ...
;         G_PAIR(0, 1);
; #pragma unroll 1
;         for (int t = 2; t < nt; t += 2) G_PAIR(t, 0);
.LBB0_1906:
	ds_read_b128 v[134:137], v185
	ds_read_b128 v[138:141], v185 offset:1024
	ds_read_b128 v[142:145], v185 offset:2048
	ds_read_b128 v[146:149], v185 offset:3072
	s_mov_b32 m0, s45
	v_lshl_add_u64 v[150:151], v[128:129], 0, s[24:25]
	ds_read_b128 v[164:167], v186
	ds_read_b128 v[168:171], v186 offset:1024
	ds_read_b128 v[172:175], v186 offset:2048
	ds_read_b128 v[176:179], v186 offset:3072
	ds_read_b128 v[190:193], v186 offset:4096
	ds_read_b128 v[194:197], v186 offset:5120
	ds_read_b128 v[198:201], v186 offset:6144
	ds_read_b128 v[202:205], v186 offset:7168
	global_load_lds_dwordx4 v[150:151], off
	s_mov_b32 m0, s46
	v_lshl_add_u64 v[150:151], v[130:131], 0, s[24:25]
	global_load_lds_dwordx4 v[150:151], off
	s_waitcnt lgkmcnt(8)
	s_barrier
	s_waitcnt lgkmcnt(0)
	v_mfma_f32_16x16x32_bf16 v[116:119], v[134:137], v[164:167], v[116:119]
	s_add_i32 s26, s24, 0xfff50080
	v_mfma_f32_16x16x32_bf16 v[112:115], v[142:145], v[164:167], v[112:115]
	s_cmp_eq_u32 s58, 40
	v_mfma_f32_16x16x32_bf16 v[108:111], v[134:137], v[172:175], v[108:111]
	s_cselect_b32 s59, s19, s21
	v_mfma_f32_16x16x32_bf16 v[104:107], v[142:145], v[172:175], v[104:107]
	s_cselect_b32 s60, s18, s20
	v_mfma_f32_16x16x32_bf16 v[92:95], v[134:137], v[190:193], v[92:95]
	s_cselect_b32 s27, s7, s23
	v_mfma_f32_16x16x32_bf16 v[88:91], v[142:145], v[190:193], v[88:91]
	s_cselect_b32 s61, s6, s22
	v_mfma_f32_16x16x32_bf16 v[76:79], v[134:137], v[198:201], v[76:79]
	v_mfma_f32_16x16x32_bf16 v[72:75], v[142:145], v[198:201], v[72:75]
	v_mfma_f32_16x16x32_bf16 v[116:119], v[138:141], v[168:171], v[116:119]
	v_mfma_f32_16x16x32_bf16 v[112:115], v[146:149], v[168:171], v[112:115]
	v_mfma_f32_16x16x32_bf16 v[108:111], v[138:141], v[176:179], v[108:111]
	v_mfma_f32_16x16x32_bf16 v[104:107], v[146:149], v[176:179], v[104:107]
	v_mfma_f32_16x16x32_bf16 v[92:95], v[138:141], v[194:197], v[92:95]
	v_mfma_f32_16x16x32_bf16 v[88:91], v[146:149], v[194:197], v[88:91]
	v_mfma_f32_16x16x32_bf16 v[76:79], v[138:141], v[202:205], v[76:79]
	v_mfma_f32_16x16x32_bf16 v[72:75], v[146:149], v[202:205], v[72:75]
	s_barrier
	s_cselect_b32 s62, 0, s26
	s_add_u32 s26, s61, s62
	s_addc_u32 s27, s27, 0
	s_mov_b32 m0, s47
	v_lshl_add_u64 v[150:151], s[26:27], 0, v[154:155]
	ds_read_b128 v[206:209], v187
	ds_read_b128 v[210:213], v187 offset:1024
	ds_read_b128 v[214:217], v187 offset:2048
	ds_read_b128 v[222:225], v187 offset:3072
	global_load_lds_dwordx4 v[150:151], off
	s_mov_b32 m0, s48
	v_lshl_add_u64 v[180:181], s[26:27], 0, v[158:159]
	global_load_lds_dwordx4 v[180:181], off
	s_barrier
	s_waitcnt lgkmcnt(0)
	v_mfma_f32_16x16x32_bf16 v[124:127], v[206:209], v[164:167], v[124:127]
	v_mfma_f32_16x16x32_bf16 v[120:123], v[214:217], v[164:167], v[120:123]
	v_mfma_f32_16x16x32_bf16 v[100:103], v[206:209], v[172:175], v[100:103]
	v_mfma_f32_16x16x32_bf16 v[96:99], v[214:217], v[172:175], v[96:99]
	v_mfma_f32_16x16x32_bf16 v[84:87], v[206:209], v[190:193], v[84:87]
	v_mfma_f32_16x16x32_bf16 v[80:83], v[214:217], v[190:193], v[80:83]
	v_mfma_f32_16x16x32_bf16 v[68:71], v[206:209], v[198:201], v[68:71]
	v_mfma_f32_16x16x32_bf16 v[64:67], v[214:217], v[198:201], v[64:67]
	v_mfma_f32_16x16x32_bf16 v[124:127], v[210:213], v[168:171], v[124:127]
	v_mfma_f32_16x16x32_bf16 v[120:123], v[222:225], v[168:171], v[120:123]
	v_mfma_f32_16x16x32_bf16 v[100:103], v[210:213], v[176:179], v[100:103]
	v_mfma_f32_16x16x32_bf16 v[96:99], v[222:225], v[176:179], v[96:99]
	v_mfma_f32_16x16x32_bf16 v[84:87], v[210:213], v[194:197], v[84:87]
	v_mfma_f32_16x16x32_bf16 v[80:83], v[222:225], v[194:197], v[80:83]
	v_mfma_f32_16x16x32_bf16 v[68:71], v[210:213], v[202:205], v[68:71]
	v_mfma_f32_16x16x32_bf16 v[64:67], v[222:225], v[202:205], v[64:67]
	s_add_u32 s60, s60, s62
	s_addc_u32 s61, s59, 0
	s_mov_b32 m0, s37
	v_lshl_add_u64 v[218:219], s[60:61], 0, v[152:153]
	s_barrier
	ds_read_b128 v[164:167], v186 offset:16384
	ds_read_b128 v[168:171], v186 offset:17408
	ds_read_b128 v[172:175], v186 offset:18432
	ds_read_b128 v[176:179], v186 offset:19456
	ds_read_b128 v[190:193], v186 offset:20480
	ds_read_b128 v[194:197], v186 offset:21504
	ds_read_b128 v[198:201], v186 offset:22528
	ds_read_b128 v[202:205], v186 offset:23552
	global_load_lds_dwordx4 v[218:219], off
	s_mov_b32 m0, s38
	v_lshl_add_u64 v[226:227], s[60:61], 0, v[156:157]
	global_load_lds_dwordx4 v[226:227], off
	s_barrier
	s_waitcnt lgkmcnt(0)
	v_mfma_f32_16x16x32_bf16 v[52:55], v[134:137], v[164:167], v[52:55]
	v_mfma_f32_16x16x32_bf16 v[48:51], v[142:145], v[164:167], v[48:51]
	v_mfma_f32_16x16x32_bf16 v[44:47], v[134:137], v[172:175], v[44:47]
	v_mfma_f32_16x16x32_bf16 v[36:39], v[142:145], v[172:175], v[36:39]
	v_mfma_f32_16x16x32_bf16 v[28:31], v[134:137], v[190:193], v[28:31]
	v_mfma_f32_16x16x32_bf16 v[20:23], v[142:145], v[190:193], v[20:23]
	v_mfma_f32_16x16x32_bf16 v[12:15], v[134:137], v[198:201], v[12:15]
	v_mfma_f32_16x16x32_bf16 v[4:7], v[142:145], v[198:201], v[4:7]
	v_mfma_f32_16x16x32_bf16 v[52:55], v[138:141], v[168:171], v[52:55]
	v_mfma_f32_16x16x32_bf16 v[48:51], v[146:149], v[168:171], v[48:51]
	v_mfma_f32_16x16x32_bf16 v[44:47], v[138:141], v[176:179], v[44:47]
	v_mfma_f32_16x16x32_bf16 v[36:39], v[146:149], v[176:179], v[36:39]
	v_mfma_f32_16x16x32_bf16 v[28:31], v[138:141], v[194:197], v[28:31]
	v_mfma_f32_16x16x32_bf16 v[20:23], v[146:149], v[194:197], v[20:23]
	v_mfma_f32_16x16x32_bf16 v[12:15], v[138:141], v[202:205], v[12:15]
	v_mfma_f32_16x16x32_bf16 v[4:7], v[146:149], v[202:205], v[4:7]
	s_barrier
	s_add_u32 s62, s26, 0xb0000
	s_addc_u32 s63, s27, 0
	s_mov_b32 m0, s52
	v_lshl_add_u64 v[134:135], s[62:63], 0, v[154:155]
	global_load_lds_dwordx4 v[134:135], off
	s_mov_b32 m0, s53
	v_lshl_add_u64 v[134:135], s[62:63], 0, v[158:159]
	global_load_lds_dwordx4 v[134:135], off
	s_waitcnt vmcnt(6)
	s_barrier
	v_mfma_f32_16x16x32_bf16 v[60:63], v[206:209], v[164:167], v[60:63]
	v_mfma_f32_16x16x32_bf16 v[56:59], v[214:217], v[164:167], v[56:59]
	v_mfma_f32_16x16x32_bf16 v[40:43], v[206:209], v[172:175], v[40:43]
	v_mfma_f32_16x16x32_bf16 v[32:35], v[214:217], v[172:175], v[32:35]
	v_mfma_f32_16x16x32_bf16 v[24:27], v[206:209], v[190:193], v[24:27]
	v_mfma_f32_16x16x32_bf16 v[16:19], v[214:217], v[190:193], v[16:19]
	v_mfma_f32_16x16x32_bf16 v[8:11], v[206:209], v[198:201], v[8:11]
	v_mfma_f32_16x16x32_bf16 v[0:3], v[214:217], v[198:201], v[0:3]
	v_mfma_f32_16x16x32_bf16 v[60:63], v[210:213], v[168:171], v[60:63]
	v_mfma_f32_16x16x32_bf16 v[56:59], v[222:225], v[168:171], v[56:59]
	v_mfma_f32_16x16x32_bf16 v[40:43], v[210:213], v[176:179], v[40:43]
	v_mfma_f32_16x16x32_bf16 v[32:35], v[222:225], v[176:179], v[32:35]
	v_mfma_f32_16x16x32_bf16 v[24:27], v[210:213], v[194:197], v[24:27]
	v_mfma_f32_16x16x32_bf16 v[16:19], v[222:225], v[194:197], v[16:19]
	v_mfma_f32_16x16x32_bf16 v[8:11], v[210:213], v[202:205], v[8:11]
	v_mfma_f32_16x16x32_bf16 v[0:3], v[222:225], v[202:205], v[0:3]
	s_barrier
	ds_read_b128 v[134:137], v132
	ds_read_b128 v[138:141], v132 offset:1024
	ds_read_b128 v[142:145], v132 offset:2048
	ds_read_b128 v[146:149], v132 offset:3072
	s_add_u32 s60, s60, 0xb0000
	s_addc_u32 s61, s61, 0
	s_mov_b32 m0, s39
	v_lshl_add_u64 v[206:207], s[60:61], 0, v[152:153]
	ds_read_b128 v[164:167], v186 offset:32768
	ds_read_b128 v[168:171], v186 offset:33792
	ds_read_b128 v[172:175], v186 offset:34816
	ds_read_b128 v[176:179], v186 offset:35840
	ds_read_b128 v[190:193], v186 offset:36864
	ds_read_b128 v[194:197], v186 offset:37888
	ds_read_b128 v[198:201], v186 offset:38912
	ds_read_b128 v[202:205], v186 offset:39936
	global_load_lds_dwordx4 v[206:207], off
	s_mov_b32 m0, s40
	v_lshl_add_u64 v[206:207], s[60:61], 0, v[156:157]
	global_load_lds_dwordx4 v[206:207], off
	s_waitcnt lgkmcnt(8)
	s_barrier
	s_waitcnt lgkmcnt(0)
	v_mfma_f32_16x16x32_bf16 v[116:119], v[134:137], v[164:167], v[116:119]
	v_mfma_f32_16x16x32_bf16 v[112:115], v[142:145], v[164:167], v[112:115]
	v_mfma_f32_16x16x32_bf16 v[108:111], v[134:137], v[172:175], v[108:111]
	v_mfma_f32_16x16x32_bf16 v[104:107], v[142:145], v[172:175], v[104:107]
	v_mfma_f32_16x16x32_bf16 v[92:95], v[134:137], v[190:193], v[92:95]
	v_mfma_f32_16x16x32_bf16 v[88:91], v[142:145], v[190:193], v[88:91]
	v_mfma_f32_16x16x32_bf16 v[76:79], v[134:137], v[198:201], v[76:79]
	v_mfma_f32_16x16x32_bf16 v[72:75], v[142:145], v[198:201], v[72:75]
	v_mfma_f32_16x16x32_bf16 v[116:119], v[138:141], v[168:171], v[116:119]
	v_mfma_f32_16x16x32_bf16 v[112:115], v[146:149], v[168:171], v[112:115]
	v_mfma_f32_16x16x32_bf16 v[108:111], v[138:141], v[176:179], v[108:111]
	v_mfma_f32_16x16x32_bf16 v[104:107], v[146:149], v[176:179], v[104:107]
	v_mfma_f32_16x16x32_bf16 v[92:95], v[138:141], v[194:197], v[92:95]
	v_mfma_f32_16x16x32_bf16 v[88:91], v[146:149], v[194:197], v[88:91]
	v_mfma_f32_16x16x32_bf16 v[76:79], v[138:141], v[202:205], v[76:79]
	v_mfma_f32_16x16x32_bf16 v[72:75], v[146:149], v[202:205], v[72:75]
	s_barrier
	s_mov_b32 m0, s54
	v_lshl_add_u64 v[150:151], v[150:151], 0, s[10:11]
	ds_read_b128 v[206:209], v133
	ds_read_b128 v[210:213], v133 offset:1024
	ds_read_b128 v[214:217], v133 offset:2048
	ds_read_b128 v[222:225], v133 offset:3072
	global_load_lds_dwordx4 v[150:151], off
	s_mov_b32 m0, s55
	v_lshl_add_u64 v[150:151], v[180:181], 0, s[10:11]
	global_load_lds_dwordx4 v[150:151], off
	s_barrier
	s_waitcnt lgkmcnt(0)
	v_mfma_f32_16x16x32_bf16 v[124:127], v[206:209], v[164:167], v[124:127]
	v_mfma_f32_16x16x32_bf16 v[120:123], v[214:217], v[164:167], v[120:123]
	v_mfma_f32_16x16x32_bf16 v[100:103], v[206:209], v[172:175], v[100:103]
	v_mfma_f32_16x16x32_bf16 v[96:99], v[214:217], v[172:175], v[96:99]
	v_mfma_f32_16x16x32_bf16 v[84:87], v[206:209], v[190:193], v[84:87]
	v_mfma_f32_16x16x32_bf16 v[80:83], v[214:217], v[190:193], v[80:83]
	v_mfma_f32_16x16x32_bf16 v[68:71], v[206:209], v[198:201], v[68:71]
	v_mfma_f32_16x16x32_bf16 v[64:67], v[214:217], v[198:201], v[64:67]
	v_mfma_f32_16x16x32_bf16 v[124:127], v[210:213], v[168:171], v[124:127]
	v_mfma_f32_16x16x32_bf16 v[120:123], v[222:225], v[168:171], v[120:123]
	v_mfma_f32_16x16x32_bf16 v[100:103], v[210:213], v[176:179], v[100:103]
	v_mfma_f32_16x16x32_bf16 v[96:99], v[222:225], v[176:179], v[96:99]
	v_mfma_f32_16x16x32_bf16 v[84:87], v[210:213], v[194:197], v[84:87]
	v_mfma_f32_16x16x32_bf16 v[80:83], v[222:225], v[194:197], v[80:83]
	v_mfma_f32_16x16x32_bf16 v[68:71], v[210:213], v[202:205], v[68:71]
	v_mfma_f32_16x16x32_bf16 v[64:67], v[222:225], v[202:205], v[64:67]
	s_mov_b32 m0, s42
	v_lshl_add_u64 v[150:151], v[218:219], 0, s[10:11]
	s_barrier
	ds_read_b128 v[164:167], v186 offset:49152
	ds_read_b128 v[168:171], v186 offset:50176
	ds_read_b128 v[172:175], v186 offset:51200
	ds_read_b128 v[176:179], v186 offset:52224
	ds_read_b128 v[190:193], v186 offset:53248
	ds_read_b128 v[194:197], v186 offset:54272
	ds_read_b128 v[198:201], v186 offset:55296
	ds_read_b128 v[202:205], v186 offset:56320
	global_load_lds_dwordx4 v[150:151], off
	s_mov_b32 m0, s43
	v_lshl_add_u64 v[150:151], v[226:227], 0, s[10:11]
	global_load_lds_dwordx4 v[150:151], off
	s_barrier
;     ...
;         G_PAIR(0, 1);
; #pragma unroll 1
;         for (int t = 2; t < nt; t += 2) G_PAIR(t, 0);
	s_waitcnt lgkmcnt(0)
	v_mfma_f32_16x16x32_bf16 v[52:55], v[134:137], v[164:167], v[52:55]
	v_mfma_f32_16x16x32_bf16 v[48:51], v[142:145], v[164:167], v[48:51]
	v_mfma_f32_16x16x32_bf16 v[44:47], v[134:137], v[172:175], v[44:47]
	v_mfma_f32_16x16x32_bf16 v[36:39], v[142:145], v[172:175], v[36:39]
	v_mfma_f32_16x16x32_bf16 v[28:31], v[134:137], v[190:193], v[28:31]
	v_mfma_f32_16x16x32_bf16 v[20:23], v[142:145], v[190:193], v[20:23]
	v_mfma_f32_16x16x32_bf16 v[12:15], v[134:137], v[198:201], v[12:15]
	v_mfma_f32_16x16x32_bf16 v[4:7], v[142:145], v[198:201], v[4:7]
	v_mfma_f32_16x16x32_bf16 v[52:55], v[138:141], v[168:171], v[52:55]
	v_mfma_f32_16x16x32_bf16 v[48:51], v[146:149], v[168:171], v[48:51]
	v_mfma_f32_16x16x32_bf16 v[44:47], v[138:141], v[176:179], v[44:47]
	v_mfma_f32_16x16x32_bf16 v[36:39], v[146:149], v[176:179], v[36:39]
	v_mfma_f32_16x16x32_bf16 v[28:31], v[138:141], v[194:197], v[28:31]
	v_mfma_f32_16x16x32_bf16 v[20:23], v[146:149], v[194:197], v[20:23]
	v_mfma_f32_16x16x32_bf16 v[12:15], v[138:141], v[202:205], v[12:15]
	v_mfma_f32_16x16x32_bf16 v[4:7], v[146:149], v[202:205], v[4:7]
	s_barrier
	s_add_u32 s26, s26, 0xb0080
	s_addc_u32 s27, s27, 0
	s_mov_b32 m0, s56
	v_lshl_add_u64 v[134:135], s[26:27], 0, v[154:155]
	global_load_lds_dwordx4 v[134:135], off
	s_mov_b32 m0, s57
	v_lshl_add_u64 v[134:135], s[26:27], 0, v[158:159]
	global_load_lds_dwordx4 v[134:135], off
	s_waitcnt vmcnt(6)
	s_barrier
	v_mfma_f32_16x16x32_bf16 v[60:63], v[206:209], v[164:167], v[60:63]
	v_mfma_f32_16x16x32_bf16 v[56:59], v[214:217], v[164:167], v[56:59]
	v_mfma_f32_16x16x32_bf16 v[40:43], v[206:209], v[172:175], v[40:43]
	v_mfma_f32_16x16x32_bf16 v[32:35], v[214:217], v[172:175], v[32:35]
	v_mfma_f32_16x16x32_bf16 v[24:27], v[206:209], v[190:193], v[24:27]
	v_mfma_f32_16x16x32_bf16 v[16:19], v[214:217], v[190:193], v[16:19]
	v_mfma_f32_16x16x32_bf16 v[8:11], v[206:209], v[198:201], v[8:11]
	v_mfma_f32_16x16x32_bf16 v[0:3], v[214:217], v[198:201], v[0:3]
	v_mfma_f32_16x16x32_bf16 v[60:63], v[210:213], v[168:171], v[60:63]
	v_mfma_f32_16x16x32_bf16 v[56:59], v[222:225], v[168:171], v[56:59]
	v_mfma_f32_16x16x32_bf16 v[40:43], v[210:213], v[176:179], v[40:43]
	v_mfma_f32_16x16x32_bf16 v[32:35], v[222:225], v[176:179], v[32:35]
	v_mfma_f32_16x16x32_bf16 v[24:27], v[210:213], v[194:197], v[24:27]
	v_mfma_f32_16x16x32_bf16 v[16:19], v[222:225], v[194:197], v[16:19]
	v_mfma_f32_16x16x32_bf16 v[8:11], v[210:213], v[202:205], v[8:11]
	v_mfma_f32_16x16x32_bf16 v[0:3], v[222:225], v[202:205], v[0:3]
	s_add_i32 s58, s58, 2
	s_add_u32 s24, s24, 0x100
	s_addc_u32 s25, s25, 0
	s_cmp_gt_u32 s58, 39
	s_cbranch_scc0 .Lrot_1906
	s_barrier
	ds_read_b128 v[134:137], v185
	ds_read_b128 v[138:141], v185 offset:1024
	ds_read_b128 v[142:145], v185 offset:2048
	ds_read_b128 v[146:149], v185 offset:3072
	s_mov_b32 m0, s45
	v_lshl_add_u64 v[150:151], v[128:129], 0, s[24:25]
	ds_read_b128 v[164:167], v186
	ds_read_b128 v[168:171], v186 offset:1024
	ds_read_b128 v[172:175], v186 offset:2048
	ds_read_b128 v[176:179], v186 offset:3072
	ds_read_b128 v[190:193], v186 offset:4096
	ds_read_b128 v[194:197], v186 offset:5120
	ds_read_b128 v[198:201], v186 offset:6144
	ds_read_b128 v[202:205], v186 offset:7168
	global_load_lds_dwordx4 v[150:151], off
	s_mov_b32 m0, s46
	v_lshl_add_u64 v[150:151], v[130:131], 0, s[24:25]
	global_load_lds_dwordx4 v[150:151], off
	s_waitcnt lgkmcnt(8)
	s_barrier
	s_waitcnt lgkmcnt(0)
	v_mfma_f32_16x16x32_bf16 v[116:119], v[134:137], v[164:167], v[116:119]
	s_add_i32 s26, s24, 0xfff50080
	v_mfma_f32_16x16x32_bf16 v[112:115], v[142:145], v[164:167], v[112:115]
	s_cmp_eq_u32 s58, 40
	v_mfma_f32_16x16x32_bf16 v[108:111], v[134:137], v[172:175], v[108:111]
	s_cselect_b32 s59, s19, s21
	v_mfma_f32_16x16x32_bf16 v[104:107], v[142:145], v[172:175], v[104:107]
	s_cselect_b32 s60, s18, s20
	v_mfma_f32_16x16x32_bf16 v[92:95], v[134:137], v[190:193], v[92:95]
	s_cselect_b32 s27, s7, s23
	v_mfma_f32_16x16x32_bf16 v[88:91], v[142:145], v[190:193], v[88:91]
	s_cselect_b32 s61, s6, s22
	v_mfma_f32_16x16x32_bf16 v[76:79], v[134:137], v[198:201], v[76:79]
	v_mfma_f32_16x16x32_bf16 v[72:75], v[142:145], v[198:201], v[72:75]
	v_mfma_f32_16x16x32_bf16 v[116:119], v[138:141], v[168:171], v[116:119]
	v_mfma_f32_16x16x32_bf16 v[112:115], v[146:149], v[168:171], v[112:115]
	v_mfma_f32_16x16x32_bf16 v[108:111], v[138:141], v[176:179], v[108:111]
	v_mfma_f32_16x16x32_bf16 v[104:107], v[146:149], v[176:179], v[104:107]
	v_mfma_f32_16x16x32_bf16 v[92:95], v[138:141], v[194:197], v[92:95]
	v_mfma_f32_16x16x32_bf16 v[88:91], v[146:149], v[194:197], v[88:91]
	v_mfma_f32_16x16x32_bf16 v[76:79], v[138:141], v[202:205], v[76:79]
	v_mfma_f32_16x16x32_bf16 v[72:75], v[146:149], v[202:205], v[72:75]
	s_barrier
	s_cselect_b32 s62, 0, s26
	s_add_u32 s26, s61, s62
	s_addc_u32 s27, s27, 0
	s_mov_b32 m0, s47
	v_lshl_add_u64 v[150:151], s[26:27], 0, v[154:155]
	ds_read_b128 v[206:209], v187
	ds_read_b128 v[210:213], v187 offset:1024
	ds_read_b128 v[214:217], v187 offset:2048
	ds_read_b128 v[222:225], v187 offset:3072
	global_load_lds_dwordx4 v[150:151], off
	s_mov_b32 m0, s48
	v_lshl_add_u64 v[180:181], s[26:27], 0, v[158:159]
	global_load_lds_dwordx4 v[180:181], off
	s_barrier
;     __device__ __forceinline__ void epi(const f32x4 (&acc)[2][2][4][2], const Unit& u, int wr, int wc, int fr, int fq) const {
;     ...
;                 for (int bj = 0; bj < 2; ++bj) xo[m][bj] = *(const u32x4*)(xb + (size_t)(row0 + ai * 128 + m * 16) * D + col0 + bj * 128);
	s_waitcnt lgkmcnt(0)
	v_mfma_f32_16x16x32_bf16 v[124:127], v[206:209], v[164:167], v[124:127]
	v_mfma_f32_16x16x32_bf16 v[120:123], v[214:217], v[164:167], v[120:123]
	v_mfma_f32_16x16x32_bf16 v[100:103], v[206:209], v[172:175], v[100:103]
	v_mfma_f32_16x16x32_bf16 v[96:99], v[214:217], v[172:175], v[96:99]
	v_mfma_f32_16x16x32_bf16 v[84:87], v[206:209], v[190:193], v[84:87]
	v_mfma_f32_16x16x32_bf16 v[80:83], v[214:217], v[190:193], v[80:83]
	v_mfma_f32_16x16x32_bf16 v[68:71], v[206:209], v[198:201], v[68:71]
	v_mfma_f32_16x16x32_bf16 v[64:67], v[214:217], v[198:201], v[64:67]
	v_mfma_f32_16x16x32_bf16 v[124:127], v[210:213], v[168:171], v[124:127]
	v_mfma_f32_16x16x32_bf16 v[120:123], v[222:225], v[168:171], v[120:123]
	v_mfma_f32_16x16x32_bf16 v[100:103], v[210:213], v[176:179], v[100:103]
	v_mfma_f32_16x16x32_bf16 v[96:99], v[222:225], v[176:179], v[96:99]
	v_mfma_f32_16x16x32_bf16 v[84:87], v[210:213], v[194:197], v[84:87]
	v_mfma_f32_16x16x32_bf16 v[80:83], v[222:225], v[194:197], v[80:83]
	v_mfma_f32_16x16x32_bf16 v[68:71], v[210:213], v[202:205], v[68:71]
	v_mfma_f32_16x16x32_bf16 v[64:67], v[222:225], v[202:205], v[64:67]
	s_add_u32 s60, s60, s62
	s_addc_u32 s61, s59, 0
	s_mov_b32 m0, s37
	v_lshl_add_u64 v[218:219], s[60:61], 0, v[152:153]
	s_barrier
	ds_read_b128 v[164:167], v186 offset:16384
	ds_read_b128 v[168:171], v186 offset:17408
	ds_read_b128 v[172:175], v186 offset:18432
	ds_read_b128 v[176:179], v186 offset:19456
	ds_read_b128 v[190:193], v186 offset:20480
	ds_read_b128 v[194:197], v186 offset:21504
	ds_read_b128 v[198:201], v186 offset:22528
	ds_read_b128 v[202:205], v186 offset:23552
	global_load_lds_dwordx4 v[218:219], off
	s_mov_b32 m0, s38
	v_lshl_add_u64 v[226:227], s[60:61], 0, v[156:157]
	global_load_lds_dwordx4 v[226:227], off
	s_barrier
	s_waitcnt lgkmcnt(0)
	v_mfma_f32_16x16x32_bf16 v[52:55], v[134:137], v[164:167], v[52:55]
	v_mfma_f32_16x16x32_bf16 v[48:51], v[142:145], v[164:167], v[48:51]
	v_mfma_f32_16x16x32_bf16 v[44:47], v[134:137], v[172:175], v[44:47]
	v_mfma_f32_16x16x32_bf16 v[36:39], v[142:145], v[172:175], v[36:39]
	v_mfma_f32_16x16x32_bf16 v[28:31], v[134:137], v[190:193], v[28:31]
	v_mfma_f32_16x16x32_bf16 v[20:23], v[142:145], v[190:193], v[20:23]
	v_mfma_f32_16x16x32_bf16 v[12:15], v[134:137], v[198:201], v[12:15]
	v_mfma_f32_16x16x32_bf16 v[4:7], v[142:145], v[198:201], v[4:7]
	v_mfma_f32_16x16x32_bf16 v[52:55], v[138:141], v[168:171], v[52:55]
	v_mfma_f32_16x16x32_bf16 v[48:51], v[146:149], v[168:171], v[48:51]
	v_mfma_f32_16x16x32_bf16 v[44:47], v[138:141], v[176:179], v[44:47]
	v_mfma_f32_16x16x32_bf16 v[36:39], v[146:149], v[176:179], v[36:39]
	v_mfma_f32_16x16x32_bf16 v[28:31], v[138:141], v[194:197], v[28:31]
	v_mfma_f32_16x16x32_bf16 v[20:23], v[146:149], v[194:197], v[20:23]
	v_mfma_f32_16x16x32_bf16 v[12:15], v[138:141], v[202:205], v[12:15]
	v_mfma_f32_16x16x32_bf16 v[4:7], v[146:149], v[202:205], v[4:7]
	s_barrier
	s_add_u32 s62, s26, 0xb0000
	s_addc_u32 s63, s27, 0
	s_mov_b32 m0, s52
	v_lshl_add_u64 v[134:135], s[62:63], 0, v[154:155]
	global_load_lds_dwordx4 v[134:135], off
	s_mov_b32 m0, s53
	v_lshl_add_u64 v[134:135], s[62:63], 0, v[158:159]
	global_load_lds_dwordx4 v[134:135], off
	s_waitcnt vmcnt(6)
	s_barrier
	v_mfma_f32_16x16x32_bf16 v[60:63], v[206:209], v[164:167], v[60:63]
	v_lshl_or_b32 v248, s30, 8, v184
	v_mfma_f32_16x16x32_bf16 v[56:59], v[214:217], v[164:167], v[56:59]
	v_lshl_add_u32 v250, s2, 8, v182
	v_mfma_f32_16x16x32_bf16 v[40:43], v[206:209], v[172:175], v[40:43]
	v_ashrrev_i32_e32 v249, 31, v248
	v_mfma_f32_16x16x32_bf16 v[32:35], v[214:217], v[172:175], v[32:35]
	v_lshlrev_b64 v[248:249], 1, v[248:249]
	v_mfma_f32_16x16x32_bf16 v[24:27], v[206:209], v[190:193], v[24:27]
	v_ashrrev_i32_e32 v251, 31, v250
	v_mfma_f32_16x16x32_bf16 v[16:19], v[214:217], v[190:193], v[16:19]
	v_lshl_add_u64 v[248:249], s[0:1], 0, v[248:249]
	v_mfma_f32_16x16x32_bf16 v[8:11], v[206:209], v[198:201], v[8:11]
	v_lshlrev_b64 v[250:251], 11, v[250:251]
	v_mfma_f32_16x16x32_bf16 v[0:3], v[214:217], v[198:201], v[0:3]
	v_lshl_add_u64 v[252:253], v[248:249], 0, v[250:251]
	v_mfma_f32_16x16x32_bf16 v[60:63], v[210:213], v[168:171], v[60:63]
	global_load_dwordx4 v[232:235], v[252:253], off
	v_mfma_f32_16x16x32_bf16 v[56:59], v[222:225], v[168:171], v[56:59]
	global_load_dwordx4 v[236:239], v[252:253], off offset:256
	v_mfma_f32_16x16x32_bf16 v[40:43], v[210:213], v[176:179], v[40:43]
	v_mov_b32_e32 v250, 0x8000
	v_mfma_f32_16x16x32_bf16 v[32:35], v[222:225], v[176:179], v[32:35]
	v_mov_b32_e32 v251, 0
	v_mfma_f32_16x16x32_bf16 v[24:27], v[210:213], v[194:197], v[24:27]
	v_lshl_add_u64 v[250:251], v[252:253], 0, v[250:251]
	v_mfma_f32_16x16x32_bf16 v[16:19], v[222:225], v[194:197], v[16:19]
	global_load_dwordx4 v[240:243], v[250:251], off
	v_mfma_f32_16x16x32_bf16 v[8:11], v[210:213], v[202:205], v[8:11]
	global_load_dwordx4 v[244:247], v[250:251], off offset:256
	v_mfma_f32_16x16x32_bf16 v[0:3], v[222:225], v[202:205], v[0:3]
	s_barrier
	ds_read_b128 v[134:137], v132
	ds_read_b128 v[138:141], v132 offset:1024
	ds_read_b128 v[142:145], v132 offset:2048
	ds_read_b128 v[146:149], v132 offset:3072
	s_add_u32 s60, s60, 0xb0000
	s_addc_u32 s61, s61, 0
	s_mov_b32 m0, s39
	v_lshl_add_u64 v[206:207], s[60:61], 0, v[152:153]
	ds_read_b128 v[164:167], v186 offset:32768
	ds_read_b128 v[168:171], v186 offset:33792
	ds_read_b128 v[172:175], v186 offset:34816
	ds_read_b128 v[176:179], v186 offset:35840
	ds_read_b128 v[190:193], v186 offset:36864
	ds_read_b128 v[194:197], v186 offset:37888
	ds_read_b128 v[198:201], v186 offset:38912
	ds_read_b128 v[202:205], v186 offset:39936
	global_load_lds_dwordx4 v[206:207], off
	s_mov_b32 m0, s40
	v_lshl_add_u64 v[206:207], s[60:61], 0, v[156:157]
	global_load_lds_dwordx4 v[206:207], off
	s_waitcnt lgkmcnt(8)
	s_barrier
;     ...
;         G_PAIR(0, 1);
; #pragma unroll 1
;         for (int t = 2; t < nt; t += 2) G_PAIR(t, 0);
	s_waitcnt lgkmcnt(0)
	v_mfma_f32_16x16x32_bf16 v[116:119], v[134:137], v[164:167], v[116:119]
	v_mfma_f32_16x16x32_bf16 v[112:115], v[142:145], v[164:167], v[112:115]
	v_mfma_f32_16x16x32_bf16 v[108:111], v[134:137], v[172:175], v[108:111]
	v_mfma_f32_16x16x32_bf16 v[104:107], v[142:145], v[172:175], v[104:107]
	v_mfma_f32_16x16x32_bf16 v[92:95], v[134:137], v[190:193], v[92:95]
	v_mfma_f32_16x16x32_bf16 v[88:91], v[142:145], v[190:193], v[88:91]
	v_mfma_f32_16x16x32_bf16 v[76:79], v[134:137], v[198:201], v[76:79]
	v_mfma_f32_16x16x32_bf16 v[72:75], v[142:145], v[198:201], v[72:75]
	v_mfma_f32_16x16x32_bf16 v[116:119], v[138:141], v[168:171], v[116:119]
	v_mfma_f32_16x16x32_bf16 v[112:115], v[146:149], v[168:171], v[112:115]
	v_mfma_f32_16x16x32_bf16 v[108:111], v[138:141], v[176:179], v[108:111]
	v_mfma_f32_16x16x32_bf16 v[104:107], v[146:149], v[176:179], v[104:107]
	v_mfma_f32_16x16x32_bf16 v[92:95], v[138:141], v[194:197], v[92:95]
	v_mfma_f32_16x16x32_bf16 v[88:91], v[146:149], v[194:197], v[88:91]
	v_mfma_f32_16x16x32_bf16 v[76:79], v[138:141], v[202:205], v[76:79]
	v_mfma_f32_16x16x32_bf16 v[72:75], v[146:149], v[202:205], v[72:75]
	s_barrier
	s_mov_b32 m0, s54
	v_lshl_add_u64 v[150:151], v[150:151], 0, s[10:11]
	ds_read_b128 v[206:209], v133
	ds_read_b128 v[210:213], v133 offset:1024
	ds_read_b128 v[214:217], v133 offset:2048
	ds_read_b128 v[222:225], v133 offset:3072
	global_load_lds_dwordx4 v[150:151], off
	s_mov_b32 m0, s55
	v_lshl_add_u64 v[150:151], v[180:181], 0, s[10:11]
	global_load_lds_dwordx4 v[150:151], off
	s_barrier
	s_waitcnt lgkmcnt(0)
	v_mfma_f32_16x16x32_bf16 v[124:127], v[206:209], v[164:167], v[124:127]
	v_mfma_f32_16x16x32_bf16 v[120:123], v[214:217], v[164:167], v[120:123]
	v_mfma_f32_16x16x32_bf16 v[100:103], v[206:209], v[172:175], v[100:103]
	v_mfma_f32_16x16x32_bf16 v[96:99], v[214:217], v[172:175], v[96:99]
	v_mfma_f32_16x16x32_bf16 v[84:87], v[206:209], v[190:193], v[84:87]
	v_mfma_f32_16x16x32_bf16 v[80:83], v[214:217], v[190:193], v[80:83]
	v_mfma_f32_16x16x32_bf16 v[68:71], v[206:209], v[198:201], v[68:71]
	v_mfma_f32_16x16x32_bf16 v[64:67], v[214:217], v[198:201], v[64:67]
	v_mfma_f32_16x16x32_bf16 v[124:127], v[210:213], v[168:171], v[124:127]
	v_mfma_f32_16x16x32_bf16 v[120:123], v[222:225], v[168:171], v[120:123]
	v_mfma_f32_16x16x32_bf16 v[100:103], v[210:213], v[176:179], v[100:103]
	v_mfma_f32_16x16x32_bf16 v[96:99], v[222:225], v[176:179], v[96:99]
	v_mfma_f32_16x16x32_bf16 v[84:87], v[210:213], v[194:197], v[84:87]
	v_mfma_f32_16x16x32_bf16 v[80:83], v[222:225], v[194:197], v[80:83]
	v_mfma_f32_16x16x32_bf16 v[68:71], v[210:213], v[202:205], v[68:71]
	v_mfma_f32_16x16x32_bf16 v[64:67], v[222:225], v[202:205], v[64:67]
	s_mov_b32 m0, s42
	v_lshl_add_u64 v[150:151], v[218:219], 0, s[10:11]
	s_barrier
	ds_read_b128 v[164:167], v186 offset:49152
	ds_read_b128 v[168:171], v186 offset:50176
	ds_read_b128 v[172:175], v186 offset:51200
	ds_read_b128 v[176:179], v186 offset:52224
	ds_read_b128 v[190:193], v186 offset:53248
	ds_read_b128 v[194:197], v186 offset:54272
	ds_read_b128 v[198:201], v186 offset:55296
	ds_read_b128 v[202:205], v186 offset:56320
	global_load_lds_dwordx4 v[150:151], off
	s_mov_b32 m0, s43
	v_lshl_add_u64 v[150:151], v[226:227], 0, s[10:11]
	global_load_lds_dwordx4 v[150:151], off
	s_barrier
	s_waitcnt lgkmcnt(0)
	v_mfma_f32_16x16x32_bf16 v[52:55], v[134:137], v[164:167], v[52:55]
	v_mfma_f32_16x16x32_bf16 v[48:51], v[142:145], v[164:167], v[48:51]
	v_mfma_f32_16x16x32_bf16 v[44:47], v[134:137], v[172:175], v[44:47]
	v_mfma_f32_16x16x32_bf16 v[36:39], v[142:145], v[172:175], v[36:39]
	v_mfma_f32_16x16x32_bf16 v[28:31], v[134:137], v[190:193], v[28:31]
	v_mfma_f32_16x16x32_bf16 v[20:23], v[142:145], v[190:193], v[20:23]
	v_mfma_f32_16x16x32_bf16 v[12:15], v[134:137], v[198:201], v[12:15]
	v_mfma_f32_16x16x32_bf16 v[4:7], v[142:145], v[198:201], v[4:7]
	v_mfma_f32_16x16x32_bf16 v[52:55], v[138:141], v[168:171], v[52:55]
	v_mfma_f32_16x16x32_bf16 v[48:51], v[146:149], v[168:171], v[48:51]
	v_mfma_f32_16x16x32_bf16 v[44:47], v[138:141], v[176:179], v[44:47]
	v_mfma_f32_16x16x32_bf16 v[36:39], v[146:149], v[176:179], v[36:39]
	v_mfma_f32_16x16x32_bf16 v[28:31], v[138:141], v[194:197], v[28:31]
	v_mfma_f32_16x16x32_bf16 v[20:23], v[146:149], v[194:197], v[20:23]
	v_mfma_f32_16x16x32_bf16 v[12:15], v[138:141], v[202:205], v[12:15]
	v_mfma_f32_16x16x32_bf16 v[4:7], v[146:149], v[202:205], v[4:7]
	s_barrier
	s_add_u32 s26, s26, 0xb0080
	s_addc_u32 s27, s27, 0
	s_mov_b32 m0, s56
	v_lshl_add_u64 v[134:135], s[26:27], 0, v[154:155]
	global_load_lds_dwordx4 v[134:135], off
	s_mov_b32 m0, s57
	v_lshl_add_u64 v[134:135], s[26:27], 0, v[158:159]
	global_load_lds_dwordx4 v[134:135], off
	s_waitcnt vmcnt(6)
	s_barrier
	v_mfma_f32_16x16x32_bf16 v[60:63], v[206:209], v[164:167], v[60:63]
	v_mfma_f32_16x16x32_bf16 v[56:59], v[214:217], v[164:167], v[56:59]
	v_mfma_f32_16x16x32_bf16 v[40:43], v[206:209], v[172:175], v[40:43]
	v_mfma_f32_16x16x32_bf16 v[32:35], v[214:217], v[172:175], v[32:35]
	v_mfma_f32_16x16x32_bf16 v[24:27], v[206:209], v[190:193], v[24:27]
	v_mfma_f32_16x16x32_bf16 v[16:19], v[214:217], v[190:193], v[16:19]
	v_mfma_f32_16x16x32_bf16 v[8:11], v[206:209], v[198:201], v[8:11]
	v_mfma_f32_16x16x32_bf16 v[0:3], v[214:217], v[198:201], v[0:3]
	v_mfma_f32_16x16x32_bf16 v[60:63], v[210:213], v[168:171], v[60:63]
	v_mfma_f32_16x16x32_bf16 v[56:59], v[222:225], v[168:171], v[56:59]
	v_mfma_f32_16x16x32_bf16 v[40:43], v[210:213], v[176:179], v[40:43]
	v_mfma_f32_16x16x32_bf16 v[32:35], v[222:225], v[176:179], v[32:35]
	v_mfma_f32_16x16x32_bf16 v[24:27], v[210:213], v[194:197], v[24:27]
	v_mfma_f32_16x16x32_bf16 v[16:19], v[222:225], v[194:197], v[16:19]
	v_mfma_f32_16x16x32_bf16 v[8:11], v[210:213], v[202:205], v[8:11]
	v_mfma_f32_16x16x32_bf16 v[0:3], v[222:225], v[202:205], v[0:3]
	s_add_i32 s58, s58, 2
	s_add_u32 s24, s24, 0x100
	s_addc_u32 s25, s25, 0
	s_cmp_gt_u32 s58, 41
	s_barrier
; __device__ __forceinline__ unsigned pk2(float lo, float hi) { unsigned r; asm volatile("v_cvt_pk_bf16_f32 %0, %1, %2" : "=v"(r) : "v"(lo), "v"(hi)); return r; }
; __device__ __forceinline__ unsigned pk2(float lo, float hi) { return f2bf(lo) | (f2bf(hi) << 16); }
;     __device__ __forceinline__ void epi(const f32x4 (&acc)[2][2][4][2], const Unit& u, int wr, int wc, int fr, int fq) const {
;     ...
;         ConvHost<3> ch; ch.begin(cj, u.g, 22, wr * 4 + wc, fq * 16 + fr);
;         const int row0 = u.pm * 256 + wr * 64 + fr, col0 = u.pn * 256 + wc * 32 + 8 * fq;
; #pragma unroll
;         for (int ai = 0; ai < 2; ++ai) {
;             u32x4 xo[4][2];
; #pragma unroll
;             for (int m = 0; m < 4; ++m)
; #pragma unroll
;                 for (int bj = 0; bj < 2; ++bj) xo[m][bj] = *(const u32x4*)(xb + (size_t)(row0 + ai * 128 + m * 16) * D + col0 + bj * 128);
; #pragma unroll
;             for (int m = 0; m < 4; ++m) {
;                 const int row = row0 + ai * 128 + m * 16; const size_t off = (size_t)row * D + col0; float ss = 0.f;
; #pragma unroll
;                 for (int bj = 0; bj < 2; ++bj) {
;                     const u32x4 o = xo[m][bj]; const f32x4 a0v = acc[ai][bj][m][0], a1v = acc[ai][bj][m][1];
;                     const float v0 = bf_lo(o.x) + coef * a0v[0], v1 = bf_hi(o.x) + coef * a0v[1], v2 = bf_lo(o.y) + coef * a0v[2], v3 = bf_hi(o.y) + coef * a0v[3];
;                     const float v4 = bf_lo(o.z) + coef * a1v[0], v5 = bf_hi(o.z) + coef * a1v[1], v6 = bf_lo(o.w) + coef * a1v[2], v7 = bf_hi(o.w) + coef * a1v[3];
;                     u32x4 w; w.x = pk2(v0, v1); w.y = pk2(v2, v3); w.z = pk2(v4, v5); w.w = pk2(v6, v7);
;                     *(u32x4*)(xb + off + bj * 128) = w;
;                     ss += ((v0 * v0 + v1 * v1) + (v2 * v2 + v3 * v3)) + ((v4 * v4 + v5 * v5) + (v6 * v6 + v7 * v7));
;                 }
;                 ss += __shfl_xor(ss, 16); ss += __shfl_xor(ss, 32);
;                 if (fq == 0) rowss[(size_t)row * 32 + u.pn * 4 + wc] = ss;
;             }
	v_lshl_or_b32 v164, s30, 8, v184
	v_lshl_add_u32 v168, s2, 8, v182
	v_ashrrev_i32_e32 v165, 31, v164
	v_lshlrev_b64 v[198:199], 1, v[164:165]
	v_ashrrev_i32_e32 v169, 31, v168
	v_lshl_add_u64 v[166:167], s[0:1], 0, v[198:199]
	v_lshlrev_b64 v[200:201], 11, v[168:169]
	v_lshl_add_u64 v[128:129], v[166:167], 0, v[200:201]
	v_mov_b32_e32 v218, 0x40000
	v_mov_b32_e32 v219, 0
	v_lshl_add_u64 v[216:217], v[128:129], 0, v[218:219]
	v_mov_b32_e32 v218, 0x8000
	s_waitcnt vmcnt(8)
	v_mov_b64_e32 v[190:191], v[232:233]
	v_mov_b64_e32 v[192:193], v[234:235]
	v_mov_b64_e32 v[194:195], v[236:237]
	v_mov_b64_e32 v[196:197], v[238:239]
	v_or_b32_e32 v178, 16, v168
	v_or_b32_e32 v174, 32, v168
	v_or_b32_e32 v170, 48, v168
	v_ashrrev_i32_e32 v179, 31, v178
	v_ashrrev_i32_e32 v175, 31, v174
	v_ashrrev_i32_e32 v171, 31, v170
	v_lshlrev_b64 v[180:181], 11, v[178:179]
	v_lshlrev_b64 v[176:177], 11, v[174:175]
	v_lshlrev_b64 v[172:173], 11, v[170:171]
	v_lshl_add_u64 v[128:129], v[166:167], 0, v[180:181]
	v_lshl_add_u64 v[130:131], v[166:167], 0, v[176:177]
	v_lshl_add_u64 v[202:203], v[166:167], 0, v[172:173]
	v_mov_b64_e32 v[148:149], v[240:241]
	v_mov_b64_e32 v[150:151], v[242:243]
	v_mov_b64_e32 v[144:145], v[244:245]
	v_mov_b64_e32 v[146:147], v[246:247]
	global_load_dwordx4 v[140:143], v[130:131], off
	global_load_dwordx4 v[136:139], v[130:131], off offset:256
	global_load_dwordx4 v[132:135], v[202:203], off
	s_nop 0
	global_load_dwordx4 v[128:131], v[202:203], off offset:256
	global_load_dwordx4 v[222:225], v[216:217], off
	global_load_dwordx4 v[226:229], v[216:217], off offset:256
	v_lshl_add_u64 v[216:217], v[216:217], 0, v[218:219]
	global_load_dwordx4 v[230:233], v[216:217], off
	global_load_dwordx4 v[234:237], v[216:217], off offset:256
	v_lshl_add_u64 v[216:217], v[216:217], 0, v[218:219]
	global_load_dwordx4 v[238:241], v[216:217], off
	global_load_dwordx4 v[242:245], v[216:217], off offset:256
	v_lshl_add_u64 v[216:217], v[216:217], 0, v[218:219]
	global_load_dwordx4 v[246:249], v[216:217], off
	global_load_dwordx4 v[250:253], v[216:217], off offset:256
	v_and_b32_e32 v202, 64, v188
	v_xor_b32_e32 v189, 16, v188
	v_add_u32_e32 v202, 64, v202
	v_cmp_lt_i32_e32 vcc, v189, v202
	v_lshlrev_b32_e32 v203, 16, v190
	v_and_b32_e32 v190, 0xffff0000, v190
	v_lshlrev_b32_e32 v204, 16, v191
	v_and_b32_e32 v191, 0xffff0000, v191
	v_lshlrev_b32_e32 v205, 16, v192
	v_and_b32_e32 v192, 0xffff0000, v192
	v_lshlrev_b32_e32 v206, 16, v193
	v_and_b32_e32 v193, 0xffff0000, v193
	v_lshlrev_b32_e32 v207, 16, v194
	v_and_b32_e32 v194, 0xffff0000, v194
	v_lshlrev_b32_e32 v208, 16, v195
	v_and_b32_e32 v195, 0xffff0000, v195
	v_lshlrev_b32_e32 v209, 16, v196
	v_and_b32_e32 v196, 0xffff0000, v196
	v_lshlrev_b32_e32 v210, 16, v197
	v_and_b32_e32 v197, 0xffff0000, v197
	v_fmac_f32_e32 v190, 0.5, v117
	v_fmac_f32_e32 v191, 0.5, v119
	v_fmac_f32_e32 v192, 0.5, v113
	v_fmac_f32_e32 v193, 0.5, v115
	v_fmac_f32_e32 v194, 0.5, v125
	v_fmac_f32_e32 v195, 0.5, v127
	v_fmac_f32_e32 v196, 0.5, v121
	v_fmac_f32_e32 v197, 0.5, v123
	v_fmac_f32_e32 v203, 0.5, v116
	v_fmac_f32_e32 v204, 0.5, v118
	v_fmac_f32_e32 v205, 0.5, v112
	v_fmac_f32_e32 v206, 0.5, v114
	v_fmac_f32_e32 v207, 0.5, v124
	v_fmac_f32_e32 v208, 0.5, v126
	v_fmac_f32_e32 v209, 0.5, v120
	v_fmac_f32_e32 v210, 0.5, v122
	v_mul_f32_e32 v112, v190, v190
	v_mul_f32_e32 v113, v191, v191
	v_mul_f32_e32 v118, v192, v192
	v_mul_f32_e32 v119, v193, v193
	v_mul_f32_e32 v120, v194, v194
	v_mul_f32_e32 v121, v195, v195
	v_mul_f32_e32 v122, v196, v196
	v_mul_f32_e32 v123, v197, v197
	v_fmac_f32_e32 v112, v203, v203
	v_fmac_f32_e32 v113, v204, v204
	v_fmac_f32_e32 v118, v205, v205
	v_fmac_f32_e32 v119, v206, v206
	v_fmac_f32_e32 v120, v207, v207
	v_fmac_f32_e32 v121, v208, v208
	v_fmac_f32_e32 v122, v209, v209
	v_fmac_f32_e32 v123, v210, v210
	v_add_f32_e32 v112, v112, v113
	v_add_f32_e32 v113, v118, v119
	v_add_f32_e32 v118, v120, v121
	v_add_f32_e32 v119, v122, v123
	v_cndmask_b32_e32 v189, v188, v189, vcc
	v_add_f32_e32 v112, v112, v113
	v_add_f32_e32 v113, v118, v119
	v_add_f32_e32 v113, v112, v113
	v_lshlrev_b32_e32 v112, 2, v189
	v_mov_b32_e32 v122, v113
	s_nop 1
	v_permlane16_swap_b32 v122, v113
	v_lshl_add_u64 v[118:119], s[0:1], 0, v[200:201]
	v_cvt_pk_bf16_f32 v114, v203, v190
	v_lshl_add_u64 v[120:121], v[118:119], 0, v[198:199]
	v_cvt_pk_bf16_f32 v115, v204, v191
	v_cvt_pk_bf16_f32 v116, v205, v192
	v_cvt_pk_bf16_f32 v117, v206, v193
	global_store_dwordx4 v[120:121], v[114:117], off
	s_waitcnt lgkmcnt(0)
	s_nop 0
	v_add_f32_e32 v114, v113, v122
	v_xor_b32_e32 v113, 32, v188
	v_cmp_lt_i32_e32 vcc, v113, v202
	v_cvt_pk_bf16_f32 v116, v207, v194
	v_cvt_pk_bf16_f32 v117, v208, v195
	v_cvt_pk_bf16_f32 v118, v209, v196
	v_cvt_pk_bf16_f32 v119, v210, v197
	global_store_dwordx4 v[120:121], v[116:119], off offset:256
	s_nop 0
	v_cndmask_b32_e32 v113, v188, v113, vcc
	v_lshlrev_b32_e32 v113, 2, v113
	v_mov_b32_e32 v115, v114
	s_nop 1
	v_permlane32_swap_b32 v115, v114
	s_and_saveexec_b64 s[20:21], s[4:5]
	s_cbranch_execz .LBB0_1909
	s_waitcnt lgkmcnt(0)
	v_add_f32_e32 v116, v114, v115
	s_lshl_b32 s22, s30, 2
	v_lshlrev_b64 v[114:115], 7, v[168:169]
	s_ashr_i32 s23, s22, 31
	v_lshl_add_u64 v[114:115], s[8:9], 0, v[114:115]
	v_lshl_add_u64 v[114:115], s[22:23], 2, v[114:115]
	s_lshl_b32 s2, s41, 2
	v_lshl_add_u64 v[114:115], v[114:115], 0, s[2:3]
	global_store_dword v[114:115], v116, off
; __device__ __forceinline__ unsigned pk2(float lo, float hi) { unsigned r; asm volatile("v_cvt_pk_bf16_f32 %0, %1, %2" : "=v"(r) : "v"(lo), "v"(hi)); return r; }
; __device__ __forceinline__ unsigned pk2(float lo, float hi) { return f2bf(lo) | (f2bf(hi) << 16); }
;     __device__ __forceinline__ void epi(const f32x4 (&acc)[2][2][4][2], const Unit& u, int wr, int wc, int fr, int fq) const {
;     ...
;             for (int m = 0; m < 4; ++m) {
;                 const int row = row0 + ai * 128 + m * 16; const size_t off = (size_t)row * D + col0; float ss = 0.f;
; #pragma unroll
;                 for (int bj = 0; bj < 2; ++bj) {
;                     const u32x4 o = xo[m][bj]; const f32x4 a0v = acc[ai][bj][m][0], a1v = acc[ai][bj][m][1];
;                     const float v0 = bf_lo(o.x) + coef * a0v[0], v1 = bf_hi(o.x) + coef * a0v[1], v2 = bf_lo(o.y) + coef * a0v[2], v3 = bf_hi(o.y) + coef * a0v[3];
;                     const float v4 = bf_lo(o.z) + coef * a1v[0], v5 = bf_hi(o.z) + coef * a1v[1], v6 = bf_lo(o.w) + coef * a1v[2], v7 = bf_hi(o.w) + coef * a1v[3];
;                     u32x4 w; w.x = pk2(v0, v1); w.y = pk2(v2, v3); w.z = pk2(v4, v5); w.w = pk2(v6, v7);
;                     *(u32x4*)(xb + off + bj * 128) = w;
;                     ss += ((v0 * v0 + v1 * v1) + (v2 * v2 + v3 * v3)) + ((v4 * v4 + v5 * v5) + (v6 * v6 + v7 * v7));
;                 }
;                 ss += __shfl_xor(ss, 16); ss += __shfl_xor(ss, 32);
;                 if (fq == 0) rowss[(size_t)row * 32 + u.pn * 4 + wc] = ss;
;             }
.LBB0_1909:
	s_or_b64 exec, exec, s[20:21]
	v_lshlrev_b32_e32 v114, 16, v148
	v_fmac_f32_e32 v114, 0.5, v108
	v_and_b32_e32 v108, 0xffff0000, v148
	v_fmac_f32_e32 v108, 0.5, v109
	v_lshlrev_b32_e32 v109, 16, v149
	v_fmac_f32_e32 v109, 0.5, v110
	v_and_b32_e32 v110, 0xffff0000, v149
	v_fmac_f32_e32 v110, 0.5, v111
	v_lshlrev_b32_e32 v111, 16, v150
	s_waitcnt lgkmcnt(0)
	v_and_b32_e32 v115, 0xffff0000, v150
	v_fmac_f32_e32 v111, 0.5, v104
	v_fmac_f32_e32 v115, 0.5, v105
	v_and_b32_e32 v117, 0xffff0000, v151
	v_cvt_pk_bf16_f32 v104, v114, v108
	v_cvt_pk_bf16_f32 v105, v109, v110
	v_mul_f32_e32 v108, v108, v108
	v_mul_f32_e32 v110, v110, v110
	v_lshlrev_b32_e32 v116, 16, v151
	v_fmac_f32_e32 v117, 0.5, v107
	v_fmac_f32_e32 v108, v114, v114
	v_fmac_f32_e32 v110, v109, v109
	v_fmac_f32_e32 v116, 0.5, v106
	v_add_f32_e32 v108, v108, v110
	v_mul_f32_e32 v109, v115, v115
	v_mul_f32_e32 v110, v117, v117
	v_fmac_f32_e32 v109, v111, v111
	v_fmac_f32_e32 v110, v116, v116
	v_add_f32_e32 v109, v109, v110
	v_add_f32_e32 v108, v108, v109
	v_lshlrev_b32_e32 v109, 16, v144
	v_fmac_f32_e32 v109, 0.5, v100
	v_and_b32_e32 v100, 0xffff0000, v144
	v_and_b32_e32 v110, 0xffff0000, v145
	v_cvt_pk_bf16_f32 v106, v111, v115
	v_fmac_f32_e32 v100, 0.5, v101
	v_lshlrev_b32_e32 v101, 16, v145
	v_fmac_f32_e32 v110, 0.5, v103
	v_lshlrev_b32_e32 v111, 16, v146
	v_and_b32_e32 v114, 0xffff0000, v146
	v_cvt_pk_bf16_f32 v107, v116, v117
	v_fmac_f32_e32 v101, 0.5, v102
	v_fmac_f32_e32 v111, 0.5, v96
	v_fmac_f32_e32 v114, 0.5, v97
	v_and_b32_e32 v116, 0xffff0000, v147
	v_mul_f32_e32 v96, v100, v100
	v_mul_f32_e32 v97, v110, v110
	v_lshlrev_b32_e32 v115, 16, v147
	v_fmac_f32_e32 v116, 0.5, v99
	v_fmac_f32_e32 v96, v109, v109
	v_fmac_f32_e32 v97, v101, v101
	v_fmac_f32_e32 v115, 0.5, v98
	v_add_f32_e32 v96, v96, v97
	v_mul_f32_e32 v97, v114, v114
	v_mul_f32_e32 v98, v116, v116
	v_fmac_f32_e32 v97, v111, v111
	v_fmac_f32_e32 v98, v115, v115
	v_add_f32_e32 v97, v97, v98
	v_add_f32_e32 v96, v96, v97
	v_add_f32_e32 v99, v108, v96
	v_mov_b32_e32 v108, v99
	s_nop 1
	v_permlane16_swap_b32 v108, v99
	v_lshl_add_u64 v[96:97], s[0:1], 0, v[180:181]
	v_lshl_add_u64 v[102:103], v[164:165], 1, v[96:97]
	global_store_dwordx4 v[102:103], v[104:107], off
	v_cvt_pk_bf16_f32 v98, v109, v100
	s_waitcnt lgkmcnt(0)
	v_add_f32_e32 v96, v99, v108
	v_mov_b32_e32 v97, v96
	s_nop 1
	v_permlane32_swap_b32 v97, v96
	v_cvt_pk_bf16_f32 v99, v101, v110
	v_cvt_pk_bf16_f32 v100, v111, v114
	v_cvt_pk_bf16_f32 v101, v115, v116
	global_store_dwordx4 v[102:103], v[98:101], off offset:256
	s_and_saveexec_b64 s[20:21], s[4:5]
	s_cbranch_execz .LBB0_1911
	s_waitcnt lgkmcnt(0)
	v_add_f32_e32 v98, v96, v97
	s_lshl_b32 s22, s30, 2
	v_lshlrev_b64 v[96:97], 7, v[178:179]
	s_ashr_i32 s23, s22, 31
	v_lshl_add_u64 v[96:97], s[8:9], 0, v[96:97]
	v_lshl_add_u64 v[96:97], s[22:23], 2, v[96:97]
	s_lshl_b32 s2, s41, 2
	v_lshl_add_u64 v[96:97], v[96:97], 0, s[2:3]
	global_store_dword v[96:97], v98, off
.LBB0_1911:
	s_or_b64 exec, exec, s[20:21]
	s_waitcnt vmcnt(12)
	v_lshlrev_b32_e32 v96, 16, v140
	v_fmac_f32_e32 v96, 0.5, v92
	v_and_b32_e32 v92, 0xffff0000, v140
	v_fmac_f32_e32 v92, 0.5, v93
	v_lshlrev_b32_e32 v93, 16, v141
	v_fmac_f32_e32 v93, 0.5, v94
	v_and_b32_e32 v94, 0xffff0000, v141
	v_fmac_f32_e32 v94, 0.5, v95
	v_lshlrev_b32_e32 v95, 16, v142
	s_waitcnt lgkmcnt(0)
	v_and_b32_e32 v97, 0xffff0000, v142
	v_fmac_f32_e32 v95, 0.5, v88
	v_fmac_f32_e32 v97, 0.5, v89
	v_and_b32_e32 v99, 0xffff0000, v143
	v_cvt_pk_bf16_f32 v88, v96, v92
	v_cvt_pk_bf16_f32 v89, v93, v94
	v_mul_f32_e32 v92, v92, v92
	v_mul_f32_e32 v94, v94, v94
	v_lshlrev_b32_e32 v98, 16, v143
	v_fmac_f32_e32 v99, 0.5, v91
	v_fmac_f32_e32 v92, v96, v96
	v_fmac_f32_e32 v94, v93, v93
	v_fmac_f32_e32 v98, 0.5, v90
	v_add_f32_e32 v92, v92, v94
	v_mul_f32_e32 v93, v97, v97
	v_mul_f32_e32 v94, v99, v99
	v_fmac_f32_e32 v93, v95, v95
	v_fmac_f32_e32 v94, v98, v98
	v_add_f32_e32 v93, v93, v94
	v_add_f32_e32 v92, v92, v93
	v_lshlrev_b32_e32 v93, 16, v136
	v_fmac_f32_e32 v93, 0.5, v84
	v_and_b32_e32 v84, 0xffff0000, v136
	v_and_b32_e32 v94, 0xffff0000, v137
	v_cvt_pk_bf16_f32 v90, v95, v97
	v_fmac_f32_e32 v84, 0.5, v85
	v_lshlrev_b32_e32 v85, 16, v137
	v_fmac_f32_e32 v94, 0.5, v87
	v_lshlrev_b32_e32 v95, 16, v138
	v_and_b32_e32 v96, 0xffff0000, v138
	v_cvt_pk_bf16_f32 v91, v98, v99
	v_fmac_f32_e32 v85, 0.5, v86
	v_fmac_f32_e32 v95, 0.5, v80
	v_fmac_f32_e32 v96, 0.5, v81
	v_and_b32_e32 v98, 0xffff0000, v139
	v_mul_f32_e32 v80, v84, v84
	v_mul_f32_e32 v81, v94, v94
	v_lshlrev_b32_e32 v97, 16, v139
	v_fmac_f32_e32 v98, 0.5, v83
	v_fmac_f32_e32 v80, v93, v93
	v_fmac_f32_e32 v81, v85, v85
	v_fmac_f32_e32 v97, 0.5, v82
	v_add_f32_e32 v80, v80, v81
	v_mul_f32_e32 v81, v96, v96
	v_mul_f32_e32 v82, v98, v98
	v_fmac_f32_e32 v81, v95, v95
	v_fmac_f32_e32 v82, v97, v97
	v_add_f32_e32 v81, v81, v82
	v_add_f32_e32 v80, v80, v81
	v_add_f32_e32 v83, v92, v80
	v_mov_b32_e32 v92, v83
	s_nop 1
	v_permlane16_swap_b32 v92, v83
	v_lshl_add_u64 v[80:81], s[0:1], 0, v[176:177]
	v_lshl_add_u64 v[86:87], v[164:165], 1, v[80:81]
	global_store_dwordx4 v[86:87], v[88:91], off
	v_cvt_pk_bf16_f32 v82, v93, v84
	s_waitcnt lgkmcnt(0)
	v_add_f32_e32 v80, v83, v92
	v_mov_b32_e32 v81, v80
	s_nop 1
	v_permlane32_swap_b32 v81, v80
	v_cvt_pk_bf16_f32 v83, v85, v94
	v_cvt_pk_bf16_f32 v84, v95, v96
	v_cvt_pk_bf16_f32 v85, v97, v98
	global_store_dwordx4 v[86:87], v[82:85], off offset:256
	s_and_saveexec_b64 s[20:21], s[4:5]
	s_cbranch_execz .LBB0_1913
	s_waitcnt lgkmcnt(0)
	v_add_f32_e32 v82, v80, v81
	s_lshl_b32 s22, s30, 2
	v_lshlrev_b64 v[80:81], 7, v[174:175]
	s_ashr_i32 s23, s22, 31
	v_lshl_add_u64 v[80:81], s[8:9], 0, v[80:81]
	v_lshl_add_u64 v[80:81], s[22:23], 2, v[80:81]
	s_lshl_b32 s2, s41, 2
	v_lshl_add_u64 v[80:81], v[80:81], 0, s[2:3]
	global_store_dword v[80:81], v82, off
; __device__ __forceinline__ unsigned pk2(float lo, float hi) { unsigned r; asm volatile("v_cvt_pk_bf16_f32 %0, %1, %2" : "=v"(r) : "v"(lo), "v"(hi)); return r; }
; __device__ __forceinline__ unsigned pk2(float lo, float hi) { return f2bf(lo) | (f2bf(hi) << 16); }
;     __device__ __forceinline__ void epi(const f32x4 (&acc)[2][2][4][2], const Unit& u, int wr, int wc, int fr, int fq) const {
;     ...
;                 for (int bj = 0; bj < 2; ++bj) xo[m][bj] = *(const u32x4*)(xb + (size_t)(row0 + ai * 128 + m * 16) * D + col0 + bj * 128);
; #pragma unroll
;             for (int m = 0; m < 4; ++m) {
;                 const int row = row0 + ai * 128 + m * 16; const size_t off = (size_t)row * D + col0; float ss = 0.f;
; #pragma unroll
;                 for (int bj = 0; bj < 2; ++bj) {
;                     const u32x4 o = xo[m][bj]; const f32x4 a0v = acc[ai][bj][m][0], a1v = acc[ai][bj][m][1];
;                     const float v0 = bf_lo(o.x) + coef * a0v[0], v1 = bf_hi(o.x) + coef * a0v[1], v2 = bf_lo(o.y) + coef * a0v[2], v3 = bf_hi(o.y) + coef * a0v[3];
;                     const float v4 = bf_lo(o.z) + coef * a1v[0], v5 = bf_hi(o.z) + coef * a1v[1], v6 = bf_lo(o.w) + coef * a1v[2], v7 = bf_hi(o.w) + coef * a1v[3];
;                     u32x4 w; w.x = pk2(v0, v1); w.y = pk2(v2, v3); w.z = pk2(v4, v5); w.w = pk2(v6, v7);
;                     *(u32x4*)(xb + off + bj * 128) = w;
;                     ss += ((v0 * v0 + v1 * v1) + (v2 * v2 + v3 * v3)) + ((v4 * v4 + v5 * v5) + (v6 * v6 + v7 * v7));
;                 }
;                 ss += __shfl_xor(ss, 16); ss += __shfl_xor(ss, 32);
;                 if (fq == 0) rowss[(size_t)row * 32 + u.pn * 4 + wc] = ss;
;             }
.LBB0_1913:
	s_or_b64 exec, exec, s[20:21]
	v_lshlrev_b32_e32 v80, 16, v132
	v_fmac_f32_e32 v80, 0.5, v76
	v_and_b32_e32 v76, 0xffff0000, v132
	v_fmac_f32_e32 v76, 0.5, v77
	v_lshlrev_b32_e32 v77, 16, v133
	v_fmac_f32_e32 v77, 0.5, v78
	v_and_b32_e32 v78, 0xffff0000, v133
	v_fmac_f32_e32 v78, 0.5, v79
	v_lshlrev_b32_e32 v79, 16, v134
	s_waitcnt lgkmcnt(0)
	v_and_b32_e32 v81, 0xffff0000, v134
	v_fmac_f32_e32 v79, 0.5, v72
	v_fmac_f32_e32 v81, 0.5, v73
	v_and_b32_e32 v83, 0xffff0000, v135
	v_cvt_pk_bf16_f32 v72, v80, v76
	v_cvt_pk_bf16_f32 v73, v77, v78
	v_mul_f32_e32 v76, v76, v76
	v_mul_f32_e32 v78, v78, v78
	v_lshlrev_b32_e32 v82, 16, v135
	v_fmac_f32_e32 v83, 0.5, v75
	v_fmac_f32_e32 v76, v80, v80
	v_fmac_f32_e32 v78, v77, v77
	v_fmac_f32_e32 v82, 0.5, v74
	v_add_f32_e32 v76, v76, v78
	v_mul_f32_e32 v77, v81, v81
	v_mul_f32_e32 v78, v83, v83
	v_fmac_f32_e32 v77, v79, v79
	v_fmac_f32_e32 v78, v82, v82
	v_add_f32_e32 v77, v77, v78
	v_add_f32_e32 v76, v76, v77
	v_lshlrev_b32_e32 v77, 16, v128
	v_fmac_f32_e32 v77, 0.5, v68
	v_and_b32_e32 v68, 0xffff0000, v128
	v_and_b32_e32 v78, 0xffff0000, v129
	v_cvt_pk_bf16_f32 v74, v79, v81
	v_fmac_f32_e32 v68, 0.5, v69
	v_lshlrev_b32_e32 v69, 16, v129
	v_fmac_f32_e32 v78, 0.5, v71
	v_lshlrev_b32_e32 v79, 16, v130
	v_and_b32_e32 v80, 0xffff0000, v130
	v_cvt_pk_bf16_f32 v75, v82, v83
	v_fmac_f32_e32 v69, 0.5, v70
	v_fmac_f32_e32 v79, 0.5, v64
	v_fmac_f32_e32 v80, 0.5, v65
	v_and_b32_e32 v82, 0xffff0000, v131
	v_mul_f32_e32 v64, v68, v68
	v_mul_f32_e32 v65, v78, v78
	v_lshlrev_b32_e32 v81, 16, v131
	v_fmac_f32_e32 v82, 0.5, v67
	v_fmac_f32_e32 v64, v77, v77
	v_fmac_f32_e32 v65, v69, v69
	v_fmac_f32_e32 v81, 0.5, v66
	v_add_f32_e32 v64, v64, v65
	v_mul_f32_e32 v65, v80, v80
	v_mul_f32_e32 v66, v82, v82
	v_fmac_f32_e32 v65, v79, v79
	v_fmac_f32_e32 v66, v81, v81
	v_add_f32_e32 v65, v65, v66
	v_add_f32_e32 v64, v64, v65
	v_add_f32_e32 v67, v76, v64
	v_mov_b32_e32 v76, v67
	s_nop 1
	v_permlane16_swap_b32 v76, v67
	v_lshl_add_u64 v[64:65], s[0:1], 0, v[172:173]
	v_lshl_add_u64 v[70:71], v[164:165], 1, v[64:65]
	global_store_dwordx4 v[70:71], v[72:75], off
	v_cvt_pk_bf16_f32 v66, v77, v68
	s_waitcnt lgkmcnt(0)
	v_add_f32_e32 v64, v67, v76
	v_mov_b32_e32 v65, v64
	s_nop 1
	v_permlane32_swap_b32 v65, v64
	v_cvt_pk_bf16_f32 v67, v69, v78
	v_cvt_pk_bf16_f32 v68, v79, v80
	v_cvt_pk_bf16_f32 v69, v81, v82
	global_store_dwordx4 v[70:71], v[66:69], off offset:256
	s_and_saveexec_b64 s[20:21], s[4:5]
	s_cbranch_execz .LBB0_1915
	s_waitcnt lgkmcnt(0)
	v_add_f32_e32 v66, v64, v65
	s_lshl_b32 s22, s30, 2
	v_lshlrev_b64 v[64:65], 7, v[170:171]
	s_ashr_i32 s23, s22, 31
	v_lshl_add_u64 v[64:65], s[8:9], 0, v[64:65]
	v_lshl_add_u64 v[64:65], s[22:23], 2, v[64:65]
	s_lshl_b32 s2, s41, 2
	v_lshl_add_u64 v[64:65], v[64:65], 0, s[2:3]
	global_store_dword v[64:65], v66, off
.LBB0_1915:
	s_or_b64 exec, exec, s[20:21]
	v_add_u32_e32 v100, 0x80, v168
	v_ashrrev_i32_e32 v101, 31, v100
	v_lshlrev_b64 v[110:111], 11, v[100:101]
	s_waitcnt lgkmcnt(0)
	v_lshl_add_u64 v[64:65], v[166:167], 0, v[110:111]
	s_waitcnt vmcnt(8)
	v_mov_b64_e32 v[102:103], v[222:223]
	v_mov_b64_e32 v[104:105], v[224:225]
	v_mov_b64_e32 v[106:107], v[226:227]
	v_mov_b64_e32 v[108:109], v[228:229]
	v_add_u32_e32 v96, 0x90, v168
	v_add_u32_e32 v92, 0xa0, v168
	v_add_u32_e32 v88, 0xb0, v168
	v_ashrrev_i32_e32 v97, 31, v96
	v_ashrrev_i32_e32 v93, 31, v92
	v_ashrrev_i32_e32 v89, 31, v88
	v_lshlrev_b64 v[98:99], 11, v[96:97]
	v_lshlrev_b64 v[94:95], 11, v[92:93]
	v_lshlrev_b64 v[90:91], 11, v[88:89]
	v_lshl_add_u64 v[64:65], v[166:167], 0, v[98:99]
	v_lshl_add_u64 v[66:67], v[166:167], 0, v[94:95]
	v_lshl_add_u64 v[114:115], v[166:167], 0, v[90:91]
	v_mov_b64_e32 v[84:85], v[230:231]
	v_mov_b64_e32 v[86:87], v[232:233]
	v_mov_b64_e32 v[80:81], v[234:235]
	v_mov_b64_e32 v[82:83], v[236:237]
	v_mov_b64_e32 v[76:77], v[238:239]
	v_mov_b64_e32 v[78:79], v[240:241]
	v_mov_b64_e32 v[72:73], v[242:243]
	v_mov_b64_e32 v[74:75], v[244:245]
	v_mov_b64_e32 v[68:69], v[246:247]
	v_mov_b64_e32 v[70:71], v[248:249]
	s_nop 0
	v_mov_b64_e32 v[64:65], v[250:251]
	v_mov_b64_e32 v[66:67], v[252:253]
	v_lshlrev_b32_e32 v114, 16, v102
	v_and_b32_e32 v102, 0xffff0000, v102
	v_lshlrev_b32_e32 v115, 16, v103
	v_and_b32_e32 v103, 0xffff0000, v103
	v_lshlrev_b32_e32 v116, 16, v104
	v_and_b32_e32 v104, 0xffff0000, v104
	v_lshlrev_b32_e32 v117, 16, v105
	v_and_b32_e32 v105, 0xffff0000, v105
	v_lshlrev_b32_e32 v118, 16, v106
	v_and_b32_e32 v106, 0xffff0000, v106
	v_lshlrev_b32_e32 v119, 16, v107
	v_and_b32_e32 v107, 0xffff0000, v107
	v_lshlrev_b32_e32 v120, 16, v108
	v_and_b32_e32 v108, 0xffff0000, v108
	v_lshlrev_b32_e32 v121, 16, v109
	v_and_b32_e32 v109, 0xffff0000, v109
	v_fmac_f32_e32 v102, 0.5, v53
	v_fmac_f32_e32 v103, 0.5, v55
	v_fmac_f32_e32 v104, 0.5, v49
	v_fmac_f32_e32 v105, 0.5, v51
	v_fmac_f32_e32 v106, 0.5, v61
	v_fmac_f32_e32 v107, 0.5, v63
	v_fmac_f32_e32 v108, 0.5, v57
	v_fmac_f32_e32 v109, 0.5, v59
	v_fmac_f32_e32 v114, 0.5, v52
	v_fmac_f32_e32 v115, 0.5, v54
	v_fmac_f32_e32 v116, 0.5, v48
	v_fmac_f32_e32 v117, 0.5, v50
	v_fmac_f32_e32 v118, 0.5, v60
	v_fmac_f32_e32 v119, 0.5, v62
	v_fmac_f32_e32 v120, 0.5, v56
	v_fmac_f32_e32 v121, 0.5, v58
	v_mul_f32_e32 v52, v102, v102
	v_mul_f32_e32 v53, v103, v103
	v_mul_f32_e32 v54, v104, v104
	v_mul_f32_e32 v55, v105, v105
	v_mul_f32_e32 v56, v106, v106
	v_mul_f32_e32 v57, v107, v107
	v_mul_f32_e32 v58, v108, v108
	v_mul_f32_e32 v59, v109, v109
	v_fmac_f32_e32 v52, v114, v114
	v_fmac_f32_e32 v53, v115, v115
	v_fmac_f32_e32 v54, v116, v116
	v_fmac_f32_e32 v55, v117, v117
	v_fmac_f32_e32 v56, v118, v118
	v_fmac_f32_e32 v57, v119, v119
	v_fmac_f32_e32 v58, v120, v120
	v_fmac_f32_e32 v59, v121, v121
	v_add_f32_e32 v52, v52, v53
	v_add_f32_e32 v53, v54, v55
	v_add_f32_e32 v54, v56, v57
	v_add_f32_e32 v55, v58, v59
	v_add_f32_e32 v52, v52, v53
	v_add_f32_e32 v53, v54, v55
	v_add_f32_e32 v56, v52, v53
	v_mov_b32_e32 v57, v56
	s_nop 1
	v_permlane16_swap_b32 v57, v56
	v_lshl_add_u64 v[52:53], s[0:1], 0, v[110:111]
	v_cvt_pk_bf16_f32 v48, v114, v102
	v_lshl_add_u64 v[54:55], v[164:165], 1, v[52:53]
	v_cvt_pk_bf16_f32 v49, v115, v103
	v_cvt_pk_bf16_f32 v50, v116, v104
	v_cvt_pk_bf16_f32 v51, v117, v105
	global_store_dwordx4 v[54:55], v[48:51], off
	s_waitcnt lgkmcnt(0)
	s_nop 0
	v_add_f32_e32 v48, v56, v57
	v_mov_b32_e32 v49, v48
	s_nop 1
	v_permlane32_swap_b32 v49, v48
	v_cvt_pk_bf16_f32 v50, v118, v106
	v_cvt_pk_bf16_f32 v51, v119, v107
	v_cvt_pk_bf16_f32 v52, v120, v108
	v_cvt_pk_bf16_f32 v53, v121, v109
	global_store_dwordx4 v[54:55], v[50:53], off offset:256
	s_and_saveexec_b64 s[20:21], s[4:5]
	s_cbranch_execz .LBB0_1917
	s_waitcnt lgkmcnt(0)
	v_add_f32_e32 v50, v48, v49
	s_lshl_b32 s22, s30, 2
	v_lshlrev_b64 v[48:49], 7, v[100:101]
	s_ashr_i32 s23, s22, 31
	v_lshl_add_u64 v[48:49], s[8:9], 0, v[48:49]
	v_lshl_add_u64 v[48:49], s[22:23], 2, v[48:49]
	s_lshl_b32 s2, s41, 2
	v_lshl_add_u64 v[48:49], v[48:49], 0, s[2:3]
	global_store_dword v[48:49], v50, off
; __device__ __forceinline__ unsigned pk2(float lo, float hi) { unsigned r; asm volatile("v_cvt_pk_bf16_f32 %0, %1, %2" : "=v"(r) : "v"(lo), "v"(hi)); return r; }
; __device__ __forceinline__ unsigned pk2(float lo, float hi) { return f2bf(lo) | (f2bf(hi) << 16); }
;     __device__ __forceinline__ void epi(const f32x4 (&acc)[2][2][4][2], const Unit& u, int wr, int wc, int fr, int fq) const {
;     ...
;             for (int m = 0; m < 4; ++m) {
;                 const int row = row0 + ai * 128 + m * 16; const size_t off = (size_t)row * D + col0; float ss = 0.f;
; #pragma unroll
;                 for (int bj = 0; bj < 2; ++bj) {
;                     const u32x4 o = xo[m][bj]; const f32x4 a0v = acc[ai][bj][m][0], a1v = acc[ai][bj][m][1];
;                     const float v0 = bf_lo(o.x) + coef * a0v[0], v1 = bf_hi(o.x) + coef * a0v[1], v2 = bf_lo(o.y) + coef * a0v[2], v3 = bf_hi(o.y) + coef * a0v[3];
;                     const float v4 = bf_lo(o.z) + coef * a1v[0], v5 = bf_hi(o.z) + coef * a1v[1], v6 = bf_lo(o.w) + coef * a1v[2], v7 = bf_hi(o.w) + coef * a1v[3];
;                     u32x4 w; w.x = pk2(v0, v1); w.y = pk2(v2, v3); w.z = pk2(v4, v5); w.w = pk2(v6, v7);
;                     *(u32x4*)(xb + off + bj * 128) = w;
;                     ss += ((v0 * v0 + v1 * v1) + (v2 * v2 + v3 * v3)) + ((v4 * v4 + v5 * v5) + (v6 * v6 + v7 * v7));
;                 }
;                 ss += __shfl_xor(ss, 16); ss += __shfl_xor(ss, 32);
;                 if (fq == 0) rowss[(size_t)row * 32 + u.pn * 4 + wc] = ss;
;             }
.LBB0_1917:
	s_or_b64 exec, exec, s[20:21]
	v_lshlrev_b32_e32 v48, 16, v84
	v_fmac_f32_e32 v48, 0.5, v44
	v_and_b32_e32 v44, 0xffff0000, v84
	v_fmac_f32_e32 v44, 0.5, v45
	v_lshlrev_b32_e32 v45, 16, v85
	v_fmac_f32_e32 v45, 0.5, v46
	v_and_b32_e32 v46, 0xffff0000, v85
	v_fmac_f32_e32 v46, 0.5, v47
	v_lshlrev_b32_e32 v47, 16, v86
	s_waitcnt lgkmcnt(0)
	v_and_b32_e32 v49, 0xffff0000, v86
	v_fmac_f32_e32 v47, 0.5, v36
	v_fmac_f32_e32 v49, 0.5, v37
	v_and_b32_e32 v51, 0xffff0000, v87
	v_cvt_pk_bf16_f32 v36, v48, v44
	v_cvt_pk_bf16_f32 v37, v45, v46
	v_mul_f32_e32 v44, v44, v44
	v_mul_f32_e32 v46, v46, v46
	v_lshlrev_b32_e32 v50, 16, v87
	v_fmac_f32_e32 v51, 0.5, v39
	v_fmac_f32_e32 v44, v48, v48
	v_fmac_f32_e32 v46, v45, v45
	v_fmac_f32_e32 v50, 0.5, v38
	v_add_f32_e32 v44, v44, v46
	v_mul_f32_e32 v45, v49, v49
	v_mul_f32_e32 v46, v51, v51
	v_cvt_pk_bf16_f32 v38, v47, v49
	v_fmac_f32_e32 v45, v47, v47
	v_fmac_f32_e32 v46, v50, v50
	v_lshlrev_b32_e32 v47, 16, v81
	v_add_f32_e32 v45, v45, v46
	v_and_b32_e32 v46, 0xffff0000, v80
	v_fmac_f32_e32 v47, 0.5, v42
	v_and_b32_e32 v42, 0xffff0000, v81
	v_add_f32_e32 v44, v44, v45
	v_lshlrev_b32_e32 v45, 16, v80
	v_fmac_f32_e32 v46, 0.5, v41
	v_fmac_f32_e32 v42, 0.5, v43
	v_lshlrev_b32_e32 v43, 16, v82
	v_and_b32_e32 v48, 0xffff0000, v82
	v_cvt_pk_bf16_f32 v39, v50, v51
	v_fmac_f32_e32 v45, 0.5, v40
	v_fmac_f32_e32 v43, 0.5, v32
	v_fmac_f32_e32 v48, 0.5, v33
	v_and_b32_e32 v50, 0xffff0000, v83
	v_mul_f32_e32 v32, v46, v46
	v_mul_f32_e32 v33, v42, v42
	v_lshlrev_b32_e32 v49, 16, v83
	v_fmac_f32_e32 v50, 0.5, v35
	v_fmac_f32_e32 v32, v45, v45
	v_fmac_f32_e32 v33, v47, v47
	v_fmac_f32_e32 v49, 0.5, v34
	v_add_f32_e32 v32, v32, v33
	v_mul_f32_e32 v33, v48, v48
	v_mul_f32_e32 v34, v50, v50
	v_fmac_f32_e32 v33, v43, v43
	v_fmac_f32_e32 v34, v49, v49
	v_add_f32_e32 v33, v33, v34
	v_add_f32_e32 v32, v32, v33
	v_add_f32_e32 v35, v44, v32
	v_mov_b32_e32 v44, v35
	s_nop 1
	v_permlane16_swap_b32 v44, v35
	v_lshl_add_u64 v[32:33], s[0:1], 0, v[98:99]
	v_lshl_add_u64 v[40:41], v[164:165], 1, v[32:33]
	global_store_dwordx4 v[40:41], v[36:39], off
	v_cvt_pk_bf16_f32 v34, v45, v46
	s_waitcnt lgkmcnt(0)
	v_add_f32_e32 v32, v35, v44
	v_mov_b32_e32 v33, v32
	s_nop 1
	v_permlane32_swap_b32 v33, v32
	v_cvt_pk_bf16_f32 v35, v47, v42
	v_cvt_pk_bf16_f32 v36, v43, v48
	v_cvt_pk_bf16_f32 v37, v49, v50
	global_store_dwordx4 v[40:41], v[34:37], off offset:256
	s_and_saveexec_b64 s[20:21], s[4:5]
	s_cbranch_execz .LBB0_1919
	s_waitcnt lgkmcnt(0)
	v_add_f32_e32 v34, v32, v33
	s_lshl_b32 s22, s30, 2
	v_lshlrev_b64 v[32:33], 7, v[96:97]
	s_ashr_i32 s23, s22, 31
	v_lshl_add_u64 v[32:33], s[8:9], 0, v[32:33]
	v_lshl_add_u64 v[32:33], s[22:23], 2, v[32:33]
	s_lshl_b32 s2, s41, 2
	v_lshl_add_u64 v[32:33], v[32:33], 0, s[2:3]
	global_store_dword v[32:33], v34, off
; __device__ __forceinline__ unsigned pk2(float lo, float hi) { unsigned r; asm volatile("v_cvt_pk_bf16_f32 %0, %1, %2" : "=v"(r) : "v"(lo), "v"(hi)); return r; }
; __device__ __forceinline__ unsigned pk2(float lo, float hi) { return f2bf(lo) | (f2bf(hi) << 16); }
;     __device__ __forceinline__ void epi(const f32x4 (&acc)[2][2][4][2], const Unit& u, int wr, int wc, int fr, int fq) const {
;     ...
;             for (int m = 0; m < 4; ++m) {
;                 const int row = row0 + ai * 128 + m * 16; const size_t off = (size_t)row * D + col0; float ss = 0.f;
; #pragma unroll
;                 for (int bj = 0; bj < 2; ++bj) {
;                     const u32x4 o = xo[m][bj]; const f32x4 a0v = acc[ai][bj][m][0], a1v = acc[ai][bj][m][1];
;                     const float v0 = bf_lo(o.x) + coef * a0v[0], v1 = bf_hi(o.x) + coef * a0v[1], v2 = bf_lo(o.y) + coef * a0v[2], v3 = bf_hi(o.y) + coef * a0v[3];
;                     const float v4 = bf_lo(o.z) + coef * a1v[0], v5 = bf_hi(o.z) + coef * a1v[1], v6 = bf_lo(o.w) + coef * a1v[2], v7 = bf_hi(o.w) + coef * a1v[3];
;                     u32x4 w; w.x = pk2(v0, v1); w.y = pk2(v2, v3); w.z = pk2(v4, v5); w.w = pk2(v6, v7);
;                     *(u32x4*)(xb + off + bj * 128) = w;
;                     ss += ((v0 * v0 + v1 * v1) + (v2 * v2 + v3 * v3)) + ((v4 * v4 + v5 * v5) + (v6 * v6 + v7 * v7));
;                 }
;                 ss += __shfl_xor(ss, 16); ss += __shfl_xor(ss, 32);
;                 if (fq == 0) rowss[(size_t)row * 32 + u.pn * 4 + wc] = ss;
;             }
.LBB0_1919:
	s_or_b64 exec, exec, s[20:21]
	v_lshlrev_b32_e32 v32, 16, v76
	v_fmac_f32_e32 v32, 0.5, v28
	v_and_b32_e32 v28, 0xffff0000, v76
	v_fmac_f32_e32 v28, 0.5, v29
	v_lshlrev_b32_e32 v29, 16, v77
	v_fmac_f32_e32 v29, 0.5, v30
	v_and_b32_e32 v30, 0xffff0000, v77
	v_fmac_f32_e32 v30, 0.5, v31
	v_lshlrev_b32_e32 v31, 16, v78
	s_waitcnt lgkmcnt(0)
	v_and_b32_e32 v33, 0xffff0000, v78
	v_fmac_f32_e32 v31, 0.5, v20
	v_fmac_f32_e32 v33, 0.5, v21
	v_and_b32_e32 v35, 0xffff0000, v79
	v_cvt_pk_bf16_f32 v20, v32, v28
	v_cvt_pk_bf16_f32 v21, v29, v30
	v_mul_f32_e32 v28, v28, v28
	v_mul_f32_e32 v30, v30, v30
	v_lshlrev_b32_e32 v34, 16, v79
	v_fmac_f32_e32 v35, 0.5, v23
	v_fmac_f32_e32 v28, v32, v32
	v_fmac_f32_e32 v30, v29, v29
	v_fmac_f32_e32 v34, 0.5, v22
	v_add_f32_e32 v28, v28, v30
	v_mul_f32_e32 v29, v33, v33
	v_mul_f32_e32 v30, v35, v35
	v_cvt_pk_bf16_f32 v22, v31, v33
	v_fmac_f32_e32 v29, v31, v31
	v_fmac_f32_e32 v30, v34, v34
	v_lshlrev_b32_e32 v31, 16, v73
	v_add_f32_e32 v29, v29, v30
	v_and_b32_e32 v30, 0xffff0000, v72
	v_fmac_f32_e32 v31, 0.5, v26
	v_and_b32_e32 v26, 0xffff0000, v73
	v_add_f32_e32 v28, v28, v29
	v_lshlrev_b32_e32 v29, 16, v72
	v_fmac_f32_e32 v30, 0.5, v25
	v_fmac_f32_e32 v26, 0.5, v27
	v_lshlrev_b32_e32 v27, 16, v74
	v_and_b32_e32 v32, 0xffff0000, v74
	v_cvt_pk_bf16_f32 v23, v34, v35
	v_fmac_f32_e32 v29, 0.5, v24
	v_fmac_f32_e32 v27, 0.5, v16
	v_fmac_f32_e32 v32, 0.5, v17
	v_and_b32_e32 v34, 0xffff0000, v75
	v_mul_f32_e32 v16, v30, v30
	v_mul_f32_e32 v17, v26, v26
	v_lshlrev_b32_e32 v33, 16, v75
	v_fmac_f32_e32 v34, 0.5, v19
	v_fmac_f32_e32 v16, v29, v29
	v_fmac_f32_e32 v17, v31, v31
	v_fmac_f32_e32 v33, 0.5, v18
	v_add_f32_e32 v16, v16, v17
	v_mul_f32_e32 v17, v32, v32
	v_mul_f32_e32 v18, v34, v34
	v_fmac_f32_e32 v17, v27, v27
	v_fmac_f32_e32 v18, v33, v33
	v_add_f32_e32 v17, v17, v18
	v_add_f32_e32 v16, v16, v17
	v_add_f32_e32 v19, v28, v16
	v_mov_b32_e32 v28, v19
	s_nop 1
	v_permlane16_swap_b32 v28, v19
	v_lshl_add_u64 v[16:17], s[0:1], 0, v[94:95]
	v_lshl_add_u64 v[24:25], v[164:165], 1, v[16:17]
	global_store_dwordx4 v[24:25], v[20:23], off
	v_cvt_pk_bf16_f32 v18, v29, v30
	s_waitcnt lgkmcnt(0)
	v_add_f32_e32 v16, v19, v28
	v_mov_b32_e32 v17, v16
	s_nop 1
	v_permlane32_swap_b32 v17, v16
	v_cvt_pk_bf16_f32 v19, v31, v26
	v_cvt_pk_bf16_f32 v20, v27, v32
	v_cvt_pk_bf16_f32 v21, v33, v34
	global_store_dwordx4 v[24:25], v[18:21], off offset:256
	s_and_saveexec_b64 s[20:21], s[4:5]
	s_cbranch_execz .LBB0_1921
	s_waitcnt lgkmcnt(0)
	v_add_f32_e32 v18, v16, v17
	s_lshl_b32 s22, s30, 2
	v_lshlrev_b64 v[16:17], 7, v[92:93]
	s_ashr_i32 s23, s22, 31
	v_lshl_add_u64 v[16:17], s[8:9], 0, v[16:17]
	v_lshl_add_u64 v[16:17], s[22:23], 2, v[16:17]
	s_lshl_b32 s2, s41, 2
	v_lshl_add_u64 v[16:17], v[16:17], 0, s[2:3]
	global_store_dword v[16:17], v18, off
.LBB0_1921:
	s_or_b64 exec, exec, s[20:21]
	v_lshlrev_b32_e32 v16, 16, v68
	v_fmac_f32_e32 v16, 0.5, v12
	v_and_b32_e32 v12, 0xffff0000, v68
	v_fmac_f32_e32 v12, 0.5, v13
	v_lshlrev_b32_e32 v13, 16, v69
	v_fmac_f32_e32 v13, 0.5, v14
	v_and_b32_e32 v14, 0xffff0000, v69
	v_fmac_f32_e32 v14, 0.5, v15
	v_lshlrev_b32_e32 v15, 16, v70
	s_waitcnt lgkmcnt(0)
	v_and_b32_e32 v17, 0xffff0000, v70
	v_fmac_f32_e32 v15, 0.5, v4
	v_fmac_f32_e32 v17, 0.5, v5
	v_and_b32_e32 v19, 0xffff0000, v71
	v_cvt_pk_bf16_f32 v4, v16, v12
	v_cvt_pk_bf16_f32 v5, v13, v14
	v_mul_f32_e32 v12, v12, v12
	v_mul_f32_e32 v14, v14, v14
	v_lshlrev_b32_e32 v18, 16, v71
	v_fmac_f32_e32 v19, 0.5, v7
	v_fmac_f32_e32 v12, v16, v16
	v_fmac_f32_e32 v14, v13, v13
	v_fmac_f32_e32 v18, 0.5, v6
	v_add_f32_e32 v12, v12, v14
	v_mul_f32_e32 v13, v17, v17
	v_mul_f32_e32 v14, v19, v19
	v_cvt_pk_bf16_f32 v6, v15, v17
	v_fmac_f32_e32 v13, v15, v15
	v_fmac_f32_e32 v14, v18, v18
	v_lshlrev_b32_e32 v15, 16, v65
	v_add_f32_e32 v13, v13, v14
	v_and_b32_e32 v14, 0xffff0000, v64
	v_fmac_f32_e32 v15, 0.5, v10
	v_and_b32_e32 v10, 0xffff0000, v65
	v_add_f32_e32 v12, v12, v13
	v_lshlrev_b32_e32 v13, 16, v64
	v_fmac_f32_e32 v14, 0.5, v9
	v_fmac_f32_e32 v10, 0.5, v11
	v_lshlrev_b32_e32 v11, 16, v66
	v_and_b32_e32 v16, 0xffff0000, v66
	v_cvt_pk_bf16_f32 v7, v18, v19
	v_fmac_f32_e32 v13, 0.5, v8
	v_fmac_f32_e32 v11, 0.5, v0
	v_fmac_f32_e32 v16, 0.5, v1
	v_and_b32_e32 v18, 0xffff0000, v67
	v_mul_f32_e32 v0, v14, v14
	v_mul_f32_e32 v1, v10, v10
	v_lshlrev_b32_e32 v17, 16, v67
	v_fmac_f32_e32 v18, 0.5, v3
	v_fmac_f32_e32 v0, v13, v13
	v_fmac_f32_e32 v1, v15, v15
	v_fmac_f32_e32 v17, 0.5, v2
	v_add_f32_e32 v0, v0, v1
	v_mul_f32_e32 v1, v16, v16
	v_mul_f32_e32 v2, v18, v18
	v_fmac_f32_e32 v1, v11, v11
	v_fmac_f32_e32 v2, v17, v17
	v_add_f32_e32 v1, v1, v2
	v_add_f32_e32 v0, v0, v1
	v_add_f32_e32 v3, v12, v0
	v_mov_b32_e32 v12, v3
	s_nop 1
	v_permlane16_swap_b32 v12, v3
	v_lshl_add_u64 v[0:1], s[0:1], 0, v[90:91]
	v_lshl_add_u64 v[8:9], v[164:165], 1, v[0:1]
	global_store_dwordx4 v[8:9], v[4:7], off
	v_cvt_pk_bf16_f32 v2, v13, v14
	s_waitcnt lgkmcnt(0)
	v_add_f32_e32 v0, v3, v12
	v_mov_b32_e32 v1, v0
	s_nop 1
	v_permlane32_swap_b32 v1, v0
	v_cvt_pk_bf16_f32 v3, v15, v10
	v_cvt_pk_bf16_f32 v4, v11, v16
	v_cvt_pk_bf16_f32 v5, v17, v18
	global_store_dwordx4 v[8:9], v[2:5], off offset:256
	s_and_saveexec_b64 s[20:21], s[4:5]
	s_cbranch_execz .LBB0_1898
	s_waitcnt lgkmcnt(0)
	v_add_f32_e32 v2, v0, v1
	s_lshl_b32 s22, s30, 2
	v_lshlrev_b64 v[0:1], 7, v[88:89]
	s_ashr_i32 s23, s22, 31
	v_lshl_add_u64 v[0:1], s[8:9], 0, v[0:1]
	v_lshl_add_u64 v[0:1], s[22:23], 2, v[0:1]
	s_lshl_b32 s2, s41, 2
	v_lshl_add_u64 v[0:1], v[0:1], 0, s[2:3]
	global_store_dword v[0:1], v2, off
	s_branch .LBB0_1898
